# removed the redundant mid-block s_setprio 0 / s_setprio 1 pairs inside the 32-MFMA blocks of all GEMM loops
# speedup vs baseline: 1.0012x; 1.0012x over previous
.LBB0_122:
	s_cmp_eq_u32 s89, 12
	s_cselect_b32 s42, s20, s65
	s_cselect_b32 s43, s16, s86
	s_cselect_b32 s45, s31, s88
	s_cselect_b32 s44, s59, s87
	s_add_u32 s38, s42, 0x80
	s_addc_u32 s39, s43, 0
	s_add_u32 s74, s44, 0x80
	s_addc_u32 s75, s45, 0
	s_add_i32 s35, 0, 0x10000
	s_mov_b64 s[18:19], s[68:69]
	v_add_u32_e32 v140, s35, v142
	s_add_i32 s49, 0, 0x14000
	ds_read_b128 v[136:139], v140
	ds_read_b128 v[144:147], v140 offset:1024
	ds_read_b128 v[148:151], v140 offset:2048
	ds_read_b128 v[152:155], v140 offset:3072
	v_add_u32_e32 v140, s49, v142
	ds_read_b128 v[156:159], v140
	ds_read_b128 v[160:163], v140 offset:1024
	ds_read_b128 v[164:167], v140 offset:2048
	ds_read_b128 v[168:171], v140 offset:3072
	s_add_u32 s18, s18, 0x40000
	s_addc_u32 s19, s19, 0
	v_lshl_add_u64 v[140:141], s[18:19], 0, v[130:131]
	s_add_i32 m0, s67, 0xc000
	ds_read_b128 v[172:175], v143
	ds_read_b128 v[176:179], v143 offset:1024
	ds_read_b128 v[180:183], v143 offset:2048
	ds_read_b128 v[184:187], v143 offset:3072
	ds_read_b128 v[188:191], v143 offset:4096
	ds_read_b128 v[192:195], v143 offset:5120
	ds_read_b128 v[196:199], v143 offset:6144
	ds_read_b128 v[200:203], v143 offset:7168
	global_load_lds_dwordx4 v[140:141], off
	v_lshl_add_u64 v[140:141], s[18:19], 0, v[132:133]
	s_add_i32 m0, s67, 0xe000
	s_nop 0
	global_load_lds_dwordx4 v[140:141], off
	s_waitcnt vmcnt(8)
	s_waitcnt lgkmcnt(0)
	s_barrier
	s_setprio 1
	s_waitcnt lgkmcnt(0)
	v_mfma_f32_16x16x32_bf16 v[126:129], v[136:139], v[172:175], v[126:129]
	v_mfma_f32_16x16x32_bf16 v[122:125], v[148:151], v[172:175], v[122:125]
	v_mfma_f32_16x16x32_bf16 v[110:113], v[136:139], v[180:183], v[110:113]
	v_mfma_f32_16x16x32_bf16 v[106:109], v[148:151], v[180:183], v[106:109]
	v_mfma_f32_16x16x32_bf16 v[92:95], v[136:139], v[188:191], v[92:95]
	v_mfma_f32_16x16x32_bf16 v[88:91], v[148:151], v[188:191], v[88:91]
	v_mfma_f32_16x16x32_bf16 v[76:79], v[136:139], v[196:199], v[76:79]
	v_mfma_f32_16x16x32_bf16 v[72:75], v[148:151], v[196:199], v[72:75]
	v_mfma_f32_16x16x32_bf16 v[126:129], v[144:147], v[176:179], v[126:129]
	v_mfma_f32_16x16x32_bf16 v[122:125], v[152:155], v[176:179], v[122:125]
	v_mfma_f32_16x16x32_bf16 v[110:113], v[144:147], v[184:187], v[110:113]
	v_mfma_f32_16x16x32_bf16 v[106:109], v[152:155], v[184:187], v[106:109]
	v_mfma_f32_16x16x32_bf16 v[92:95], v[144:147], v[192:195], v[92:95]
	v_mfma_f32_16x16x32_bf16 v[88:91], v[152:155], v[192:195], v[88:91]
	v_mfma_f32_16x16x32_bf16 v[76:79], v[144:147], v[200:203], v[76:79]
	v_mfma_f32_16x16x32_bf16 v[72:75], v[152:155], v[200:203], v[72:75]
	v_mfma_f32_16x16x32_bf16 v[118:121], v[156:159], v[172:175], v[118:121]
	v_mfma_f32_16x16x32_bf16 v[114:117], v[164:167], v[172:175], v[114:117]
	v_mfma_f32_16x16x32_bf16 v[102:105], v[156:159], v[180:183], v[102:105]
	v_mfma_f32_16x16x32_bf16 v[98:101], v[164:167], v[180:183], v[98:101]
	v_mfma_f32_16x16x32_bf16 v[84:87], v[156:159], v[188:191], v[84:87]
	v_mfma_f32_16x16x32_bf16 v[80:83], v[164:167], v[188:191], v[80:83]
	v_mfma_f32_16x16x32_bf16 v[68:71], v[156:159], v[196:199], v[68:71]
	v_mfma_f32_16x16x32_bf16 v[64:67], v[164:167], v[196:199], v[64:67]
	v_mfma_f32_16x16x32_bf16 v[118:121], v[160:163], v[176:179], v[118:121]
	v_mfma_f32_16x16x32_bf16 v[114:117], v[168:171], v[176:179], v[114:117]
	v_mfma_f32_16x16x32_bf16 v[102:105], v[160:163], v[184:187], v[102:105]
	v_mfma_f32_16x16x32_bf16 v[98:101], v[168:171], v[184:187], v[98:101]
	v_mfma_f32_16x16x32_bf16 v[84:87], v[160:163], v[192:195], v[84:87]
	v_mfma_f32_16x16x32_bf16 v[80:83], v[168:171], v[192:195], v[80:83]
	v_mfma_f32_16x16x32_bf16 v[68:71], v[160:163], v[200:203], v[68:71]
	v_mfma_f32_16x16x32_bf16 v[64:67], v[168:171], v[200:203], v[64:67]
	s_setprio 0
	s_barrier
	s_add_i32 s18, s35, s14
	v_lshl_add_u64 v[140:141], s[44:45], 0, v[96:97]
	s_mov_b32 m0, s18
	ds_read_b128 v[172:175], v143 offset:16384
	ds_read_b128 v[176:179], v143 offset:17408
	ds_read_b128 v[180:183], v143 offset:18432
	ds_read_b128 v[184:187], v143 offset:19456
	ds_read_b128 v[188:191], v143 offset:20480
	ds_read_b128 v[192:195], v143 offset:21504
	ds_read_b128 v[196:199], v143 offset:22528
	ds_read_b128 v[200:203], v143 offset:23552
	global_load_lds_dwordx4 v[140:141], off
	s_add_i32 m0, s18, 0x2000
	s_add_u32 s18, s44, 0x40000
	v_lshl_add_u64 v[140:141], s[44:45], 0, v[134:135]
	s_addc_u32 s19, s45, 0
	s_add_i32 s35, s49, s14
	global_load_lds_dwordx4 v[140:141], off
	v_lshl_add_u64 v[140:141], s[18:19], 0, v[96:97]
	s_mov_b32 m0, s35
	s_nop 0
	global_load_lds_dwordx4 v[140:141], off
	v_lshl_add_u64 v[140:141], s[18:19], 0, v[134:135]
	s_add_i32 m0, s35, 0x2000
	s_nop 0
	global_load_lds_dwordx4 v[140:141], off
	v_lshl_add_u64 v[140:141], s[42:43], 0, v[130:131]
	s_mov_b32 m0, s67
	s_nop 0
	global_load_lds_dwordx4 v[140:141], off
	v_lshl_add_u64 v[140:141], s[42:43], 0, v[132:133]
	s_mov_b32 m0, s73
	s_nop 0
	global_load_lds_dwordx4 v[140:141], off
	s_waitcnt vmcnt(8)
	s_waitcnt lgkmcnt(0)
	s_barrier
	s_setprio 1
	s_waitcnt lgkmcnt(0)
	v_mfma_f32_16x16x32_bf16 v[60:63], v[136:139], v[172:175], v[60:63]
	v_mfma_f32_16x16x32_bf16 v[56:59], v[148:151], v[172:175], v[56:59]
	v_mfma_f32_16x16x32_bf16 v[44:47], v[136:139], v[180:183], v[44:47]
	v_mfma_f32_16x16x32_bf16 v[40:43], v[148:151], v[180:183], v[40:43]
	v_mfma_f32_16x16x32_bf16 v[28:31], v[136:139], v[188:191], v[28:31]
	v_mfma_f32_16x16x32_bf16 v[24:27], v[148:151], v[188:191], v[24:27]
	v_mfma_f32_16x16x32_bf16 v[12:15], v[136:139], v[196:199], v[12:15]
	v_mfma_f32_16x16x32_bf16 v[8:11], v[148:151], v[196:199], v[8:11]
	v_mfma_f32_16x16x32_bf16 v[60:63], v[144:147], v[176:179], v[60:63]
	v_mfma_f32_16x16x32_bf16 v[56:59], v[152:155], v[176:179], v[56:59]
	v_mfma_f32_16x16x32_bf16 v[44:47], v[144:147], v[184:187], v[44:47]
	v_mfma_f32_16x16x32_bf16 v[40:43], v[152:155], v[184:187], v[40:43]
	v_mfma_f32_16x16x32_bf16 v[28:31], v[144:147], v[192:195], v[28:31]
	v_mfma_f32_16x16x32_bf16 v[24:27], v[152:155], v[192:195], v[24:27]
	v_mfma_f32_16x16x32_bf16 v[12:15], v[144:147], v[200:203], v[12:15]
	v_mfma_f32_16x16x32_bf16 v[8:11], v[152:155], v[200:203], v[8:11]
	v_mfma_f32_16x16x32_bf16 v[52:55], v[156:159], v[172:175], v[52:55]
	v_mfma_f32_16x16x32_bf16 v[48:51], v[164:167], v[172:175], v[48:51]
	v_mfma_f32_16x16x32_bf16 v[36:39], v[156:159], v[180:183], v[36:39]
	v_mfma_f32_16x16x32_bf16 v[32:35], v[164:167], v[180:183], v[32:35]
	v_mfma_f32_16x16x32_bf16 v[20:23], v[156:159], v[188:191], v[20:23]
	v_mfma_f32_16x16x32_bf16 v[16:19], v[164:167], v[188:191], v[16:19]
	v_mfma_f32_16x16x32_bf16 v[4:7], v[156:159], v[196:199], v[4:7]
	v_mfma_f32_16x16x32_bf16 v[0:3], v[164:167], v[196:199], v[0:3]
	v_mfma_f32_16x16x32_bf16 v[52:55], v[160:163], v[176:179], v[52:55]
	v_mfma_f32_16x16x32_bf16 v[48:51], v[168:171], v[176:179], v[48:51]
	v_mfma_f32_16x16x32_bf16 v[36:39], v[160:163], v[184:187], v[36:39]
	v_mfma_f32_16x16x32_bf16 v[32:35], v[168:171], v[184:187], v[32:35]
	v_mfma_f32_16x16x32_bf16 v[20:23], v[160:163], v[192:195], v[20:23]
	v_mfma_f32_16x16x32_bf16 v[16:19], v[168:171], v[192:195], v[16:19]
	v_mfma_f32_16x16x32_bf16 v[4:7], v[160:163], v[200:203], v[4:7]
	v_mfma_f32_16x16x32_bf16 v[0:3], v[168:171], v[200:203], v[0:3]
	s_setprio 0
	s_barrier
	s_add_i32 s35, 0, 0x18000
	v_add_u32_e32 v140, s35, v142
	s_add_i32 s44, 0, 0x1c000
	ds_read_b128 v[136:139], v140
	ds_read_b128 v[144:147], v140 offset:1024
	ds_read_b128 v[148:151], v140 offset:2048
	ds_read_b128 v[152:155], v140 offset:3072
	v_add_u32_e32 v140, s44, v142
	ds_read_b128 v[156:159], v140
	ds_read_b128 v[160:163], v140 offset:1024
	ds_read_b128 v[164:167], v140 offset:2048
	ds_read_b128 v[168:171], v140 offset:3072
	s_add_u32 s18, s42, 0x40000
	s_addc_u32 s19, s43, 0
	s_mov_b32 m0, s76
	v_lshl_add_u64 v[140:141], s[18:19], 0, v[130:131]
	ds_read_b128 v[172:175], v143 offset:32768
	ds_read_b128 v[176:179], v143 offset:33792
	ds_read_b128 v[180:183], v143 offset:34816
	ds_read_b128 v[184:187], v143 offset:35840
	ds_read_b128 v[188:191], v143 offset:36864
	ds_read_b128 v[192:195], v143 offset:37888
	ds_read_b128 v[196:199], v143 offset:38912
	ds_read_b128 v[200:203], v143 offset:39936
	global_load_lds_dwordx4 v[140:141], off
	v_lshl_add_u64 v[140:141], s[18:19], 0, v[132:133]
	s_mov_b32 m0, s77
	s_nop 0
	global_load_lds_dwordx4 v[140:141], off
	s_waitcnt vmcnt(8)
	s_waitcnt lgkmcnt(0)
	s_barrier
	s_setprio 1
	s_waitcnt lgkmcnt(0)
	v_mfma_f32_16x16x32_bf16 v[126:129], v[136:139], v[172:175], v[126:129]
	v_mfma_f32_16x16x32_bf16 v[122:125], v[148:151], v[172:175], v[122:125]
	v_mfma_f32_16x16x32_bf16 v[110:113], v[136:139], v[180:183], v[110:113]
	v_mfma_f32_16x16x32_bf16 v[106:109], v[148:151], v[180:183], v[106:109]
	v_mfma_f32_16x16x32_bf16 v[92:95], v[136:139], v[188:191], v[92:95]
	v_mfma_f32_16x16x32_bf16 v[88:91], v[148:151], v[188:191], v[88:91]
	v_mfma_f32_16x16x32_bf16 v[76:79], v[136:139], v[196:199], v[76:79]
	v_mfma_f32_16x16x32_bf16 v[72:75], v[148:151], v[196:199], v[72:75]
	v_mfma_f32_16x16x32_bf16 v[126:129], v[144:147], v[176:179], v[126:129]
	v_mfma_f32_16x16x32_bf16 v[122:125], v[152:155], v[176:179], v[122:125]
	v_mfma_f32_16x16x32_bf16 v[110:113], v[144:147], v[184:187], v[110:113]
	v_mfma_f32_16x16x32_bf16 v[106:109], v[152:155], v[184:187], v[106:109]
	v_mfma_f32_16x16x32_bf16 v[92:95], v[144:147], v[192:195], v[92:95]
	v_mfma_f32_16x16x32_bf16 v[88:91], v[152:155], v[192:195], v[88:91]
	v_mfma_f32_16x16x32_bf16 v[76:79], v[144:147], v[200:203], v[76:79]
	v_mfma_f32_16x16x32_bf16 v[72:75], v[152:155], v[200:203], v[72:75]
	v_mfma_f32_16x16x32_bf16 v[118:121], v[156:159], v[172:175], v[118:121]
	v_mfma_f32_16x16x32_bf16 v[114:117], v[164:167], v[172:175], v[114:117]
	v_mfma_f32_16x16x32_bf16 v[102:105], v[156:159], v[180:183], v[102:105]
	v_mfma_f32_16x16x32_bf16 v[98:101], v[164:167], v[180:183], v[98:101]
	v_mfma_f32_16x16x32_bf16 v[84:87], v[156:159], v[188:191], v[84:87]
	v_mfma_f32_16x16x32_bf16 v[80:83], v[164:167], v[188:191], v[80:83]
	v_mfma_f32_16x16x32_bf16 v[68:71], v[156:159], v[196:199], v[68:71]
	v_mfma_f32_16x16x32_bf16 v[64:67], v[164:167], v[196:199], v[64:67]
	v_mfma_f32_16x16x32_bf16 v[118:121], v[160:163], v[176:179], v[118:121]
	v_mfma_f32_16x16x32_bf16 v[114:117], v[168:171], v[176:179], v[114:117]
	v_mfma_f32_16x16x32_bf16 v[102:105], v[160:163], v[184:187], v[102:105]
	v_mfma_f32_16x16x32_bf16 v[98:101], v[168:171], v[184:187], v[98:101]
	v_mfma_f32_16x16x32_bf16 v[84:87], v[160:163], v[192:195], v[84:87]
	v_mfma_f32_16x16x32_bf16 v[80:83], v[168:171], v[192:195], v[80:83]
	v_mfma_f32_16x16x32_bf16 v[68:71], v[160:163], v[200:203], v[68:71]
	v_mfma_f32_16x16x32_bf16 v[64:67], v[168:171], v[200:203], v[64:67]
	s_setprio 0
	s_barrier
	s_add_i32 s18, s35, s14
	v_lshl_add_u64 v[140:141], s[74:75], 0, v[96:97]
	s_mov_b32 m0, s18
	ds_read_b128 v[172:175], v143 offset:49152
	ds_read_b128 v[176:179], v143 offset:50176
	ds_read_b128 v[180:183], v143 offset:51200
	ds_read_b128 v[184:187], v143 offset:52224
	ds_read_b128 v[188:191], v143 offset:53248
	ds_read_b128 v[192:195], v143 offset:54272
	ds_read_b128 v[196:199], v143 offset:55296
	ds_read_b128 v[200:203], v143 offset:56320
	global_load_lds_dwordx4 v[140:141], off
	s_add_i32 m0, s18, 0x2000
	s_add_u32 s18, s74, 0x40000
	v_lshl_add_u64 v[140:141], s[74:75], 0, v[134:135]
	s_addc_u32 s19, s75, 0
	s_add_i32 s35, s44, s14
	global_load_lds_dwordx4 v[140:141], off
	v_lshl_add_u64 v[140:141], s[18:19], 0, v[96:97]
	s_mov_b32 m0, s35
	s_nop 0
	global_load_lds_dwordx4 v[140:141], off
	v_lshl_add_u64 v[140:141], s[18:19], 0, v[134:135]
	s_add_i32 m0, s35, 0x2000
	s_nop 0
	global_load_lds_dwordx4 v[140:141], off
	v_lshl_add_u64 v[140:141], s[38:39], 0, v[130:131]
	s_mov_b32 m0, s81
	s_nop 0
	global_load_lds_dwordx4 v[140:141], off
	v_lshl_add_u64 v[140:141], s[38:39], 0, v[132:133]
	s_mov_b32 m0, s82
	s_nop 0
	global_load_lds_dwordx4 v[140:141], off
	s_waitcnt vmcnt(8)
	s_waitcnt lgkmcnt(0)
	s_barrier
	s_setprio 1
	s_waitcnt lgkmcnt(0)
	v_mfma_f32_16x16x32_bf16 v[60:63], v[136:139], v[172:175], v[60:63]
	v_mfma_f32_16x16x32_bf16 v[56:59], v[148:151], v[172:175], v[56:59]
	v_mfma_f32_16x16x32_bf16 v[44:47], v[136:139], v[180:183], v[44:47]
	v_mfma_f32_16x16x32_bf16 v[40:43], v[148:151], v[180:183], v[40:43]
	v_mfma_f32_16x16x32_bf16 v[28:31], v[136:139], v[188:191], v[28:31]
	v_mfma_f32_16x16x32_bf16 v[24:27], v[148:151], v[188:191], v[24:27]
	v_mfma_f32_16x16x32_bf16 v[12:15], v[136:139], v[196:199], v[12:15]
	v_mfma_f32_16x16x32_bf16 v[8:11], v[148:151], v[196:199], v[8:11]
	v_mfma_f32_16x16x32_bf16 v[60:63], v[144:147], v[176:179], v[60:63]
	v_mfma_f32_16x16x32_bf16 v[56:59], v[152:155], v[176:179], v[56:59]
	v_mfma_f32_16x16x32_bf16 v[44:47], v[144:147], v[184:187], v[44:47]
	v_mfma_f32_16x16x32_bf16 v[40:43], v[152:155], v[184:187], v[40:43]
	v_mfma_f32_16x16x32_bf16 v[28:31], v[144:147], v[192:195], v[28:31]
	v_mfma_f32_16x16x32_bf16 v[24:27], v[152:155], v[192:195], v[24:27]
	v_mfma_f32_16x16x32_bf16 v[12:15], v[144:147], v[200:203], v[12:15]
	v_mfma_f32_16x16x32_bf16 v[8:11], v[152:155], v[200:203], v[8:11]
	v_mfma_f32_16x16x32_bf16 v[52:55], v[156:159], v[172:175], v[52:55]
	v_mfma_f32_16x16x32_bf16 v[48:51], v[164:167], v[172:175], v[48:51]
	v_mfma_f32_16x16x32_bf16 v[36:39], v[156:159], v[180:183], v[36:39]
	v_mfma_f32_16x16x32_bf16 v[32:35], v[164:167], v[180:183], v[32:35]
	v_mfma_f32_16x16x32_bf16 v[20:23], v[156:159], v[188:191], v[20:23]
	v_mfma_f32_16x16x32_bf16 v[16:19], v[164:167], v[188:191], v[16:19]
	v_mfma_f32_16x16x32_bf16 v[4:7], v[156:159], v[196:199], v[4:7]
	v_mfma_f32_16x16x32_bf16 v[0:3], v[164:167], v[196:199], v[0:3]
	v_mfma_f32_16x16x32_bf16 v[52:55], v[160:163], v[176:179], v[52:55]
	v_mfma_f32_16x16x32_bf16 v[48:51], v[168:171], v[176:179], v[48:51]
	v_mfma_f32_16x16x32_bf16 v[36:39], v[160:163], v[184:187], v[36:39]
	v_mfma_f32_16x16x32_bf16 v[32:35], v[168:171], v[184:187], v[32:35]
	v_mfma_f32_16x16x32_bf16 v[20:23], v[160:163], v[192:195], v[20:23]
	v_mfma_f32_16x16x32_bf16 v[16:19], v[168:171], v[192:195], v[16:19]
	v_mfma_f32_16x16x32_bf16 v[4:7], v[160:163], v[200:203], v[4:7]
	v_mfma_f32_16x16x32_bf16 v[0:3], v[168:171], v[200:203], v[0:3]
	s_setprio 0
	s_barrier
	s_add_i32 s89, s89, 2
	s_add_u32 s65, s65, 0x100
	s_addc_u32 s86, s86, 0
	s_add_u32 s87, s87, 0x100
	s_addc_u32 s88, s88, 0
	s_add_u32 s68, s68, 0x100
	s_addc_u32 s69, s69, 0
	s_cmp_gt_u32 s89, 13
	s_cbranch_scc0 .LBB0_122
	s_and_b64 vcc, exec, s[28:29]
	s_cbranch_vccz .LBB0_125
	s_barrier

.LBB0_195:
	s_cmp_eq_u32 s72, s76
	s_cselect_b64 s[18:19], -1, 0
	s_add_i32 s76, s76, 2
	s_and_b64 s[42:43], s[18:19], exec
	s_cselect_b32 s44, s38, s73
	s_cselect_b32 s45, s39, s75
	s_cselect_b32 s47, s61, vcc_hi
	s_cselect_b32 s46, s60, vcc_lo
	s_add_u32 s58, s44, 0x80
	s_addc_u32 s59, s45, 0
	s_add_u32 s42, s46, 0x80
	s_addc_u32 s43, s47, 0
	s_add_i32 s35, 0, 0x10000
	s_and_b64 s[30:31], s[18:19], exec
	s_mov_b64 s[68:69], s[78:79]
	v_add_u32_e32 v144, s35, v170
	s_cselect_b32 s49, s29, s14
	s_add_i32 s70, 0, 0x14000
	ds_read_b128 v[132:135], v144
	ds_read_b128 v[136:139], v144 offset:1024
	ds_read_b128 v[140:143], v144 offset:2048
	ds_read_b128 v[150:153], v144 offset:3072
	v_add_u32_e32 v144, s70, v170
	ds_read_b128 v[154:157], v144
	ds_read_b128 v[158:161], v144 offset:1024
	ds_read_b128 v[162:165], v144 offset:2048
	ds_read_b128 v[172:175], v144 offset:3072
	s_and_b64 s[18:19], s[18:19], exec
	s_cselect_b32 s18, 0, s67
	s_cselect_b32 s19, s20, s66
	s_add_u32 s30, s68, s66
	s_addc_u32 s31, s69, s67
	v_lshl_add_u64 v[144:145], s[30:31], 0, v[96:97]
	s_add_i32 m0, s63, 0xc000
	ds_read_b128 v[176:179], v171
	ds_read_b128 v[180:183], v171 offset:1024
	ds_read_b128 v[184:187], v171 offset:2048
	ds_read_b128 v[188:191], v171 offset:3072
	ds_read_b128 v[192:195], v171 offset:4096
	ds_read_b128 v[196:199], v171 offset:5120
	ds_read_b128 v[200:203], v171 offset:6144
	ds_read_b128 v[204:207], v171 offset:7168
	global_load_lds_dwordx4 v[144:145], off
	v_lshl_add_u64 v[144:145], s[30:31], 0, v[130:131]
	s_add_i32 m0, s63, 0xe000
	s_nop 0
	global_load_lds_dwordx4 v[144:145], off
	s_waitcnt vmcnt(8)
	s_waitcnt lgkmcnt(0)
	s_barrier
	s_setprio 1
	s_waitcnt lgkmcnt(0)
	v_mfma_f32_16x16x32_bf16 v[126:129], v[132:135], v[176:179], v[126:129]
	v_mfma_f32_16x16x32_bf16 v[122:125], v[140:143], v[176:179], v[122:125]
	v_mfma_f32_16x16x32_bf16 v[110:113], v[132:135], v[184:187], v[110:113]
	v_mfma_f32_16x16x32_bf16 v[106:109], v[140:143], v[184:187], v[106:109]
	v_mfma_f32_16x16x32_bf16 v[92:95], v[132:135], v[192:195], v[92:95]
	v_mfma_f32_16x16x32_bf16 v[88:91], v[140:143], v[192:195], v[88:91]
	v_mfma_f32_16x16x32_bf16 v[76:79], v[132:135], v[200:203], v[76:79]
	v_mfma_f32_16x16x32_bf16 v[72:75], v[140:143], v[200:203], v[72:75]
	v_mfma_f32_16x16x32_bf16 v[126:129], v[136:139], v[180:183], v[126:129]
	v_mfma_f32_16x16x32_bf16 v[122:125], v[150:153], v[180:183], v[122:125]
	v_mfma_f32_16x16x32_bf16 v[110:113], v[136:139], v[188:191], v[110:113]
	v_mfma_f32_16x16x32_bf16 v[106:109], v[150:153], v[188:191], v[106:109]
	v_mfma_f32_16x16x32_bf16 v[92:95], v[136:139], v[196:199], v[92:95]
	v_mfma_f32_16x16x32_bf16 v[88:91], v[150:153], v[196:199], v[88:91]
	v_mfma_f32_16x16x32_bf16 v[76:79], v[136:139], v[204:207], v[76:79]
	v_mfma_f32_16x16x32_bf16 v[72:75], v[150:153], v[204:207], v[72:75]
	v_mfma_f32_16x16x32_bf16 v[118:121], v[154:157], v[176:179], v[118:121]
	v_mfma_f32_16x16x32_bf16 v[114:117], v[162:165], v[176:179], v[114:117]
	v_mfma_f32_16x16x32_bf16 v[102:105], v[154:157], v[184:187], v[102:105]
	v_mfma_f32_16x16x32_bf16 v[98:101], v[162:165], v[184:187], v[98:101]
	v_mfma_f32_16x16x32_bf16 v[84:87], v[154:157], v[192:195], v[84:87]
	v_mfma_f32_16x16x32_bf16 v[80:83], v[162:165], v[192:195], v[80:83]
	v_mfma_f32_16x16x32_bf16 v[68:71], v[154:157], v[200:203], v[68:71]
	v_mfma_f32_16x16x32_bf16 v[64:67], v[162:165], v[200:203], v[64:67]
	v_mfma_f32_16x16x32_bf16 v[118:121], v[158:161], v[180:183], v[118:121]
	v_mfma_f32_16x16x32_bf16 v[114:117], v[172:175], v[180:183], v[114:117]
	v_mfma_f32_16x16x32_bf16 v[102:105], v[158:161], v[188:191], v[102:105]
	v_mfma_f32_16x16x32_bf16 v[98:101], v[172:175], v[188:191], v[98:101]
	v_mfma_f32_16x16x32_bf16 v[84:87], v[158:161], v[196:199], v[84:87]
	v_mfma_f32_16x16x32_bf16 v[80:83], v[172:175], v[196:199], v[80:83]
	v_mfma_f32_16x16x32_bf16 v[68:71], v[158:161], v[204:207], v[68:71]
	v_mfma_f32_16x16x32_bf16 v[64:67], v[172:175], v[204:207], v[64:67]
	s_setprio 0
	s_barrier
	s_add_i32 s35, s35, s80
	v_mad_u64_u32 v[144:145], s[30:31], v168, s49, v[146:147]
	s_mov_b32 m0, s35
	ds_read_b128 v[176:179], v171 offset:16384
	ds_read_b128 v[180:183], v171 offset:17408
	ds_read_b128 v[184:187], v171 offset:18432
	ds_read_b128 v[188:191], v171 offset:19456
	ds_read_b128 v[192:195], v171 offset:20480
	ds_read_b128 v[196:199], v171 offset:21504
	ds_read_b128 v[200:203], v171 offset:22528
	ds_read_b128 v[204:207], v171 offset:23552
	global_load_lds_dwordx4 v144, s[46:47]
	v_mad_u64_u32 v[166:167], s[30:31], v169, s49, v[148:149]
	s_add_i32 m0, s35, 0x2000
	s_add_u32 s30, s46, s19
	s_addc_u32 s31, s47, s18
	s_add_i32 s35, s70, s80
	global_load_lds_dwordx4 v166, s[46:47]
	s_mov_b32 m0, s35
	s_nop 0
	global_load_lds_dwordx4 v144, s[30:31]
	s_add_i32 m0, s35, 0x2000
	s_nop 0
	global_load_lds_dwordx4 v166, s[30:31]
	v_mad_u64_u32 v[208:209], s[30:31], s49, v147, v[146:147]
	s_mov_b32 m0, s63
	v_mad_u64_u32 v[210:211], s[30:31], s49, v149, v[148:149]
	global_load_lds_dwordx4 v208, s[44:45]
	s_mov_b32 m0, s65
	s_nop 0
	global_load_lds_dwordx4 v210, s[44:45]
	s_waitcnt vmcnt(8)
	s_waitcnt lgkmcnt(0)
	s_barrier
	s_setprio 1
	s_waitcnt lgkmcnt(0)
	v_mfma_f32_16x16x32_bf16 v[60:63], v[132:135], v[176:179], v[60:63]
	v_mfma_f32_16x16x32_bf16 v[56:59], v[140:143], v[176:179], v[56:59]
	v_mfma_f32_16x16x32_bf16 v[44:47], v[132:135], v[184:187], v[44:47]
	v_mfma_f32_16x16x32_bf16 v[40:43], v[140:143], v[184:187], v[40:43]
	v_mfma_f32_16x16x32_bf16 v[28:31], v[132:135], v[192:195], v[28:31]
	v_mfma_f32_16x16x32_bf16 v[24:27], v[140:143], v[192:195], v[24:27]
	v_mfma_f32_16x16x32_bf16 v[12:15], v[132:135], v[200:203], v[12:15]
	v_mfma_f32_16x16x32_bf16 v[8:11], v[140:143], v[200:203], v[8:11]
	v_mfma_f32_16x16x32_bf16 v[60:63], v[136:139], v[180:183], v[60:63]
	v_mfma_f32_16x16x32_bf16 v[56:59], v[150:153], v[180:183], v[56:59]
	v_mfma_f32_16x16x32_bf16 v[44:47], v[136:139], v[188:191], v[44:47]
	v_mfma_f32_16x16x32_bf16 v[40:43], v[150:153], v[188:191], v[40:43]
	v_mfma_f32_16x16x32_bf16 v[28:31], v[136:139], v[196:199], v[28:31]
	v_mfma_f32_16x16x32_bf16 v[24:27], v[150:153], v[196:199], v[24:27]
	v_mfma_f32_16x16x32_bf16 v[12:15], v[136:139], v[204:207], v[12:15]
	v_mfma_f32_16x16x32_bf16 v[8:11], v[150:153], v[204:207], v[8:11]
	v_mfma_f32_16x16x32_bf16 v[52:55], v[154:157], v[176:179], v[52:55]
	v_mfma_f32_16x16x32_bf16 v[48:51], v[162:165], v[176:179], v[48:51]
	v_mfma_f32_16x16x32_bf16 v[36:39], v[154:157], v[184:187], v[36:39]
	v_mfma_f32_16x16x32_bf16 v[32:35], v[162:165], v[184:187], v[32:35]
	v_mfma_f32_16x16x32_bf16 v[20:23], v[154:157], v[192:195], v[20:23]
	v_mfma_f32_16x16x32_bf16 v[16:19], v[162:165], v[192:195], v[16:19]
	v_mfma_f32_16x16x32_bf16 v[4:7], v[154:157], v[200:203], v[4:7]
	v_mfma_f32_16x16x32_bf16 v[0:3], v[162:165], v[200:203], v[0:3]
	v_mfma_f32_16x16x32_bf16 v[52:55], v[158:161], v[180:183], v[52:55]
	v_mfma_f32_16x16x32_bf16 v[48:51], v[172:175], v[180:183], v[48:51]
	v_mfma_f32_16x16x32_bf16 v[36:39], v[158:161], v[188:191], v[36:39]
	v_mfma_f32_16x16x32_bf16 v[32:35], v[172:175], v[188:191], v[32:35]
	v_mfma_f32_16x16x32_bf16 v[20:23], v[158:161], v[196:199], v[20:23]
	v_mfma_f32_16x16x32_bf16 v[16:19], v[172:175], v[196:199], v[16:19]
	v_mfma_f32_16x16x32_bf16 v[4:7], v[158:161], v[204:207], v[4:7]
	v_mfma_f32_16x16x32_bf16 v[0:3], v[172:175], v[204:207], v[0:3]
	s_setprio 0
	s_barrier
	s_add_i32 s35, 0, 0x18000
	v_add_u32_e32 v145, s35, v170
	s_add_i32 s46, 0, 0x1c000
	ds_read_b128 v[132:135], v145
	ds_read_b128 v[136:139], v145 offset:1024
	ds_read_b128 v[140:143], v145 offset:2048
	ds_read_b128 v[150:153], v145 offset:3072
	v_add_u32_e32 v145, s46, v170
	ds_read_b128 v[154:157], v145
	ds_read_b128 v[158:161], v145 offset:1024
	ds_read_b128 v[162:165], v145 offset:2048
	ds_read_b128 v[172:175], v145 offset:3072
	s_add_u32 s30, s44, s19
	s_addc_u32 s31, s45, s18
	s_mov_b32 m0, s81
	ds_read_b128 v[176:179], v171 offset:32768
	ds_read_b128 v[180:183], v171 offset:33792
	ds_read_b128 v[184:187], v171 offset:34816
	ds_read_b128 v[188:191], v171 offset:35840
	ds_read_b128 v[192:195], v171 offset:36864
	ds_read_b128 v[196:199], v171 offset:37888
	ds_read_b128 v[200:203], v171 offset:38912
	ds_read_b128 v[204:207], v171 offset:39936
	global_load_lds_dwordx4 v208, s[30:31]
	s_mov_b32 m0, s90
	s_nop 0
	global_load_lds_dwordx4 v210, s[30:31]
	s_waitcnt vmcnt(8)
	s_waitcnt lgkmcnt(0)
	s_barrier
	s_setprio 1
	s_waitcnt lgkmcnt(0)
	v_mfma_f32_16x16x32_bf16 v[126:129], v[132:135], v[176:179], v[126:129]
	v_mfma_f32_16x16x32_bf16 v[122:125], v[140:143], v[176:179], v[122:125]
	v_mfma_f32_16x16x32_bf16 v[110:113], v[132:135], v[184:187], v[110:113]
	v_mfma_f32_16x16x32_bf16 v[106:109], v[140:143], v[184:187], v[106:109]
	v_mfma_f32_16x16x32_bf16 v[92:95], v[132:135], v[192:195], v[92:95]
	v_mfma_f32_16x16x32_bf16 v[88:91], v[140:143], v[192:195], v[88:91]
	v_mfma_f32_16x16x32_bf16 v[76:79], v[132:135], v[200:203], v[76:79]
	v_mfma_f32_16x16x32_bf16 v[72:75], v[140:143], v[200:203], v[72:75]
	v_mfma_f32_16x16x32_bf16 v[126:129], v[136:139], v[180:183], v[126:129]
	v_mfma_f32_16x16x32_bf16 v[122:125], v[150:153], v[180:183], v[122:125]
	v_mfma_f32_16x16x32_bf16 v[110:113], v[136:139], v[188:191], v[110:113]
	v_mfma_f32_16x16x32_bf16 v[106:109], v[150:153], v[188:191], v[106:109]
	v_mfma_f32_16x16x32_bf16 v[92:95], v[136:139], v[196:199], v[92:95]
	v_mfma_f32_16x16x32_bf16 v[88:91], v[150:153], v[196:199], v[88:91]
	v_mfma_f32_16x16x32_bf16 v[76:79], v[136:139], v[204:207], v[76:79]
	v_mfma_f32_16x16x32_bf16 v[72:75], v[150:153], v[204:207], v[72:75]
	v_mfma_f32_16x16x32_bf16 v[118:121], v[154:157], v[176:179], v[118:121]
	v_mfma_f32_16x16x32_bf16 v[114:117], v[162:165], v[176:179], v[114:117]
	v_mfma_f32_16x16x32_bf16 v[102:105], v[154:157], v[184:187], v[102:105]
	v_mfma_f32_16x16x32_bf16 v[98:101], v[162:165], v[184:187], v[98:101]
	v_mfma_f32_16x16x32_bf16 v[84:87], v[154:157], v[192:195], v[84:87]
	v_mfma_f32_16x16x32_bf16 v[80:83], v[162:165], v[192:195], v[80:83]
	v_mfma_f32_16x16x32_bf16 v[68:71], v[154:157], v[200:203], v[68:71]
	v_mfma_f32_16x16x32_bf16 v[64:67], v[162:165], v[200:203], v[64:67]
	v_mfma_f32_16x16x32_bf16 v[118:121], v[158:161], v[180:183], v[118:121]
	v_mfma_f32_16x16x32_bf16 v[114:117], v[172:175], v[180:183], v[114:117]
	v_mfma_f32_16x16x32_bf16 v[102:105], v[158:161], v[188:191], v[102:105]
	v_mfma_f32_16x16x32_bf16 v[98:101], v[172:175], v[188:191], v[98:101]
	v_mfma_f32_16x16x32_bf16 v[84:87], v[158:161], v[196:199], v[84:87]
	v_mfma_f32_16x16x32_bf16 v[80:83], v[172:175], v[196:199], v[80:83]
	v_mfma_f32_16x16x32_bf16 v[68:71], v[158:161], v[204:207], v[68:71]
	v_mfma_f32_16x16x32_bf16 v[64:67], v[172:175], v[204:207], v[64:67]
	s_setprio 0
	s_barrier
	s_add_i32 s30, s35, s80
	s_mov_b32 m0, s30
	ds_read_b128 v[176:179], v171 offset:49152
	ds_read_b128 v[180:183], v171 offset:50176
	ds_read_b128 v[184:187], v171 offset:51200
	ds_read_b128 v[188:191], v171 offset:52224
	ds_read_b128 v[192:195], v171 offset:53248
	ds_read_b128 v[196:199], v171 offset:54272
	ds_read_b128 v[200:203], v171 offset:55296
	ds_read_b128 v[204:207], v171 offset:56320
	global_load_lds_dwordx4 v144, s[42:43]
	s_add_i32 m0, s30, 0x2000
	s_add_u32 s30, s42, s19
	s_addc_u32 s31, s43, s18
	s_add_i32 s18, s46, s80
	global_load_lds_dwordx4 v166, s[42:43]
	s_mov_b32 m0, s18
	s_nop 0
	global_load_lds_dwordx4 v144, s[30:31]
	s_add_i32 m0, s18, 0x2000
	s_nop 0
	global_load_lds_dwordx4 v166, s[30:31]
	s_mov_b32 m0, s82
	s_nop 0
	global_load_lds_dwordx4 v208, s[58:59]
	s_mov_b32 m0, s83
	s_nop 0
	global_load_lds_dwordx4 v210, s[58:59]
	s_waitcnt vmcnt(8)
	s_waitcnt lgkmcnt(0)
	s_barrier
	s_setprio 1
	s_waitcnt lgkmcnt(0)
	v_mfma_f32_16x16x32_bf16 v[60:63], v[132:135], v[176:179], v[60:63]
	v_mfma_f32_16x16x32_bf16 v[56:59], v[140:143], v[176:179], v[56:59]
	v_mfma_f32_16x16x32_bf16 v[44:47], v[132:135], v[184:187], v[44:47]
	v_mfma_f32_16x16x32_bf16 v[40:43], v[140:143], v[184:187], v[40:43]
	v_mfma_f32_16x16x32_bf16 v[28:31], v[132:135], v[192:195], v[28:31]
	v_mfma_f32_16x16x32_bf16 v[24:27], v[140:143], v[192:195], v[24:27]
	v_mfma_f32_16x16x32_bf16 v[12:15], v[132:135], v[200:203], v[12:15]
	v_mfma_f32_16x16x32_bf16 v[8:11], v[140:143], v[200:203], v[8:11]
	v_mfma_f32_16x16x32_bf16 v[60:63], v[136:139], v[180:183], v[60:63]
	v_mfma_f32_16x16x32_bf16 v[56:59], v[150:153], v[180:183], v[56:59]
	v_mfma_f32_16x16x32_bf16 v[44:47], v[136:139], v[188:191], v[44:47]
	v_mfma_f32_16x16x32_bf16 v[40:43], v[150:153], v[188:191], v[40:43]
	v_mfma_f32_16x16x32_bf16 v[28:31], v[136:139], v[196:199], v[28:31]
	v_mfma_f32_16x16x32_bf16 v[24:27], v[150:153], v[196:199], v[24:27]
	v_mfma_f32_16x16x32_bf16 v[12:15], v[136:139], v[204:207], v[12:15]
	v_mfma_f32_16x16x32_bf16 v[8:11], v[150:153], v[204:207], v[8:11]
	v_mfma_f32_16x16x32_bf16 v[52:55], v[154:157], v[176:179], v[52:55]
	v_mfma_f32_16x16x32_bf16 v[48:51], v[162:165], v[176:179], v[48:51]
	v_mfma_f32_16x16x32_bf16 v[36:39], v[154:157], v[184:187], v[36:39]
	v_mfma_f32_16x16x32_bf16 v[32:35], v[162:165], v[184:187], v[32:35]
	v_mfma_f32_16x16x32_bf16 v[20:23], v[154:157], v[192:195], v[20:23]
	v_mfma_f32_16x16x32_bf16 v[16:19], v[162:165], v[192:195], v[16:19]
	v_mfma_f32_16x16x32_bf16 v[4:7], v[154:157], v[200:203], v[4:7]
	v_mfma_f32_16x16x32_bf16 v[0:3], v[162:165], v[200:203], v[0:3]
	v_mfma_f32_16x16x32_bf16 v[52:55], v[158:161], v[180:183], v[52:55]
	v_mfma_f32_16x16x32_bf16 v[48:51], v[172:175], v[180:183], v[48:51]
	v_mfma_f32_16x16x32_bf16 v[36:39], v[158:161], v[188:191], v[36:39]
	v_mfma_f32_16x16x32_bf16 v[32:35], v[172:175], v[188:191], v[32:35]
	v_mfma_f32_16x16x32_bf16 v[20:23], v[158:161], v[196:199], v[20:23]
	v_mfma_f32_16x16x32_bf16 v[16:19], v[172:175], v[196:199], v[16:19]
	v_mfma_f32_16x16x32_bf16 v[4:7], v[158:161], v[204:207], v[4:7]
	v_mfma_f32_16x16x32_bf16 v[0:3], v[172:175], v[204:207], v[0:3]
	s_setprio 0
	s_barrier
	s_add_u32 s73, s73, 0x100
	s_addc_u32 s75, s75, 0
	s_add_u32 vcc_lo, vcc_lo, 0x100
	s_addc_u32 vcc_hi, vcc_hi, 0
	s_add_u32 s78, s78, 0x100
	s_addc_u32 s79, s79, 0
	s_cmp_ge_u32 s76, s16
	s_cbranch_scc0 .LBB0_195
	s_and_b64 vcc, exec, s[96:97]
	s_cbranch_vccz .LBB0_198
	s_barrier

.LBB0_383:
	s_add_u32 s18, s78, 0x80
	s_addc_u32 s19, s79, 0
	s_add_u32 s42, s78, 0x100
	s_addc_u32 s43, s79, 0
	s_add_u32 s44, s76, 0x100
	s_addc_u32 s45, s77, 0
	s_add_u32 s80, s78, 0x180
	s_addc_u32 s81, s79, 0
	s_add_u32 s84, s76, 0x180
	s_addc_u32 s85, s77, 0
	s_add_i32 vcc_hi, 0, 0x10000
	s_add_i32 s22, 0, 0x14000
	s_mov_b64 s[82:83], s[80:81]
	v_add_u32_e32 v0, vcc_hi, v155
	v_add_u32_e32 v1, s22, v155
	ds_read_b128 v[2:5], v0
	ds_read_b128 v[6:9], v0 offset:1024
	ds_read_b128 v[10:13], v0 offset:2048
	ds_read_b128 v[14:17], v0 offset:3072
	ds_read_b128 v[18:21], v1
	ds_read_b128 v[22:25], v1 offset:1024
	ds_read_b128 v[26:29], v1 offset:2048
	ds_read_b128 v[30:33], v1 offset:3072
	s_add_u32 s18, s18, 0x18000
	s_addc_u32 s19, s19, 0
	s_add_i32 s88, s49, 0xc000
	v_lshl_add_u64 v[66:67], s[18:19], 0, v[136:137]
	s_mov_b32 m0, s88
	s_add_i32 vcc_lo, s49, 0xe000
	ds_read_b128 v[34:37], v157
	ds_read_b128 v[38:41], v157 offset:1024
	ds_read_b128 v[42:45], v157 offset:2048
	ds_read_b128 v[46:49], v157 offset:3072
	ds_read_b128 v[50:53], v157 offset:4096
	ds_read_b128 v[54:57], v157 offset:5120
	ds_read_b128 v[58:61], v157 offset:6144
	ds_read_b128 v[62:65], v157 offset:7168
	global_load_lds_dwordx4 v[66:67], off
	v_lshl_add_u64 v[66:67], s[18:19], 0, v[132:133]
	s_mov_b32 m0, vcc_lo
	s_nop 0
	global_load_lds_dwordx4 v[66:67], off
	s_waitcnt vmcnt(8)
	s_waitcnt lgkmcnt(0)
	s_barrier
	s_setprio 1
	s_waitcnt lgkmcnt(0)
	v_mfma_f32_16x16x32_bf16 v[66:69], v[2:5], v[34:37], 0
	v_mfma_f32_16x16x32_bf16 v[70:73], v[10:13], v[34:37], 0
	v_mfma_f32_16x16x32_bf16 v[74:77], v[2:5], v[42:45], 0
	v_mfma_f32_16x16x32_bf16 v[78:81], v[10:13], v[42:45], 0
	v_mfma_f32_16x16x32_bf16 v[82:85], v[2:5], v[50:53], 0
	v_mfma_f32_16x16x32_bf16 v[86:89], v[10:13], v[50:53], 0
	v_mfma_f32_16x16x32_bf16 v[90:93], v[2:5], v[58:61], 0
	v_mfma_f32_16x16x32_bf16 v[98:101], v[10:13], v[58:61], 0
	v_mfma_f32_16x16x32_bf16 v[66:69], v[6:9], v[38:41], v[66:69]
	v_mfma_f32_16x16x32_bf16 v[70:73], v[14:17], v[38:41], v[70:73]
	v_mfma_f32_16x16x32_bf16 v[74:77], v[6:9], v[46:49], v[74:77]
	v_mfma_f32_16x16x32_bf16 v[78:81], v[14:17], v[46:49], v[78:81]
	v_mfma_f32_16x16x32_bf16 v[82:85], v[6:9], v[54:57], v[82:85]
	v_mfma_f32_16x16x32_bf16 v[86:89], v[14:17], v[54:57], v[86:89]
	v_mfma_f32_16x16x32_bf16 v[90:93], v[6:9], v[62:65], v[90:93]
	v_mfma_f32_16x16x32_bf16 v[98:101], v[14:17], v[62:65], v[98:101]
	v_mfma_f32_16x16x32_bf16 v[102:105], v[18:21], v[34:37], 0
	v_mfma_f32_16x16x32_bf16 v[34:37], v[26:29], v[34:37], 0
	v_mfma_f32_16x16x32_bf16 v[102:105], v[22:25], v[38:41], v[102:105]
	v_mfma_f32_16x16x32_bf16 v[34:37], v[30:33], v[38:41], v[34:37]
	v_mfma_f32_16x16x32_bf16 v[38:41], v[18:21], v[42:45], 0
	v_mfma_f32_16x16x32_bf16 v[42:45], v[26:29], v[42:45], 0
	v_mfma_f32_16x16x32_bf16 v[38:41], v[22:25], v[46:49], v[38:41]
	v_mfma_f32_16x16x32_bf16 v[42:45], v[30:33], v[46:49], v[42:45]
	v_mfma_f32_16x16x32_bf16 v[46:49], v[18:21], v[50:53], 0
	v_mfma_f32_16x16x32_bf16 v[50:53], v[26:29], v[50:53], 0
	v_mfma_f32_16x16x32_bf16 v[46:49], v[22:25], v[54:57], v[46:49]
	v_mfma_f32_16x16x32_bf16 v[50:53], v[30:33], v[54:57], v[50:53]
	v_mfma_f32_16x16x32_bf16 v[54:57], v[18:21], v[58:61], 0
	v_mfma_f32_16x16x32_bf16 v[58:61], v[26:29], v[58:61], 0
	v_mfma_f32_16x16x32_bf16 v[54:57], v[22:25], v[62:65], v[54:57]
	v_mfma_f32_16x16x32_bf16 v[58:61], v[30:33], v[62:65], v[58:61]
	s_setprio 0
	s_barrier
	s_add_i32 vcc_hi, vcc_hi, s75
	s_add_i32 s70, vcc_hi, 0x2000
	v_lshl_add_u64 v[94:95], s[44:45], 0, v[134:135]
	s_mov_b32 m0, vcc_hi
	s_add_u32 s18, s44, 0x18000
	ds_read_b128 v[62:65], v157 offset:16384
	ds_read_b128 v[106:109], v157 offset:17408
	ds_read_b128 v[110:113], v157 offset:18432
	ds_read_b128 v[114:117], v157 offset:19456
	ds_read_b128 v[118:121], v157 offset:20480
	ds_read_b128 v[122:125], v157 offset:21504
	ds_read_b128 v[126:129], v157 offset:22528
	ds_read_b128 v[138:141], v157 offset:23552
	global_load_lds_dwordx4 v[94:95], off
	v_lshl_add_u64 v[94:95], s[44:45], 0, v[130:131]
	s_mov_b32 m0, s70
	s_addc_u32 s19, s45, 0
	s_add_i32 s22, s22, s75
	global_load_lds_dwordx4 v[94:95], off
	v_lshl_add_u64 v[94:95], s[18:19], 0, v[134:135]
	s_mov_b32 m0, s22
	s_add_i32 s23, s22, 0x2000
	global_load_lds_dwordx4 v[94:95], off
	v_lshl_add_u64 v[94:95], s[18:19], 0, v[130:131]
	s_mov_b32 m0, s23
	s_nop 0
	global_load_lds_dwordx4 v[94:95], off
	v_lshl_add_u64 v[94:95], s[42:43], 0, v[136:137]
	s_mov_b32 m0, s49
	s_nop 0
	global_load_lds_dwordx4 v[94:95], off
	v_lshl_add_u64 v[94:95], s[42:43], 0, v[132:133]
	s_mov_b32 m0, s89
	s_nop 0
	global_load_lds_dwordx4 v[94:95], off
	s_waitcnt vmcnt(8)
	s_waitcnt lgkmcnt(0)
	s_barrier
	s_setprio 1
	s_waitcnt lgkmcnt(0)
	v_mfma_f32_16x16x32_bf16 v[142:145], v[2:5], v[62:65], 0
	v_mfma_f32_16x16x32_bf16 v[150:153], v[2:5], v[110:113], 0
	v_mfma_f32_16x16x32_bf16 v[162:165], v[2:5], v[118:121], 0
	v_mfma_f32_16x16x32_bf16 v[2:5], v[2:5], v[126:129], 0
	v_mfma_f32_16x16x32_bf16 v[142:145], v[6:9], v[106:109], v[142:145]
	v_mfma_f32_16x16x32_bf16 v[146:149], v[10:13], v[62:65], 0
	v_mfma_f32_16x16x32_bf16 v[150:153], v[6:9], v[114:117], v[150:153]
	v_mfma_f32_16x16x32_bf16 v[158:161], v[10:13], v[110:113], 0
	v_mfma_f32_16x16x32_bf16 v[162:165], v[6:9], v[122:125], v[162:165]
	v_mfma_f32_16x16x32_bf16 v[166:169], v[10:13], v[118:121], 0
	v_mfma_f32_16x16x32_bf16 v[4:7], v[6:9], v[138:141], v[2:5]
	v_mfma_f32_16x16x32_bf16 v[8:11], v[10:13], v[126:129], 0
	v_mfma_f32_16x16x32_bf16 v[8:11], v[14:17], v[138:141], v[8:11]
	v_mfma_f32_16x16x32_bf16 v[146:149], v[14:17], v[106:109], v[146:149]
	v_mfma_f32_16x16x32_bf16 v[158:161], v[14:17], v[114:117], v[158:161]
	v_mfma_f32_16x16x32_bf16 v[166:169], v[14:17], v[122:125], v[166:169]
	v_mfma_f32_16x16x32_bf16 v[12:15], v[18:21], v[62:65], 0
	v_mfma_f32_16x16x32_bf16 v[62:65], v[26:29], v[62:65], 0
	v_mfma_f32_16x16x32_bf16 v[12:15], v[22:25], v[106:109], v[12:15]
	v_mfma_f32_16x16x32_bf16 v[62:65], v[30:33], v[106:109], v[62:65]
	v_mfma_f32_16x16x32_bf16 v[106:109], v[18:21], v[110:113], 0
	v_mfma_f32_16x16x32_bf16 v[110:113], v[26:29], v[110:113], 0
	v_mfma_f32_16x16x32_bf16 v[106:109], v[22:25], v[114:117], v[106:109]
	v_mfma_f32_16x16x32_bf16 v[110:113], v[30:33], v[114:117], v[110:113]
	v_mfma_f32_16x16x32_bf16 v[114:117], v[18:21], v[118:121], 0
	v_mfma_f32_16x16x32_bf16 v[16:19], v[18:21], v[126:129], 0
	v_mfma_f32_16x16x32_bf16 v[114:117], v[22:25], v[122:125], v[114:117]
	v_mfma_f32_16x16x32_bf16 v[118:121], v[26:29], v[118:121], 0
	v_mfma_f32_16x16x32_bf16 v[16:19], v[22:25], v[138:141], v[16:19]
	v_mfma_f32_16x16x32_bf16 v[20:23], v[26:29], v[126:129], 0
	v_mfma_f32_16x16x32_bf16 v[118:121], v[30:33], v[122:125], v[118:121]
	v_mfma_f32_16x16x32_bf16 v[20:23], v[30:33], v[138:141], v[20:23]
	s_setprio 0
	s_barrier
	s_add_i32 s35, 0, 0x18000
	s_add_i32 s44, 0, 0x1c000
	v_add_u32_e32 v2, s35, v155
	v_add_u32_e32 v3, s44, v155
	ds_read_b128 v[24:27], v2
	ds_read_b128 v[28:31], v2 offset:1024
	ds_read_b128 v[122:125], v2 offset:2048
	ds_read_b128 v[126:129], v2 offset:3072
	ds_read_b128 v[138:141], v3
	ds_read_b128 v[170:173], v3 offset:1024
	ds_read_b128 v[174:177], v3 offset:2048
	ds_read_b128 v[178:181], v3 offset:3072
	s_add_u32 s18, s42, 0x18000
	s_addc_u32 s19, s43, 0
	s_mov_b32 m0, s90
	v_lshl_add_u64 v[32:33], s[18:19], 0, v[136:137]
	ds_read_b128 v[182:185], v157 offset:32768
	ds_read_b128 v[190:193], v157 offset:33792
	ds_read_b128 v[194:197], v157 offset:34816
	ds_read_b128 v[198:201], v157 offset:35840
	ds_read_b128 v[202:205], v157 offset:36864
	ds_read_b128 v[206:209], v157 offset:37888
	ds_read_b128 v[210:213], v157 offset:38912
	ds_read_b128 v[220:223], v157 offset:39936
	global_load_lds_dwordx4 v[32:33], off
	v_lshl_add_u64 v[32:33], s[18:19], 0, v[132:133]
	s_mov_b32 m0, s91
	s_nop 0
	global_load_lds_dwordx4 v[32:33], off
	s_waitcnt vmcnt(8)
	s_waitcnt lgkmcnt(0)
	s_barrier
	s_setprio 1
	s_waitcnt lgkmcnt(0)
	v_mfma_f32_16x16x32_bf16 v[66:69], v[24:27], v[182:185], v[66:69]
	v_mfma_f32_16x16x32_bf16 v[70:73], v[122:125], v[182:185], v[70:73]
	v_mfma_f32_16x16x32_bf16 v[74:77], v[24:27], v[194:197], v[74:77]
	v_mfma_f32_16x16x32_bf16 v[78:81], v[122:125], v[194:197], v[78:81]
	v_mfma_f32_16x16x32_bf16 v[82:85], v[24:27], v[202:205], v[82:85]
	v_mfma_f32_16x16x32_bf16 v[86:89], v[122:125], v[202:205], v[86:89]
	v_mfma_f32_16x16x32_bf16 v[90:93], v[24:27], v[210:213], v[90:93]
	v_mfma_f32_16x16x32_bf16 v[98:101], v[122:125], v[210:213], v[98:101]
	v_mfma_f32_16x16x32_bf16 v[66:69], v[28:31], v[190:193], v[66:69]
	v_mfma_f32_16x16x32_bf16 v[70:73], v[126:129], v[190:193], v[70:73]
	v_mfma_f32_16x16x32_bf16 v[74:77], v[28:31], v[198:201], v[74:77]
	v_mfma_f32_16x16x32_bf16 v[78:81], v[126:129], v[198:201], v[78:81]
	v_mfma_f32_16x16x32_bf16 v[82:85], v[28:31], v[206:209], v[82:85]
	v_mfma_f32_16x16x32_bf16 v[86:89], v[126:129], v[206:209], v[86:89]
	v_mfma_f32_16x16x32_bf16 v[90:93], v[28:31], v[220:223], v[90:93]
	v_mfma_f32_16x16x32_bf16 v[98:101], v[126:129], v[220:223], v[98:101]
	v_mfma_f32_16x16x32_bf16 v[102:105], v[138:141], v[182:185], v[102:105]
	v_mfma_f32_16x16x32_bf16 v[32:35], v[174:177], v[182:185], v[34:37]
	v_mfma_f32_16x16x32_bf16 v[36:39], v[138:141], v[194:197], v[38:41]
	v_mfma_f32_16x16x32_bf16 v[40:43], v[174:177], v[194:197], v[42:45]
	v_mfma_f32_16x16x32_bf16 v[44:47], v[138:141], v[202:205], v[46:49]
	v_mfma_f32_16x16x32_bf16 v[48:51], v[174:177], v[202:205], v[50:53]
	v_mfma_f32_16x16x32_bf16 v[52:55], v[138:141], v[210:213], v[54:57]
	v_mfma_f32_16x16x32_bf16 v[56:59], v[174:177], v[210:213], v[58:61]
	v_mfma_f32_16x16x32_bf16 v[102:105], v[170:173], v[190:193], v[102:105]
	v_mfma_f32_16x16x32_bf16 v[32:35], v[178:181], v[190:193], v[32:35]
	v_mfma_f32_16x16x32_bf16 v[36:39], v[170:173], v[198:201], v[36:39]
	v_mfma_f32_16x16x32_bf16 v[40:43], v[178:181], v[198:201], v[40:43]
	v_mfma_f32_16x16x32_bf16 v[44:47], v[170:173], v[206:209], v[44:47]
	v_mfma_f32_16x16x32_bf16 v[52:55], v[170:173], v[220:223], v[52:55]
	v_mfma_f32_16x16x32_bf16 v[56:59], v[178:181], v[220:223], v[56:59]
	v_mfma_f32_16x16x32_bf16 v[48:51], v[178:181], v[206:209], v[48:51]
	s_setprio 0
	s_barrier
	s_add_i32 s18, s35, s75
	s_add_i32 s35, s18, 0x2000
	v_lshl_add_u64 v[60:61], s[84:85], 0, v[134:135]
	s_mov_b32 m0, s18
	s_add_u32 s42, s84, 0x18000
	ds_read_b128 v[182:185], v157 offset:49152
	ds_read_b128 v[190:193], v157 offset:50176
	ds_read_b128 v[194:197], v157 offset:51200
	ds_read_b128 v[198:201], v157 offset:52224
	ds_read_b128 v[202:205], v157 offset:53248
	ds_read_b128 v[206:209], v157 offset:54272
	ds_read_b128 v[210:213], v157 offset:55296
	ds_read_b128 v[220:223], v157 offset:56320
	global_load_lds_dwordx4 v[60:61], off
	v_lshl_add_u64 v[60:61], s[84:85], 0, v[130:131]
	s_mov_b32 m0, s35
	s_addc_u32 s43, s85, 0
	s_add_i32 s19, s44, s75
	global_load_lds_dwordx4 v[60:61], off
	v_lshl_add_u64 v[60:61], s[42:43], 0, v[134:135]
	s_mov_b32 m0, s19
	s_add_i32 s84, s19, 0x2000
	global_load_lds_dwordx4 v[60:61], off
	v_lshl_add_u64 v[60:61], s[42:43], 0, v[130:131]
	s_mov_b32 m0, s84
	s_nop 0
	global_load_lds_dwordx4 v[60:61], off
	v_lshl_add_u64 v[60:61], s[82:83], 0, v[136:137]
	s_mov_b32 m0, s93
	s_nop 0
	global_load_lds_dwordx4 v[60:61], off
	v_lshl_add_u64 v[60:61], s[82:83], 0, v[132:133]
	s_mov_b32 m0, s94
	s_nop 0
	global_load_lds_dwordx4 v[60:61], off
	s_waitcnt vmcnt(8)
	s_waitcnt lgkmcnt(0)
	s_barrier
	s_setprio 1
	s_waitcnt lgkmcnt(0)
	v_mfma_f32_16x16x32_bf16 v[4:7], v[24:27], v[210:213], v[4:7]
	v_mfma_f32_16x16x32_bf16 v[8:11], v[122:125], v[210:213], v[8:11]
	v_mfma_f32_16x16x32_bf16 v[142:145], v[24:27], v[182:185], v[142:145]
	v_mfma_f32_16x16x32_bf16 v[146:149], v[122:125], v[182:185], v[146:149]
	v_mfma_f32_16x16x32_bf16 v[150:153], v[24:27], v[194:197], v[150:153]
	v_mfma_f32_16x16x32_bf16 v[158:161], v[122:125], v[194:197], v[158:161]
	v_mfma_f32_16x16x32_bf16 v[162:165], v[24:27], v[202:205], v[162:165]
	v_mfma_f32_16x16x32_bf16 v[166:169], v[122:125], v[202:205], v[166:169]
	v_mfma_f32_16x16x32_bf16 v[4:7], v[28:31], v[220:223], v[4:7]
	v_mfma_f32_16x16x32_bf16 v[8:11], v[126:129], v[220:223], v[8:11]
	v_mfma_f32_16x16x32_bf16 v[142:145], v[28:31], v[190:193], v[142:145]
	v_mfma_f32_16x16x32_bf16 v[146:149], v[126:129], v[190:193], v[146:149]
	v_mfma_f32_16x16x32_bf16 v[150:153], v[28:31], v[198:201], v[150:153]
	v_mfma_f32_16x16x32_bf16 v[158:161], v[126:129], v[198:201], v[158:161]
	v_mfma_f32_16x16x32_bf16 v[162:165], v[28:31], v[206:209], v[162:165]
	v_mfma_f32_16x16x32_bf16 v[166:169], v[126:129], v[206:209], v[166:169]
	v_mfma_f32_16x16x32_bf16 v[12:15], v[138:141], v[182:185], v[12:15]
	v_mfma_f32_16x16x32_bf16 v[24:27], v[174:177], v[182:185], v[62:65]
	v_mfma_f32_16x16x32_bf16 v[28:31], v[138:141], v[194:197], v[106:109]
	v_mfma_f32_16x16x32_bf16 v[60:63], v[174:177], v[194:197], v[110:113]
	v_mfma_f32_16x16x32_bf16 v[106:109], v[138:141], v[202:205], v[114:117]
	v_mfma_f32_16x16x32_bf16 v[110:113], v[174:177], v[202:205], v[118:121]
	v_mfma_f32_16x16x32_bf16 v[16:19], v[138:141], v[210:213], v[16:19]
	v_mfma_f32_16x16x32_bf16 v[20:23], v[174:177], v[210:213], v[20:23]
	v_mfma_f32_16x16x32_bf16 v[12:15], v[170:173], v[190:193], v[12:15]
	v_mfma_f32_16x16x32_bf16 v[24:27], v[178:181], v[190:193], v[24:27]
	v_mfma_f32_16x16x32_bf16 v[28:31], v[170:173], v[198:201], v[28:31]
	v_mfma_f32_16x16x32_bf16 v[60:63], v[178:181], v[198:201], v[60:63]
	v_mfma_f32_16x16x32_bf16 v[106:109], v[170:173], v[206:209], v[106:109]
	v_mfma_f32_16x16x32_bf16 v[110:113], v[178:181], v[206:209], v[110:113]
	v_mfma_f32_16x16x32_bf16 v[16:19], v[170:173], v[220:223], v[16:19]
	v_mfma_f32_16x16x32_bf16 v[20:23], v[178:181], v[220:223], v[20:23]
	s_setprio 0
	s_barrier
	s_add_u32 s44, s78, 0x200
	s_addc_u32 s45, s79, 0
	s_add_u32 s46, s76, 0x200
	s_addc_u32 s47, s77, 0
	s_add_u32 s78, s78, 0x280
	s_addc_u32 s79, s79, 0
	s_add_u32 s76, s76, 0x280
	s_addc_u32 s77, s77, 0
	s_mov_b64 s[42:43], s[78:79]
	ds_read_b128 v[114:117], v0
	ds_read_b128 v[118:121], v0 offset:1024
	ds_read_b128 v[122:125], v0 offset:2048
	ds_read_b128 v[126:129], v0 offset:3072
	ds_read_b128 v[138:141], v1
	ds_read_b128 v[170:173], v1 offset:1024
	ds_read_b128 v[174:177], v1 offset:2048
	ds_read_b128 v[178:181], v1 offset:3072
	s_add_u32 s80, s80, 0x18000
	s_addc_u32 s81, s81, 0
	s_mov_b32 m0, s88
	v_lshl_add_u64 v[64:65], s[80:81], 0, v[136:137]
	ds_read_b128 v[182:185], v157
	ds_read_b128 v[190:193], v157 offset:1024
	ds_read_b128 v[194:197], v157 offset:2048
	ds_read_b128 v[198:201], v157 offset:3072
	ds_read_b128 v[202:205], v157 offset:4096
	ds_read_b128 v[206:209], v157 offset:5120
	ds_read_b128 v[210:213], v157 offset:6144
	ds_read_b128 v[220:223], v157 offset:7168
	global_load_lds_dwordx4 v[64:65], off
	v_lshl_add_u64 v[64:65], s[80:81], 0, v[132:133]
	s_mov_b32 m0, vcc_lo
	s_nop 0
	global_load_lds_dwordx4 v[64:65], off
	s_waitcnt vmcnt(8)
	s_waitcnt lgkmcnt(0)
	s_barrier
	s_setprio 1
	s_waitcnt lgkmcnt(0)
	v_mfma_f32_16x16x32_bf16 v[64:67], v[114:117], v[182:185], v[66:69]
	v_mfma_f32_16x16x32_bf16 v[68:71], v[122:125], v[182:185], v[70:73]
	v_mfma_f32_16x16x32_bf16 v[72:75], v[114:117], v[194:197], v[74:77]
	v_mfma_f32_16x16x32_bf16 v[76:79], v[122:125], v[194:197], v[78:81]
	v_mfma_f32_16x16x32_bf16 v[80:83], v[114:117], v[202:205], v[82:85]
	v_mfma_f32_16x16x32_bf16 v[84:87], v[122:125], v[202:205], v[86:89]
	v_mfma_f32_16x16x32_bf16 v[88:91], v[114:117], v[210:213], v[90:93]
	v_mfma_f32_16x16x32_bf16 v[92:95], v[122:125], v[210:213], v[98:101]
	v_mfma_f32_16x16x32_bf16 v[64:67], v[118:121], v[190:193], v[64:67]
	v_mfma_f32_16x16x32_bf16 v[68:71], v[126:129], v[190:193], v[68:71]
	v_mfma_f32_16x16x32_bf16 v[72:75], v[118:121], v[198:201], v[72:75]
	v_mfma_f32_16x16x32_bf16 v[76:79], v[126:129], v[198:201], v[76:79]
	v_mfma_f32_16x16x32_bf16 v[80:83], v[118:121], v[206:209], v[80:83]
	v_mfma_f32_16x16x32_bf16 v[84:87], v[126:129], v[206:209], v[84:87]
	v_mfma_f32_16x16x32_bf16 v[88:91], v[118:121], v[220:223], v[88:91]
	v_mfma_f32_16x16x32_bf16 v[92:95], v[126:129], v[220:223], v[92:95]
	v_mfma_f32_16x16x32_bf16 v[98:101], v[138:141], v[182:185], v[102:105]
	v_mfma_f32_16x16x32_bf16 v[32:35], v[174:177], v[182:185], v[32:35]
	v_mfma_f32_16x16x32_bf16 v[36:39], v[138:141], v[194:197], v[36:39]
	v_mfma_f32_16x16x32_bf16 v[40:43], v[174:177], v[194:197], v[40:43]
	v_mfma_f32_16x16x32_bf16 v[44:47], v[138:141], v[202:205], v[44:47]
	v_mfma_f32_16x16x32_bf16 v[52:55], v[138:141], v[210:213], v[52:55]
	v_mfma_f32_16x16x32_bf16 v[56:59], v[174:177], v[210:213], v[56:59]
	v_mfma_f32_16x16x32_bf16 v[98:101], v[170:173], v[190:193], v[98:101]
	v_mfma_f32_16x16x32_bf16 v[32:35], v[178:181], v[190:193], v[32:35]
	v_mfma_f32_16x16x32_bf16 v[36:39], v[170:173], v[198:201], v[36:39]
	v_mfma_f32_16x16x32_bf16 v[40:43], v[178:181], v[198:201], v[40:43]
	v_mfma_f32_16x16x32_bf16 v[44:47], v[170:173], v[206:209], v[44:47]
	v_mfma_f32_16x16x32_bf16 v[48:51], v[174:177], v[202:205], v[48:51]
	v_mfma_f32_16x16x32_bf16 v[52:55], v[170:173], v[220:223], v[52:55]
	v_mfma_f32_16x16x32_bf16 v[56:59], v[178:181], v[220:223], v[56:59]
	v_mfma_f32_16x16x32_bf16 v[48:51], v[178:181], v[206:209], v[48:51]
	s_setprio 0
	s_barrier
	s_mov_b32 m0, vcc_hi
	v_lshl_add_u64 v[186:187], s[46:47], 0, v[134:135]
	ds_read_b128 v[102:105], v157 offset:16384
	ds_read_b128 v[182:185], v157 offset:17408
	ds_read_b128 v[190:193], v157 offset:18432
	ds_read_b128 v[194:197], v157 offset:19456
	ds_read_b128 v[198:201], v157 offset:20480
	ds_read_b128 v[202:205], v157 offset:21504
	ds_read_b128 v[206:209], v157 offset:22528
	ds_read_b128 v[210:213], v157 offset:23552
	global_load_lds_dwordx4 v[186:187], off
	v_lshl_add_u64 v[186:187], s[46:47], 0, v[130:131]
	s_add_u32 s46, s46, 0x18000
	s_mov_b32 m0, s70
	s_addc_u32 s47, s47, 0
	global_load_lds_dwordx4 v[186:187], off
	v_lshl_add_u64 v[186:187], s[46:47], 0, v[134:135]
	s_mov_b32 m0, s22
	s_nop 0
	global_load_lds_dwordx4 v[186:187], off
	v_lshl_add_u64 v[186:187], s[46:47], 0, v[130:131]
	s_mov_b32 m0, s23
	s_nop 0
	global_load_lds_dwordx4 v[186:187], off
	v_lshl_add_u64 v[186:187], s[44:45], 0, v[136:137]
	s_mov_b32 m0, s49
	s_nop 0
	global_load_lds_dwordx4 v[186:187], off
	v_lshl_add_u64 v[186:187], s[44:45], 0, v[132:133]
	s_mov_b32 m0, s89
	s_nop 0
	global_load_lds_dwordx4 v[186:187], off
	s_waitcnt vmcnt(8)
	s_waitcnt lgkmcnt(0)
	s_barrier
	s_setprio 1
	s_waitcnt lgkmcnt(0)
	v_mfma_f32_16x16x32_bf16 v[4:7], v[114:117], v[206:209], v[4:7]
	v_mfma_f32_16x16x32_bf16 v[8:11], v[122:125], v[206:209], v[8:11]
	v_mfma_f32_16x16x32_bf16 v[142:145], v[114:117], v[102:105], v[142:145]
	v_mfma_f32_16x16x32_bf16 v[146:149], v[122:125], v[102:105], v[146:149]
	v_mfma_f32_16x16x32_bf16 v[150:153], v[114:117], v[190:193], v[150:153]
	v_mfma_f32_16x16x32_bf16 v[158:161], v[122:125], v[190:193], v[158:161]
	v_mfma_f32_16x16x32_bf16 v[162:165], v[114:117], v[198:201], v[162:165]
	v_mfma_f32_16x16x32_bf16 v[166:169], v[122:125], v[198:201], v[166:169]
	v_mfma_f32_16x16x32_bf16 v[4:7], v[118:121], v[210:213], v[4:7]
	v_mfma_f32_16x16x32_bf16 v[8:11], v[126:129], v[210:213], v[8:11]
	v_mfma_f32_16x16x32_bf16 v[142:145], v[118:121], v[182:185], v[142:145]
	v_mfma_f32_16x16x32_bf16 v[146:149], v[126:129], v[182:185], v[146:149]
	v_mfma_f32_16x16x32_bf16 v[150:153], v[118:121], v[194:197], v[150:153]
	v_mfma_f32_16x16x32_bf16 v[158:161], v[126:129], v[194:197], v[158:161]
	v_mfma_f32_16x16x32_bf16 v[162:165], v[118:121], v[202:205], v[162:165]
	v_mfma_f32_16x16x32_bf16 v[166:169], v[126:129], v[202:205], v[166:169]
	v_mfma_f32_16x16x32_bf16 v[12:15], v[138:141], v[102:105], v[12:15]
	v_mfma_f32_16x16x32_bf16 v[24:27], v[174:177], v[102:105], v[24:27]
	v_mfma_f32_16x16x32_bf16 v[28:31], v[138:141], v[190:193], v[28:31]
	v_mfma_f32_16x16x32_bf16 v[60:63], v[174:177], v[190:193], v[60:63]
	v_mfma_f32_16x16x32_bf16 v[102:105], v[138:141], v[198:201], v[106:109]
	v_mfma_f32_16x16x32_bf16 v[106:109], v[174:177], v[198:201], v[110:113]
	v_mfma_f32_16x16x32_bf16 v[16:19], v[138:141], v[206:209], v[16:19]
	v_mfma_f32_16x16x32_bf16 v[20:23], v[174:177], v[206:209], v[20:23]
	v_mfma_f32_16x16x32_bf16 v[12:15], v[170:173], v[182:185], v[12:15]
	v_mfma_f32_16x16x32_bf16 v[24:27], v[178:181], v[182:185], v[24:27]
	v_mfma_f32_16x16x32_bf16 v[28:31], v[170:173], v[194:197], v[28:31]
	v_mfma_f32_16x16x32_bf16 v[60:63], v[178:181], v[194:197], v[60:63]
	v_mfma_f32_16x16x32_bf16 v[102:105], v[170:173], v[202:205], v[102:105]
	v_mfma_f32_16x16x32_bf16 v[106:109], v[178:181], v[202:205], v[106:109]
	v_mfma_f32_16x16x32_bf16 v[16:19], v[170:173], v[210:213], v[16:19]
	v_mfma_f32_16x16x32_bf16 v[20:23], v[178:181], v[210:213], v[20:23]
	s_setprio 0
	s_barrier
	ds_read_b128 v[110:113], v2
	ds_read_b128 v[114:117], v2 offset:1024
	ds_read_b128 v[118:121], v2 offset:2048
	ds_read_b128 v[122:125], v2 offset:3072
	ds_read_b128 v[126:129], v3
	ds_read_b128 v[138:141], v3 offset:1024
	ds_read_b128 v[170:173], v3 offset:2048
	ds_read_b128 v[174:177], v3 offset:3072
	s_add_u32 s44, s44, 0x18000
	s_addc_u32 s45, s45, 0
	s_mov_b32 m0, s90
	v_lshl_add_u64 v[186:187], s[44:45], 0, v[136:137]
	ds_read_b128 v[178:181], v157 offset:32768
	ds_read_b128 v[182:185], v157 offset:33792
	ds_read_b128 v[190:193], v157 offset:34816
	ds_read_b128 v[194:197], v157 offset:35840
	ds_read_b128 v[198:201], v157 offset:36864
	ds_read_b128 v[202:205], v157 offset:37888
	ds_read_b128 v[206:209], v157 offset:38912
	ds_read_b128 v[210:213], v157 offset:39936
	global_load_lds_dwordx4 v[186:187], off
	v_lshl_add_u64 v[186:187], s[44:45], 0, v[132:133]
	s_mov_b32 m0, s91
	s_nop 0
	global_load_lds_dwordx4 v[186:187], off
	s_waitcnt vmcnt(8)
	s_waitcnt lgkmcnt(0)
	s_barrier
	s_setprio 1
	s_waitcnt lgkmcnt(0)
	v_mfma_f32_16x16x32_bf16 v[64:67], v[110:113], v[178:181], v[64:67]
	v_mfma_f32_16x16x32_bf16 v[68:71], v[118:121], v[178:181], v[68:71]
	v_mfma_f32_16x16x32_bf16 v[72:75], v[110:113], v[190:193], v[72:75]
	v_mfma_f32_16x16x32_bf16 v[76:79], v[118:121], v[190:193], v[76:79]
	v_mfma_f32_16x16x32_bf16 v[80:83], v[110:113], v[198:201], v[80:83]
	v_mfma_f32_16x16x32_bf16 v[84:87], v[118:121], v[198:201], v[84:87]
	v_mfma_f32_16x16x32_bf16 v[88:91], v[110:113], v[206:209], v[88:91]
	v_mfma_f32_16x16x32_bf16 v[92:95], v[118:121], v[206:209], v[92:95]
	v_mfma_f32_16x16x32_bf16 v[64:67], v[114:117], v[182:185], v[64:67]
	v_mfma_f32_16x16x32_bf16 v[68:71], v[122:125], v[182:185], v[68:71]
	v_mfma_f32_16x16x32_bf16 v[72:75], v[114:117], v[194:197], v[72:75]
	v_mfma_f32_16x16x32_bf16 v[76:79], v[122:125], v[194:197], v[76:79]
	v_mfma_f32_16x16x32_bf16 v[80:83], v[114:117], v[202:205], v[80:83]
	v_mfma_f32_16x16x32_bf16 v[84:87], v[122:125], v[202:205], v[84:87]
	v_mfma_f32_16x16x32_bf16 v[88:91], v[114:117], v[210:213], v[88:91]
	v_mfma_f32_16x16x32_bf16 v[92:95], v[122:125], v[210:213], v[92:95]
	v_mfma_f32_16x16x32_bf16 v[98:101], v[126:129], v[178:181], v[98:101]
	v_mfma_f32_16x16x32_bf16 v[32:35], v[170:173], v[178:181], v[32:35]
	v_mfma_f32_16x16x32_bf16 v[36:39], v[126:129], v[190:193], v[36:39]
	v_mfma_f32_16x16x32_bf16 v[40:43], v[170:173], v[190:193], v[40:43]
	v_mfma_f32_16x16x32_bf16 v[44:47], v[126:129], v[198:201], v[44:47]
	v_mfma_f32_16x16x32_bf16 v[52:55], v[126:129], v[206:209], v[52:55]
	v_mfma_f32_16x16x32_bf16 v[56:59], v[170:173], v[206:209], v[56:59]
	v_mfma_f32_16x16x32_bf16 v[98:101], v[138:141], v[182:185], v[98:101]
	v_mfma_f32_16x16x32_bf16 v[32:35], v[174:177], v[182:185], v[32:35]
	v_mfma_f32_16x16x32_bf16 v[36:39], v[138:141], v[194:197], v[36:39]
	v_mfma_f32_16x16x32_bf16 v[40:43], v[174:177], v[194:197], v[40:43]
	v_mfma_f32_16x16x32_bf16 v[44:47], v[138:141], v[202:205], v[44:47]
	v_mfma_f32_16x16x32_bf16 v[48:51], v[170:173], v[198:201], v[48:51]
	v_mfma_f32_16x16x32_bf16 v[52:55], v[138:141], v[210:213], v[52:55]
	v_mfma_f32_16x16x32_bf16 v[56:59], v[174:177], v[210:213], v[56:59]
	v_mfma_f32_16x16x32_bf16 v[48:51], v[174:177], v[202:205], v[48:51]
	s_setprio 0
	s_barrier
	s_mov_b32 m0, s18
	v_lshl_add_u64 v[186:187], s[76:77], 0, v[134:135]
	s_add_u32 s44, s76, 0x18000
	ds_read_b128 v[178:181], v157 offset:49152
	ds_read_b128 v[182:185], v157 offset:50176
	ds_read_b128 v[190:193], v157 offset:51200
	ds_read_b128 v[194:197], v157 offset:52224
	ds_read_b128 v[198:201], v157 offset:53248
	ds_read_b128 v[202:205], v157 offset:54272
	ds_read_b128 v[206:209], v157 offset:55296
	ds_read_b128 v[210:213], v157 offset:56320
	global_load_lds_dwordx4 v[186:187], off
	v_lshl_add_u64 v[186:187], s[76:77], 0, v[130:131]
	s_mov_b32 m0, s35
	s_addc_u32 s45, s77, 0
	global_load_lds_dwordx4 v[186:187], off
	v_lshl_add_u64 v[186:187], s[44:45], 0, v[134:135]
	s_mov_b32 m0, s19
	s_nop 0
	global_load_lds_dwordx4 v[186:187], off
	v_lshl_add_u64 v[186:187], s[44:45], 0, v[130:131]
	s_mov_b32 m0, s84
	s_nop 0
	global_load_lds_dwordx4 v[186:187], off
	v_lshl_add_u64 v[186:187], s[42:43], 0, v[136:137]
	s_mov_b32 m0, s93
	s_nop 0
	global_load_lds_dwordx4 v[186:187], off
	v_lshl_add_u64 v[186:187], s[42:43], 0, v[132:133]
	s_mov_b32 m0, s94
	s_nop 0
	global_load_lds_dwordx4 v[186:187], off
	s_waitcnt vmcnt(8)
	s_waitcnt lgkmcnt(0)
	s_barrier
	s_setprio 1
	s_waitcnt lgkmcnt(0)
	v_mfma_f32_16x16x32_bf16 v[4:7], v[110:113], v[206:209], v[4:7]
	v_mfma_f32_16x16x32_bf16 v[8:11], v[118:121], v[206:209], v[8:11]
	v_mfma_f32_16x16x32_bf16 v[142:145], v[110:113], v[178:181], v[142:145]
	v_mfma_f32_16x16x32_bf16 v[146:149], v[118:121], v[178:181], v[146:149]
	v_mfma_f32_16x16x32_bf16 v[150:153], v[110:113], v[190:193], v[150:153]
	v_mfma_f32_16x16x32_bf16 v[158:161], v[118:121], v[190:193], v[158:161]
	v_mfma_f32_16x16x32_bf16 v[162:165], v[110:113], v[198:201], v[162:165]
	v_mfma_f32_16x16x32_bf16 v[166:169], v[118:121], v[198:201], v[166:169]
	v_mfma_f32_16x16x32_bf16 v[4:7], v[114:117], v[210:213], v[4:7]
	v_mfma_f32_16x16x32_bf16 v[8:11], v[122:125], v[210:213], v[8:11]
	v_mfma_f32_16x16x32_bf16 v[142:145], v[114:117], v[182:185], v[142:145]
	v_mfma_f32_16x16x32_bf16 v[146:149], v[122:125], v[182:185], v[146:149]
	v_mfma_f32_16x16x32_bf16 v[150:153], v[114:117], v[194:197], v[150:153]
	v_mfma_f32_16x16x32_bf16 v[158:161], v[122:125], v[194:197], v[158:161]
	v_mfma_f32_16x16x32_bf16 v[162:165], v[114:117], v[202:205], v[162:165]
	v_mfma_f32_16x16x32_bf16 v[166:169], v[122:125], v[202:205], v[166:169]
	v_mfma_f32_16x16x32_bf16 v[12:15], v[126:129], v[178:181], v[12:15]
	v_mfma_f32_16x16x32_bf16 v[24:27], v[170:173], v[178:181], v[24:27]
	v_mfma_f32_16x16x32_bf16 v[28:31], v[126:129], v[190:193], v[28:31]
	v_mfma_f32_16x16x32_bf16 v[60:63], v[170:173], v[190:193], v[60:63]
	v_mfma_f32_16x16x32_bf16 v[102:105], v[126:129], v[198:201], v[102:105]
	v_mfma_f32_16x16x32_bf16 v[106:109], v[170:173], v[198:201], v[106:109]
	v_mfma_f32_16x16x32_bf16 v[16:19], v[126:129], v[206:209], v[16:19]
	v_mfma_f32_16x16x32_bf16 v[20:23], v[170:173], v[206:209], v[20:23]
	v_mfma_f32_16x16x32_bf16 v[12:15], v[138:141], v[182:185], v[12:15]
	v_mfma_f32_16x16x32_bf16 v[24:27], v[174:177], v[182:185], v[24:27]
	v_mfma_f32_16x16x32_bf16 v[28:31], v[138:141], v[194:197], v[28:31]
	v_mfma_f32_16x16x32_bf16 v[60:63], v[174:177], v[194:197], v[60:63]
	v_mfma_f32_16x16x32_bf16 v[102:105], v[138:141], v[202:205], v[102:105]
	v_mfma_f32_16x16x32_bf16 v[106:109], v[174:177], v[202:205], v[106:109]
	v_mfma_f32_16x16x32_bf16 v[16:19], v[138:141], v[210:213], v[16:19]
	v_mfma_f32_16x16x32_bf16 v[20:23], v[174:177], v[210:213], v[20:23]
	s_setprio 0
	s_barrier
	s_add_u32 s76, s38, 0x80
	s_addc_u32 s77, s39, 0
	s_add_u32 s42, s68, 0x80
	s_addc_u32 s43, s69, 0
	ds_read_b128 v[110:113], v0
	ds_read_b128 v[114:117], v0 offset:1024
	ds_read_b128 v[118:121], v0 offset:2048
	ds_read_b128 v[122:125], v0 offset:3072
	ds_read_b128 v[126:129], v1
	ds_read_b128 v[138:141], v1 offset:1024
	ds_read_b128 v[170:173], v1 offset:2048
	ds_read_b128 v[174:177], v1 offset:3072
	s_add_u32 s44, s78, 0x18000
	s_addc_u32 s45, s79, 0
	s_mov_b32 m0, s88
	v_lshl_add_u64 v[0:1], s[44:45], 0, v[136:137]
	ds_read_b128 v[178:181], v157
	ds_read_b128 v[182:185], v157 offset:1024
	ds_read_b128 v[190:193], v157 offset:2048
	ds_read_b128 v[194:197], v157 offset:3072
	ds_read_b128 v[198:201], v157 offset:4096
	ds_read_b128 v[202:205], v157 offset:5120
	ds_read_b128 v[206:209], v157 offset:6144
	ds_read_b128 v[210:213], v157 offset:7168
	global_load_lds_dwordx4 v[0:1], off
	v_lshl_add_u64 v[0:1], s[44:45], 0, v[132:133]
	s_mov_b32 m0, vcc_lo
	s_nop 0
	global_load_lds_dwordx4 v[0:1], off
	s_waitcnt vmcnt(8)
	s_waitcnt lgkmcnt(0)
	s_barrier
	s_setprio 1
	s_waitcnt lgkmcnt(0)
	v_mfma_f32_16x16x32_bf16 v[88:91], v[110:113], v[206:209], v[88:91]
	v_mfma_f32_16x16x32_bf16 v[64:67], v[110:113], v[178:181], v[64:67]
	v_mfma_f32_16x16x32_bf16 v[68:71], v[118:121], v[178:181], v[68:71]
	v_mfma_f32_16x16x32_bf16 v[72:75], v[110:113], v[190:193], v[72:75]
	v_mfma_f32_16x16x32_bf16 v[76:79], v[118:121], v[190:193], v[76:79]
	v_mfma_f32_16x16x32_bf16 v[80:83], v[110:113], v[198:201], v[80:83]
	v_mfma_f32_16x16x32_bf16 v[84:87], v[118:121], v[198:201], v[84:87]
	v_mfma_f32_16x16x32_bf16 v[220:223], v[114:117], v[210:213], v[88:91]
	v_mfma_f32_16x16x32_bf16 v[88:91], v[118:121], v[206:209], v[92:95]
	v_mfma_f32_16x16x32_bf16 v[64:67], v[114:117], v[182:185], v[64:67]
	v_mfma_f32_16x16x32_bf16 v[68:71], v[122:125], v[182:185], v[68:71]
	v_mfma_f32_16x16x32_bf16 v[72:75], v[114:117], v[194:197], v[72:75]
	v_mfma_f32_16x16x32_bf16 v[76:79], v[122:125], v[194:197], v[76:79]
	v_mfma_f32_16x16x32_bf16 v[80:83], v[114:117], v[202:205], v[80:83]
	v_mfma_f32_16x16x32_bf16 v[84:87], v[122:125], v[202:205], v[84:87]
	v_mfma_f32_16x16x32_bf16 v[92:95], v[122:125], v[210:213], v[88:91]
	v_mfma_f32_16x16x32_bf16 v[48:51], v[170:173], v[198:201], v[48:51]
	v_mfma_f32_16x16x32_bf16 v[88:91], v[126:129], v[178:181], v[98:101]
	v_mfma_f32_16x16x32_bf16 v[32:35], v[170:173], v[178:181], v[32:35]
	v_mfma_f32_16x16x32_bf16 v[36:39], v[126:129], v[190:193], v[36:39]
	v_mfma_f32_16x16x32_bf16 v[40:43], v[170:173], v[190:193], v[40:43]
	v_mfma_f32_16x16x32_bf16 v[44:47], v[126:129], v[198:201], v[44:47]
	v_mfma_f32_16x16x32_bf16 v[178:181], v[174:177], v[202:205], v[48:51]
	v_mfma_f32_16x16x32_bf16 v[48:51], v[126:129], v[206:209], v[52:55]
	v_mfma_f32_16x16x32_bf16 v[32:35], v[174:177], v[182:185], v[32:35]
	v_mfma_f32_16x16x32_bf16 v[36:39], v[138:141], v[194:197], v[36:39]
	v_mfma_f32_16x16x32_bf16 v[40:43], v[174:177], v[194:197], v[40:43]
	v_mfma_f32_16x16x32_bf16 v[44:47], v[138:141], v[202:205], v[44:47]
	v_mfma_f32_16x16x32_bf16 v[52:55], v[138:141], v[210:213], v[48:51]
	v_mfma_f32_16x16x32_bf16 v[48:51], v[170:173], v[206:209], v[56:59]
	v_mfma_f32_16x16x32_bf16 v[224:227], v[138:141], v[182:185], v[88:91]
	v_mfma_f32_16x16x32_bf16 v[182:185], v[174:177], v[210:213], v[48:51]
	s_setprio 0
	s_barrier
	s_mov_b32 m0, vcc_hi
	v_lshl_add_u64 v[0:1], s[68:69], 0, v[134:135]
	s_add_u32 s44, s68, 0x18000
	s_nop 0
	ds_read_b128 v[48:51], v157 offset:16384
	ds_read_b128 v[56:59], v157 offset:17408
	ds_read_b128 v[88:91], v157 offset:18432
	ds_read_b128 v[98:101], v157 offset:19456
	ds_read_b128 v[190:193], v157 offset:20480
	ds_read_b128 v[194:197], v157 offset:21504
	ds_read_b128 v[198:201], v157 offset:22528
	ds_read_b128 v[202:205], v157 offset:23552
	global_load_lds_dwordx4 v[0:1], off
	v_lshl_add_u64 v[0:1], s[68:69], 0, v[130:131]
	s_mov_b32 m0, s70
	s_addc_u32 s45, s69, 0
	global_load_lds_dwordx4 v[0:1], off
	v_lshl_add_u64 v[0:1], s[44:45], 0, v[134:135]
	s_mov_b32 m0, s22
	s_nop 0
	global_load_lds_dwordx4 v[0:1], off
	v_lshl_add_u64 v[0:1], s[44:45], 0, v[130:131]
	s_mov_b32 m0, s23
	s_nop 0
	global_load_lds_dwordx4 v[0:1], off
	v_lshl_add_u64 v[0:1], s[38:39], 0, v[136:137]
	s_mov_b32 m0, s49
	s_nop 0
	global_load_lds_dwordx4 v[0:1], off
	v_lshl_add_u64 v[0:1], s[38:39], 0, v[132:133]
	s_mov_b32 m0, s89
	s_nop 0
	global_load_lds_dwordx4 v[0:1], off
	s_waitcnt vmcnt(8)
	s_waitcnt lgkmcnt(0)
	s_barrier
	s_setprio 1
	s_waitcnt lgkmcnt(0)
	v_mfma_f32_16x16x32_bf16 v[4:7], v[110:113], v[198:201], v[4:7]
	v_mfma_f32_16x16x32_bf16 v[142:145], v[110:113], v[48:51], v[142:145]
	v_mfma_f32_16x16x32_bf16 v[146:149], v[118:121], v[48:51], v[146:149]
	v_mfma_f32_16x16x32_bf16 v[150:153], v[110:113], v[88:91], v[150:153]
	v_mfma_f32_16x16x32_bf16 v[158:161], v[118:121], v[88:91], v[158:161]
	v_mfma_f32_16x16x32_bf16 v[162:165], v[110:113], v[190:193], v[162:165]
	v_mfma_f32_16x16x32_bf16 v[166:169], v[118:121], v[190:193], v[166:169]
	v_mfma_f32_16x16x32_bf16 v[4:7], v[114:117], v[202:205], v[4:7]
	v_mfma_f32_16x16x32_bf16 v[8:11], v[118:121], v[198:201], v[8:11]
	v_mfma_f32_16x16x32_bf16 v[142:145], v[114:117], v[56:59], v[142:145]
	v_mfma_f32_16x16x32_bf16 v[146:149], v[122:125], v[56:59], v[146:149]
	v_mfma_f32_16x16x32_bf16 v[150:153], v[114:117], v[98:101], v[150:153]
	v_mfma_f32_16x16x32_bf16 v[158:161], v[122:125], v[98:101], v[158:161]
	v_mfma_f32_16x16x32_bf16 v[162:165], v[114:117], v[194:197], v[162:165]
	v_mfma_f32_16x16x32_bf16 v[166:169], v[122:125], v[194:197], v[166:169]
	v_mfma_f32_16x16x32_bf16 v[206:209], v[122:125], v[202:205], v[8:11]
	v_mfma_f32_16x16x32_bf16 v[8:11], v[126:129], v[48:51], v[12:15]
	v_mfma_f32_16x16x32_bf16 v[12:15], v[138:141], v[56:59], v[8:11]
	v_mfma_f32_16x16x32_bf16 v[8:11], v[170:173], v[48:51], v[24:27]
	v_mfma_f32_16x16x32_bf16 v[210:213], v[174:177], v[56:59], v[8:11]
	v_mfma_f32_16x16x32_bf16 v[8:11], v[126:129], v[88:91], v[28:31]
	v_mfma_f32_16x16x32_bf16 v[28:31], v[138:141], v[98:101], v[8:11]
	v_mfma_f32_16x16x32_bf16 v[8:11], v[170:173], v[88:91], v[60:63]
	v_mfma_f32_16x16x32_bf16 v[228:231], v[174:177], v[98:101], v[8:11]
	v_mfma_f32_16x16x32_bf16 v[8:11], v[126:129], v[190:193], v[102:105]
	v_mfma_f32_16x16x32_bf16 v[232:235], v[138:141], v[194:197], v[8:11]
	v_mfma_f32_16x16x32_bf16 v[8:11], v[170:173], v[190:193], v[106:109]
	v_mfma_f32_16x16x32_bf16 v[190:193], v[174:177], v[194:197], v[8:11]
	v_mfma_f32_16x16x32_bf16 v[8:11], v[126:129], v[198:201], v[16:19]
	v_mfma_f32_16x16x32_bf16 v[138:141], v[138:141], v[202:205], v[8:11]
	v_mfma_f32_16x16x32_bf16 v[8:11], v[170:173], v[198:201], v[20:23]
	v_mfma_f32_16x16x32_bf16 v[170:173], v[174:177], v[202:205], v[8:11]
	s_setprio 0
	s_barrier
	s_nop 4
	ds_read_b128 v[8:11], v2
	ds_read_b128 v[20:23], v2 offset:1024
	ds_read_b128 v[174:177], v2 offset:2048
	ds_read_b128 v[194:197], v2 offset:3072
	ds_read_b128 v[198:201], v3
	ds_read_b128 v[202:205], v3 offset:1024
	ds_read_b128 v[236:239], v3 offset:2048
	ds_read_b128 v[240:243], v3 offset:3072
	s_add_u32 s22, s38, 0x18000
	s_addc_u32 s23, s39, 0
	s_mov_b32 m0, s90
	v_lshl_add_u64 v[56:57], s[22:23], 0, v[136:137]
	ds_read_b128 v[0:3], v157 offset:32768
	ds_read_b128 v[16:19], v157 offset:33792
	ds_read_b128 v[24:27], v157 offset:34816
	ds_read_b128 v[60:63], v157 offset:35840
	ds_read_b128 v[244:247], v157 offset:36864
	ds_read_b128 v[248:251], v157 offset:37888
	ds_read_b128 v[186:189], v157 offset:38912
	ds_read_b128 v[48:51], v157 offset:39936
	global_load_lds_dwordx4 v[56:57], off
	v_lshl_add_u64 v[56:57], s[22:23], 0, v[132:133]
	s_mov_b32 m0, s91
	s_nop 0
	global_load_lds_dwordx4 v[56:57], off
	s_waitcnt vmcnt(8)
	s_waitcnt lgkmcnt(0)
	s_barrier
	s_setprio 1
	s_waitcnt lgkmcnt(0)
	v_mfma_f32_16x16x32_bf16 v[56:59], v[8:11], v[0:3], v[64:67]
	v_mfma_f32_16x16x32_bf16 v[122:125], v[20:23], v[16:19], v[56:59]
	v_mfma_f32_16x16x32_bf16 v[56:59], v[174:177], v[0:3], v[68:71]
	v_mfma_f32_16x16x32_bf16 v[114:117], v[194:197], v[16:19], v[56:59]
	v_mfma_f32_16x16x32_bf16 v[56:59], v[8:11], v[24:27], v[72:75]
	v_mfma_f32_16x16x32_bf16 v[106:109], v[20:23], v[60:63], v[56:59]
	v_mfma_f32_16x16x32_bf16 v[56:59], v[174:177], v[24:27], v[76:79]
	v_mfma_f32_16x16x32_bf16 v[98:101], v[194:197], v[60:63], v[56:59]
	v_mfma_f32_16x16x32_bf16 v[56:59], v[8:11], v[244:247], v[80:83]
	v_mfma_f32_16x16x32_bf16 v[88:91], v[20:23], v[248:251], v[56:59]
	v_mfma_f32_16x16x32_bf16 v[56:59], v[174:177], v[244:247], v[84:87]
	v_mfma_f32_16x16x32_bf16 v[80:83], v[194:197], v[248:251], v[56:59]
	v_mfma_f32_16x16x32_bf16 v[56:59], v[8:11], v[186:189], v[220:223]
	v_mfma_f32_16x16x32_bf16 v[64:67], v[174:177], v[186:189], v[92:95]
	v_mfma_f32_16x16x32_bf16 v[56:59], v[20:23], v[48:51], v[56:59]
	v_mfma_f32_16x16x32_bf16 v[220:223], v[194:197], v[48:51], v[64:67]
	v_mfma_f32_16x16x32_bf16 v[64:67], v[198:201], v[0:3], v[224:227]
	v_mfma_f32_16x16x32_bf16 v[0:3], v[236:239], v[0:3], v[32:35]
	v_mfma_f32_16x16x32_bf16 v[118:121], v[240:243], v[16:19], v[0:3]
	v_mfma_f32_16x16x32_bf16 v[0:3], v[198:201], v[24:27], v[36:39]
	v_mfma_f32_16x16x32_bf16 v[110:113], v[202:205], v[60:63], v[0:3]
	v_mfma_f32_16x16x32_bf16 v[0:3], v[236:239], v[24:27], v[40:43]
	v_mfma_f32_16x16x32_bf16 v[102:105], v[240:243], v[60:63], v[0:3]
	v_mfma_f32_16x16x32_bf16 v[0:3], v[198:201], v[244:247], v[44:47]
	v_mfma_f32_16x16x32_bf16 v[92:95], v[202:205], v[248:251], v[0:3]
	v_mfma_f32_16x16x32_bf16 v[0:3], v[236:239], v[244:247], v[178:181]
	v_mfma_f32_16x16x32_bf16 v[84:87], v[240:243], v[248:251], v[0:3]
	v_mfma_f32_16x16x32_bf16 v[0:3], v[198:201], v[186:189], v[52:55]
	v_mfma_f32_16x16x32_bf16 v[60:63], v[202:205], v[48:51], v[0:3]
	v_mfma_f32_16x16x32_bf16 v[0:3], v[236:239], v[186:189], v[182:185]
	v_mfma_f32_16x16x32_bf16 v[126:129], v[202:205], v[16:19], v[64:67]
	v_mfma_f32_16x16x32_bf16 v[52:55], v[240:243], v[48:51], v[0:3]
	s_setprio 0
	s_barrier
	s_mov_b32 m0, s18
	s_nop 2
	v_lshl_add_u64 v[0:1], s[42:43], 0, v[134:135]
	s_add_u32 s22, s42, 0x18000
	ds_read_b128 v[36:39], v157 offset:49152
	ds_read_b128 v[44:47], v157 offset:50176
	ds_read_b128 v[48:51], v157 offset:51200
	ds_read_b128 v[178:181], v157 offset:52224
	ds_read_b128 v[182:185], v157 offset:53248
	ds_read_b128 v[186:189], v157 offset:54272
	ds_read_b128 v[224:227], v157 offset:55296
	ds_read_b128 v[244:247], v157 offset:56320
	global_load_lds_dwordx4 v[0:1], off
	v_lshl_add_u64 v[0:1], s[42:43], 0, v[130:131]
	s_mov_b32 m0, s35
	s_addc_u32 s23, s43, 0
	global_load_lds_dwordx4 v[0:1], off
	v_lshl_add_u64 v[0:1], s[22:23], 0, v[134:135]
	s_mov_b32 m0, s19
	s_nop 0
	global_load_lds_dwordx4 v[0:1], off
	v_lshl_add_u64 v[0:1], s[22:23], 0, v[130:131]
	s_mov_b32 m0, s84
	s_nop 0
	global_load_lds_dwordx4 v[0:1], off
	v_lshl_add_u64 v[0:1], s[76:77], 0, v[136:137]
	s_mov_b32 m0, s93
	s_nop 0
	global_load_lds_dwordx4 v[0:1], off
	v_lshl_add_u64 v[0:1], s[76:77], 0, v[132:133]
	s_mov_b32 m0, s94
	s_nop 0
	global_load_lds_dwordx4 v[0:1], off
	s_waitcnt vmcnt(8)
	s_waitcnt lgkmcnt(0)
	s_barrier
	s_setprio 1
	s_waitcnt lgkmcnt(0)
	v_mfma_f32_16x16x32_bf16 v[0:3], v[8:11], v[36:39], v[142:145]
	v_mfma_f32_16x16x32_bf16 v[72:75], v[20:23], v[44:47], v[0:3]
	v_mfma_f32_16x16x32_bf16 v[0:3], v[174:177], v[36:39], v[146:149]
	v_mfma_f32_16x16x32_bf16 v[64:67], v[194:197], v[44:47], v[0:3]
	v_mfma_f32_16x16x32_bf16 v[0:3], v[8:11], v[48:51], v[150:153]
	v_mfma_f32_16x16x32_bf16 v[40:43], v[20:23], v[178:181], v[0:3]
	v_mfma_f32_16x16x32_bf16 v[0:3], v[174:177], v[48:51], v[158:161]
	v_mfma_f32_16x16x32_bf16 v[32:35], v[194:197], v[178:181], v[0:3]
	v_mfma_f32_16x16x32_bf16 v[0:3], v[8:11], v[182:185], v[162:165]
	v_mfma_f32_16x16x32_bf16 v[24:27], v[20:23], v[186:189], v[0:3]
	v_mfma_f32_16x16x32_bf16 v[0:3], v[174:177], v[182:185], v[166:169]
	v_mfma_f32_16x16x32_bf16 v[16:19], v[194:197], v[186:189], v[0:3]
	v_mfma_f32_16x16x32_bf16 v[0:3], v[8:11], v[224:227], v[4:7]
	v_mfma_f32_16x16x32_bf16 v[8:11], v[20:23], v[244:247], v[0:3]
	v_mfma_f32_16x16x32_bf16 v[0:3], v[174:177], v[224:227], v[206:209]
	v_mfma_f32_16x16x32_bf16 v[0:3], v[194:197], v[244:247], v[0:3]
	v_mfma_f32_16x16x32_bf16 v[4:7], v[198:201], v[36:39], v[12:15]
	v_mfma_f32_16x16x32_bf16 v[76:79], v[202:205], v[44:47], v[4:7]
	v_mfma_f32_16x16x32_bf16 v[4:7], v[236:239], v[36:39], v[210:213]
	v_mfma_f32_16x16x32_bf16 v[68:71], v[240:243], v[44:47], v[4:7]
	v_mfma_f32_16x16x32_bf16 v[4:7], v[198:201], v[48:51], v[28:31]
	v_mfma_f32_16x16x32_bf16 v[44:47], v[202:205], v[178:181], v[4:7]
	v_mfma_f32_16x16x32_bf16 v[4:7], v[236:239], v[48:51], v[228:231]
	v_mfma_f32_16x16x32_bf16 v[36:39], v[240:243], v[178:181], v[4:7]
	v_mfma_f32_16x16x32_bf16 v[4:7], v[198:201], v[182:185], v[232:235]
	v_mfma_f32_16x16x32_bf16 v[28:31], v[202:205], v[186:189], v[4:7]
	v_mfma_f32_16x16x32_bf16 v[4:7], v[236:239], v[182:185], v[190:193]
	v_mfma_f32_16x16x32_bf16 v[20:23], v[240:243], v[186:189], v[4:7]
	v_mfma_f32_16x16x32_bf16 v[4:7], v[198:201], v[224:227], v[138:141]
	v_mfma_f32_16x16x32_bf16 v[12:15], v[202:205], v[244:247], v[4:7]
	v_mfma_f32_16x16x32_bf16 v[4:7], v[236:239], v[224:227], v[170:173]
	v_mfma_f32_16x16x32_bf16 v[4:7], v[240:243], v[244:247], v[4:7]
	s_setprio 0
	s_barrier
	s_andn2_b64 vcc, exec, s[62:63]
	s_cbranch_vccnz .LBB0_385
	s_barrier

.LBB0_409:
	s_ashr_i32 s61, s60, 31
	s_lshl_b64 s[18:19], s[60:61], 17
	s_add_u32 s62, s47, s18
	s_addc_u32 s63, s71, s19
	s_and_b64 s[18:19], s[6:7], exec
	s_cselect_b32 s39, s63, s79
	s_cselect_b32 s38, s62, s78
	s_ashr_i32 s59, s58, 31
	s_lshl_b64 s[18:19], s[58:59], 17
	s_add_u32 s64, s14, s18
	s_addc_u32 s65, s16, s19
	s_and_b64 s[18:19], s[6:7], exec
	s_cselect_b32 s69, s65, s77
	s_cselect_b32 s68, s64, s76
	s_add_u32 s18, s78, 0x80
	s_addc_u32 s19, s79, 0
	s_add_u32 s42, s78, 0x100
	s_addc_u32 s43, s79, 0
	s_add_u32 s44, s76, 0x100
	s_addc_u32 s45, s77, 0
	s_add_u32 s78, s78, 0x180
	s_addc_u32 s79, s79, 0
	s_add_u32 s80, s76, 0x180
	s_addc_u32 s81, s77, 0
	s_add_i32 s49, 0, 0x10000
	s_add_i32 s20, 0, 0x14000
	s_mov_b64 s[76:77], s[78:79]
	v_add_u32_e32 v96, s49, v139
	v_add_u32_e32 v138, s20, v139
	ds_read_b128 v[0:3], v96
	ds_read_b128 v[4:7], v96 offset:1024
	ds_read_b128 v[8:11], v96 offset:2048
	ds_read_b128 v[12:15], v96 offset:3072
	ds_read_b128 v[16:19], v138
	ds_read_b128 v[20:23], v138 offset:1024
	ds_read_b128 v[24:27], v138 offset:2048
	ds_read_b128 v[28:31], v138 offset:3072
	s_add_u32 s18, s18, 0x10000
	s_addc_u32 s19, s19, 0
	s_add_i32 s59, s67, 0xc000
	v_lshl_add_u64 v[64:65], s[18:19], 0, v[130:131]
	s_mov_b32 m0, s59
	ds_read_b128 v[32:35], v141
	ds_read_b128 v[36:39], v141 offset:1024
	ds_read_b128 v[40:43], v141 offset:2048
	ds_read_b128 v[44:47], v141 offset:3072
	ds_read_b128 v[48:51], v141 offset:4096
	ds_read_b128 v[52:55], v141 offset:5120
	ds_read_b128 v[56:59], v141 offset:6144
	ds_read_b128 v[60:63], v141 offset:7168
	global_load_lds_dwordx4 v[64:65], off
	v_lshl_add_u64 v[64:65], s[18:19], 0, v[134:135]
	s_add_i32 s18, s67, 0xe000
	s_mov_b32 m0, s18
	s_nop 0
	global_load_lds_dwordx4 v[64:65], off
	s_waitcnt vmcnt(8)
	s_waitcnt lgkmcnt(0)
	s_barrier
	s_setprio 1
	s_waitcnt lgkmcnt(0)
	v_mfma_f32_16x16x32_bf16 v[64:67], v[0:3], v[32:35], 0
	v_mfma_f32_16x16x32_bf16 v[68:71], v[8:11], v[32:35], 0
	v_mfma_f32_16x16x32_bf16 v[72:75], v[0:3], v[40:43], 0
	v_mfma_f32_16x16x32_bf16 v[76:79], v[8:11], v[40:43], 0
	v_mfma_f32_16x16x32_bf16 v[80:83], v[0:3], v[48:51], 0
	v_mfma_f32_16x16x32_bf16 v[84:87], v[8:11], v[48:51], 0
	v_mfma_f32_16x16x32_bf16 v[88:91], v[0:3], v[56:59], 0
	v_mfma_f32_16x16x32_bf16 v[92:95], v[8:11], v[56:59], 0
	v_mfma_f32_16x16x32_bf16 v[64:67], v[4:7], v[36:39], v[64:67]
	v_mfma_f32_16x16x32_bf16 v[68:71], v[12:15], v[36:39], v[68:71]
	v_mfma_f32_16x16x32_bf16 v[72:75], v[4:7], v[44:47], v[72:75]
	v_mfma_f32_16x16x32_bf16 v[76:79], v[12:15], v[44:47], v[76:79]
	v_mfma_f32_16x16x32_bf16 v[80:83], v[4:7], v[52:55], v[80:83]
	v_mfma_f32_16x16x32_bf16 v[84:87], v[12:15], v[52:55], v[84:87]
	v_mfma_f32_16x16x32_bf16 v[88:91], v[4:7], v[60:63], v[88:91]
	v_mfma_f32_16x16x32_bf16 v[92:95], v[12:15], v[60:63], v[92:95]
	v_mfma_f32_16x16x32_bf16 v[98:101], v[16:19], v[32:35], 0
	v_mfma_f32_16x16x32_bf16 v[32:35], v[24:27], v[32:35], 0
	v_mfma_f32_16x16x32_bf16 v[98:101], v[20:23], v[36:39], v[98:101]
	v_mfma_f32_16x16x32_bf16 v[32:35], v[28:31], v[36:39], v[32:35]
	v_mfma_f32_16x16x32_bf16 v[36:39], v[16:19], v[40:43], 0
	v_mfma_f32_16x16x32_bf16 v[40:43], v[24:27], v[40:43], 0
	v_mfma_f32_16x16x32_bf16 v[36:39], v[20:23], v[44:47], v[36:39]
	v_mfma_f32_16x16x32_bf16 v[40:43], v[28:31], v[44:47], v[40:43]
	v_mfma_f32_16x16x32_bf16 v[44:47], v[16:19], v[48:51], 0
	v_mfma_f32_16x16x32_bf16 v[48:51], v[24:27], v[48:51], 0
	v_mfma_f32_16x16x32_bf16 v[44:47], v[20:23], v[52:55], v[44:47]
	v_mfma_f32_16x16x32_bf16 v[48:51], v[28:31], v[52:55], v[48:51]
	v_mfma_f32_16x16x32_bf16 v[52:55], v[16:19], v[56:59], 0
	v_mfma_f32_16x16x32_bf16 v[56:59], v[24:27], v[56:59], 0
	v_mfma_f32_16x16x32_bf16 v[52:55], v[20:23], v[60:63], v[52:55]
	v_mfma_f32_16x16x32_bf16 v[56:59], v[28:31], v[60:63], v[56:59]
	s_setprio 0
	s_barrier
	s_add_i32 s49, s49, s46
	v_lshl_add_u64 v[142:143], s[44:45], 0, v[132:133]
	s_mov_b32 m0, s49
	s_add_i32 s19, s49, 0x2000
	ds_read_b128 v[60:63], v141 offset:16384
	ds_read_b128 v[102:105], v141 offset:17408
	ds_read_b128 v[106:109], v141 offset:18432
	ds_read_b128 v[110:113], v141 offset:19456
	ds_read_b128 v[114:117], v141 offset:20480
	ds_read_b128 v[118:121], v141 offset:21504
	ds_read_b128 v[122:125], v141 offset:22528
	ds_read_b128 v[126:129], v141 offset:23552
	global_load_lds_dwordx4 v[142:143], off
	v_lshl_add_u64 v[142:143], s[44:45], 0, v[136:137]
	s_add_u32 s44, s44, 0x10000
	s_mov_b32 m0, s19
	s_addc_u32 s45, s45, 0
	s_add_i32 s20, s20, s46
	global_load_lds_dwordx4 v[142:143], off
	v_lshl_add_u64 v[142:143], s[44:45], 0, v[132:133]
	s_mov_b32 m0, s20
	s_add_i32 s33, s20, 0x2000
	global_load_lds_dwordx4 v[142:143], off
	v_lshl_add_u64 v[142:143], s[44:45], 0, v[136:137]
	s_mov_b32 m0, s33
	s_nop 0
	global_load_lds_dwordx4 v[142:143], off
	v_lshl_add_u64 v[142:143], s[42:43], 0, v[130:131]
	s_mov_b32 m0, s67
	s_nop 0
	global_load_lds_dwordx4 v[142:143], off
	v_lshl_add_u64 v[142:143], s[42:43], 0, v[134:135]
	s_mov_b32 m0, s72
	s_nop 0
	global_load_lds_dwordx4 v[142:143], off
	s_waitcnt vmcnt(8)
	s_waitcnt lgkmcnt(0)
	s_barrier
	s_setprio 1
	s_waitcnt lgkmcnt(0)
	v_mfma_f32_16x16x32_bf16 v[142:145], v[0:3], v[60:63], 0
	v_mfma_f32_16x16x32_bf16 v[150:153], v[0:3], v[106:109], 0
	v_mfma_f32_16x16x32_bf16 v[158:161], v[0:3], v[114:117], 0
	v_mfma_f32_16x16x32_bf16 v[0:3], v[0:3], v[122:125], 0
	v_mfma_f32_16x16x32_bf16 v[142:145], v[4:7], v[102:105], v[142:145]
	v_mfma_f32_16x16x32_bf16 v[150:153], v[4:7], v[110:113], v[150:153]
	v_mfma_f32_16x16x32_bf16 v[158:161], v[4:7], v[118:121], v[158:161]
	v_mfma_f32_16x16x32_bf16 v[0:3], v[4:7], v[126:129], v[0:3]
	v_mfma_f32_16x16x32_bf16 v[4:7], v[8:11], v[122:125], 0
	v_mfma_f32_16x16x32_bf16 v[146:149], v[8:11], v[60:63], 0
	v_mfma_f32_16x16x32_bf16 v[154:157], v[8:11], v[106:109], 0
	v_mfma_f32_16x16x32_bf16 v[162:165], v[8:11], v[114:117], 0
	v_mfma_f32_16x16x32_bf16 v[4:7], v[12:15], v[126:129], v[4:7]
	v_mfma_f32_16x16x32_bf16 v[146:149], v[12:15], v[102:105], v[146:149]
	v_mfma_f32_16x16x32_bf16 v[154:157], v[12:15], v[110:113], v[154:157]
	v_mfma_f32_16x16x32_bf16 v[162:165], v[12:15], v[118:121], v[162:165]
	v_mfma_f32_16x16x32_bf16 v[8:11], v[16:19], v[60:63], 0
	v_mfma_f32_16x16x32_bf16 v[12:15], v[24:27], v[60:63], 0
	v_mfma_f32_16x16x32_bf16 v[8:11], v[20:23], v[102:105], v[8:11]
	v_mfma_f32_16x16x32_bf16 v[12:15], v[28:31], v[102:105], v[12:15]
	v_mfma_f32_16x16x32_bf16 v[60:63], v[16:19], v[106:109], 0
	v_mfma_f32_16x16x32_bf16 v[102:105], v[24:27], v[106:109], 0
	v_mfma_f32_16x16x32_bf16 v[106:109], v[16:19], v[114:117], 0
	v_mfma_f32_16x16x32_bf16 v[16:19], v[16:19], v[122:125], 0
	v_mfma_f32_16x16x32_bf16 v[60:63], v[20:23], v[110:113], v[60:63]
	v_mfma_f32_16x16x32_bf16 v[102:105], v[28:31], v[110:113], v[102:105]
	v_mfma_f32_16x16x32_bf16 v[106:109], v[20:23], v[118:121], v[106:109]
	v_mfma_f32_16x16x32_bf16 v[110:113], v[24:27], v[114:117], 0
	v_mfma_f32_16x16x32_bf16 v[16:19], v[20:23], v[126:129], v[16:19]
	v_mfma_f32_16x16x32_bf16 v[20:23], v[24:27], v[122:125], 0
	v_mfma_f32_16x16x32_bf16 v[110:113], v[28:31], v[118:121], v[110:113]
	v_mfma_f32_16x16x32_bf16 v[20:23], v[28:31], v[126:129], v[20:23]
	s_setprio 0
	s_barrier
	s_add_i32 s61, 0, 0x18000
	s_add_i32 s44, 0, 0x1c000
	v_add_u32_e32 v140, s61, v139
	v_add_u32_e32 v236, s44, v139
	ds_read_b128 v[24:27], v140
	ds_read_b128 v[28:31], v140 offset:1024
	ds_read_b128 v[114:117], v140 offset:2048
	ds_read_b128 v[118:121], v140 offset:3072
	ds_read_b128 v[122:125], v236
	ds_read_b128 v[126:129], v236 offset:1024
	ds_read_b128 v[166:169], v236 offset:2048
	ds_read_b128 v[170:173], v236 offset:3072
	s_add_u32 s42, s42, 0x10000
	s_addc_u32 s43, s43, 0
	s_mov_b32 m0, s73
	v_lshl_add_u64 v[206:207], s[42:43], 0, v[130:131]
	ds_read_b128 v[174:177], v141 offset:32768
	ds_read_b128 v[178:181], v141 offset:33792
	ds_read_b128 v[182:185], v141 offset:34816
	ds_read_b128 v[186:189], v141 offset:35840
	ds_read_b128 v[190:193], v141 offset:36864
	ds_read_b128 v[194:197], v141 offset:37888
	ds_read_b128 v[198:201], v141 offset:38912
	ds_read_b128 v[202:205], v141 offset:39936
	global_load_lds_dwordx4 v[206:207], off
	v_lshl_add_u64 v[206:207], s[42:43], 0, v[134:135]
	s_mov_b32 m0, s74
	s_nop 0
	global_load_lds_dwordx4 v[206:207], off
	s_waitcnt vmcnt(8)
	s_waitcnt lgkmcnt(0)
	s_barrier
	s_setprio 1
	s_waitcnt lgkmcnt(0)
	v_mfma_f32_16x16x32_bf16 v[64:67], v[24:27], v[174:177], v[64:67]
	v_mfma_f32_16x16x32_bf16 v[68:71], v[114:117], v[174:177], v[68:71]
	v_mfma_f32_16x16x32_bf16 v[72:75], v[24:27], v[182:185], v[72:75]
	v_mfma_f32_16x16x32_bf16 v[76:79], v[114:117], v[182:185], v[76:79]
	v_mfma_f32_16x16x32_bf16 v[80:83], v[24:27], v[190:193], v[80:83]
	v_mfma_f32_16x16x32_bf16 v[84:87], v[114:117], v[190:193], v[84:87]
	v_mfma_f32_16x16x32_bf16 v[88:91], v[24:27], v[198:201], v[88:91]
	v_mfma_f32_16x16x32_bf16 v[92:95], v[114:117], v[198:201], v[92:95]
	v_mfma_f32_16x16x32_bf16 v[64:67], v[28:31], v[178:181], v[64:67]
	v_mfma_f32_16x16x32_bf16 v[68:71], v[118:121], v[178:181], v[68:71]
	v_mfma_f32_16x16x32_bf16 v[72:75], v[28:31], v[186:189], v[72:75]
	v_mfma_f32_16x16x32_bf16 v[76:79], v[118:121], v[186:189], v[76:79]
	v_mfma_f32_16x16x32_bf16 v[80:83], v[28:31], v[194:197], v[80:83]
	v_mfma_f32_16x16x32_bf16 v[84:87], v[118:121], v[194:197], v[84:87]
	v_mfma_f32_16x16x32_bf16 v[88:91], v[28:31], v[202:205], v[88:91]
	v_mfma_f32_16x16x32_bf16 v[92:95], v[118:121], v[202:205], v[92:95]
	v_mfma_f32_16x16x32_bf16 v[98:101], v[122:125], v[174:177], v[98:101]
	v_mfma_f32_16x16x32_bf16 v[32:35], v[166:169], v[174:177], v[32:35]
	v_mfma_f32_16x16x32_bf16 v[36:39], v[122:125], v[182:185], v[36:39]
	v_mfma_f32_16x16x32_bf16 v[40:43], v[166:169], v[182:185], v[40:43]
	v_mfma_f32_16x16x32_bf16 v[44:47], v[122:125], v[190:193], v[44:47]
	v_mfma_f32_16x16x32_bf16 v[48:51], v[166:169], v[190:193], v[48:51]
	v_mfma_f32_16x16x32_bf16 v[52:55], v[122:125], v[198:201], v[52:55]
	v_mfma_f32_16x16x32_bf16 v[56:59], v[166:169], v[198:201], v[56:59]
	v_mfma_f32_16x16x32_bf16 v[98:101], v[126:129], v[178:181], v[98:101]
	v_mfma_f32_16x16x32_bf16 v[32:35], v[170:173], v[178:181], v[32:35]
	v_mfma_f32_16x16x32_bf16 v[36:39], v[126:129], v[186:189], v[36:39]
	v_mfma_f32_16x16x32_bf16 v[40:43], v[170:173], v[186:189], v[40:43]
	v_mfma_f32_16x16x32_bf16 v[44:47], v[126:129], v[194:197], v[44:47]
	v_mfma_f32_16x16x32_bf16 v[48:51], v[170:173], v[194:197], v[48:51]
	v_mfma_f32_16x16x32_bf16 v[52:55], v[126:129], v[202:205], v[52:55]
	v_mfma_f32_16x16x32_bf16 v[56:59], v[170:173], v[202:205], v[56:59]
	s_setprio 0
	s_barrier
	s_add_i32 s61, s61, s46
	s_add_i32 s35, s61, 0x2000
	v_lshl_add_u64 v[206:207], s[80:81], 0, v[132:133]
	s_mov_b32 m0, s61
	s_add_u32 s42, s80, 0x10000
	ds_read_b128 v[174:177], v141 offset:49152
	ds_read_b128 v[178:181], v141 offset:50176
	ds_read_b128 v[182:185], v141 offset:51200
	ds_read_b128 v[186:189], v141 offset:52224
	ds_read_b128 v[190:193], v141 offset:53248
	ds_read_b128 v[194:197], v141 offset:54272
	ds_read_b128 v[198:201], v141 offset:55296
	ds_read_b128 v[202:205], v141 offset:56320
	global_load_lds_dwordx4 v[206:207], off
	v_lshl_add_u64 v[206:207], s[80:81], 0, v[136:137]
	s_mov_b32 m0, s35
	s_addc_u32 s43, s81, 0
	s_add_i32 s44, s44, s46
	global_load_lds_dwordx4 v[206:207], off
	v_lshl_add_u64 v[206:207], s[42:43], 0, v[132:133]
	s_mov_b32 m0, s44
	s_add_i32 s45, s44, 0x2000
	global_load_lds_dwordx4 v[206:207], off
	v_lshl_add_u64 v[206:207], s[42:43], 0, v[136:137]
	s_mov_b32 m0, s45
	s_nop 0
	global_load_lds_dwordx4 v[206:207], off
	v_lshl_add_u64 v[206:207], s[76:77], 0, v[130:131]
	s_mov_b32 m0, s85
	s_nop 0
	global_load_lds_dwordx4 v[206:207], off
	v_lshl_add_u64 v[206:207], s[76:77], 0, v[134:135]
	s_mov_b32 m0, s86
	s_nop 0
	global_load_lds_dwordx4 v[206:207], off
	s_waitcnt vmcnt(8)
	s_waitcnt lgkmcnt(0)
	s_barrier
	s_setprio 1
	s_waitcnt lgkmcnt(0)
	v_mfma_f32_16x16x32_bf16 v[0:3], v[24:27], v[198:201], v[0:3]
	v_mfma_f32_16x16x32_bf16 v[4:7], v[114:117], v[198:201], v[4:7]
	v_mfma_f32_16x16x32_bf16 v[142:145], v[24:27], v[174:177], v[142:145]
	v_mfma_f32_16x16x32_bf16 v[146:149], v[114:117], v[174:177], v[146:149]
	v_mfma_f32_16x16x32_bf16 v[150:153], v[24:27], v[182:185], v[150:153]
	v_mfma_f32_16x16x32_bf16 v[154:157], v[114:117], v[182:185], v[154:157]
	v_mfma_f32_16x16x32_bf16 v[158:161], v[24:27], v[190:193], v[158:161]
	v_mfma_f32_16x16x32_bf16 v[162:165], v[114:117], v[190:193], v[162:165]
	v_mfma_f32_16x16x32_bf16 v[0:3], v[28:31], v[202:205], v[0:3]
	v_mfma_f32_16x16x32_bf16 v[4:7], v[118:121], v[202:205], v[4:7]
	v_mfma_f32_16x16x32_bf16 v[142:145], v[28:31], v[178:181], v[142:145]
	v_mfma_f32_16x16x32_bf16 v[146:149], v[118:121], v[178:181], v[146:149]
	v_mfma_f32_16x16x32_bf16 v[150:153], v[28:31], v[186:189], v[150:153]
	v_mfma_f32_16x16x32_bf16 v[154:157], v[118:121], v[186:189], v[154:157]
	v_mfma_f32_16x16x32_bf16 v[158:161], v[28:31], v[194:197], v[158:161]
	v_mfma_f32_16x16x32_bf16 v[162:165], v[118:121], v[194:197], v[162:165]
	v_mfma_f32_16x16x32_bf16 v[8:11], v[122:125], v[174:177], v[8:11]
	v_mfma_f32_16x16x32_bf16 v[12:15], v[166:169], v[174:177], v[12:15]
	v_mfma_f32_16x16x32_bf16 v[24:27], v[122:125], v[182:185], v[60:63]
	v_mfma_f32_16x16x32_bf16 v[28:31], v[166:169], v[182:185], v[102:105]
	v_mfma_f32_16x16x32_bf16 v[60:63], v[122:125], v[190:193], v[106:109]
	v_mfma_f32_16x16x32_bf16 v[102:105], v[166:169], v[190:193], v[110:113]
	v_mfma_f32_16x16x32_bf16 v[16:19], v[122:125], v[198:201], v[16:19]
	v_mfma_f32_16x16x32_bf16 v[20:23], v[166:169], v[198:201], v[20:23]
	v_mfma_f32_16x16x32_bf16 v[8:11], v[126:129], v[178:181], v[8:11]
	v_mfma_f32_16x16x32_bf16 v[12:15], v[170:173], v[178:181], v[12:15]
	v_mfma_f32_16x16x32_bf16 v[24:27], v[126:129], v[186:189], v[24:27]
	v_mfma_f32_16x16x32_bf16 v[28:31], v[170:173], v[186:189], v[28:31]
	v_mfma_f32_16x16x32_bf16 v[60:63], v[126:129], v[194:197], v[60:63]
	v_mfma_f32_16x16x32_bf16 v[102:105], v[170:173], v[194:197], v[102:105]
	v_mfma_f32_16x16x32_bf16 v[16:19], v[126:129], v[202:205], v[16:19]
	v_mfma_f32_16x16x32_bf16 v[20:23], v[170:173], v[202:205], v[20:23]
	s_setprio 0
	s_barrier
	s_add_u32 s76, s38, 0x80
	s_addc_u32 s77, s39, 0
	s_add_u32 s42, s68, 0x80
	s_addc_u32 s43, s69, 0
	ds_read_b128 v[106:109], v96
	ds_read_b128 v[110:113], v96 offset:1024
	ds_read_b128 v[114:117], v96 offset:2048
	ds_read_b128 v[118:121], v96 offset:3072
	ds_read_b128 v[122:125], v138
	ds_read_b128 v[126:129], v138 offset:1024
	ds_read_b128 v[166:169], v138 offset:2048
	ds_read_b128 v[170:173], v138 offset:3072
	s_add_u32 s78, s78, 0x10000
	s_addc_u32 s79, s79, 0
	s_mov_b32 m0, s59
	v_lshl_add_u64 v[206:207], s[78:79], 0, v[130:131]
	ds_read_b128 v[174:177], v141
	ds_read_b128 v[178:181], v141 offset:1024
	ds_read_b128 v[182:185], v141 offset:2048
	ds_read_b128 v[186:189], v141 offset:3072
	ds_read_b128 v[190:193], v141 offset:4096
	ds_read_b128 v[194:197], v141 offset:5120
	ds_read_b128 v[198:201], v141 offset:6144
	ds_read_b128 v[202:205], v141 offset:7168
	global_load_lds_dwordx4 v[206:207], off
	v_lshl_add_u64 v[206:207], s[78:79], 0, v[134:135]
	s_mov_b32 m0, s18
	s_nop 0
	global_load_lds_dwordx4 v[206:207], off
	s_waitcnt vmcnt(8)
	s_waitcnt lgkmcnt(0)
	s_barrier
	s_setprio 1
	s_waitcnt lgkmcnt(0)
	v_mfma_f32_16x16x32_bf16 v[88:91], v[106:109], v[198:201], v[88:91]
	v_mfma_f32_16x16x32_bf16 v[64:67], v[106:109], v[174:177], v[64:67]
	v_mfma_f32_16x16x32_bf16 v[68:71], v[114:117], v[174:177], v[68:71]
	v_mfma_f32_16x16x32_bf16 v[72:75], v[106:109], v[182:185], v[72:75]
	v_mfma_f32_16x16x32_bf16 v[76:79], v[114:117], v[182:185], v[76:79]
	v_mfma_f32_16x16x32_bf16 v[80:83], v[106:109], v[190:193], v[80:83]
	v_mfma_f32_16x16x32_bf16 v[84:87], v[114:117], v[190:193], v[84:87]
	v_mfma_f32_16x16x32_bf16 v[206:209], v[110:113], v[202:205], v[88:91]
	v_mfma_f32_16x16x32_bf16 v[88:91], v[114:117], v[198:201], v[92:95]
	v_mfma_f32_16x16x32_bf16 v[64:67], v[110:113], v[178:181], v[64:67]
	v_mfma_f32_16x16x32_bf16 v[68:71], v[118:121], v[178:181], v[68:71]
	v_mfma_f32_16x16x32_bf16 v[72:75], v[110:113], v[186:189], v[72:75]
	v_mfma_f32_16x16x32_bf16 v[76:79], v[118:121], v[186:189], v[76:79]
	v_mfma_f32_16x16x32_bf16 v[80:83], v[110:113], v[194:197], v[80:83]
	v_mfma_f32_16x16x32_bf16 v[84:87], v[118:121], v[194:197], v[84:87]
	v_mfma_f32_16x16x32_bf16 v[92:95], v[118:121], v[202:205], v[88:91]
	v_mfma_f32_16x16x32_bf16 v[44:47], v[122:125], v[190:193], v[44:47]
	v_mfma_f32_16x16x32_bf16 v[88:91], v[122:125], v[174:177], v[98:101]
	v_mfma_f32_16x16x32_bf16 v[32:35], v[166:169], v[174:177], v[32:35]
	v_mfma_f32_16x16x32_bf16 v[174:177], v[126:129], v[194:197], v[44:47]
	v_mfma_f32_16x16x32_bf16 v[44:47], v[166:169], v[190:193], v[48:51]
	v_mfma_f32_16x16x32_bf16 v[36:39], v[122:125], v[182:185], v[36:39]
	v_mfma_f32_16x16x32_bf16 v[40:43], v[166:169], v[182:185], v[40:43]
	v_mfma_f32_16x16x32_bf16 v[48:51], v[170:173], v[194:197], v[44:47]
	v_mfma_f32_16x16x32_bf16 v[44:47], v[122:125], v[198:201], v[52:55]
	v_mfma_f32_16x16x32_bf16 v[210:213], v[126:129], v[178:181], v[88:91]
	v_mfma_f32_16x16x32_bf16 v[32:35], v[170:173], v[178:181], v[32:35]
	v_mfma_f32_16x16x32_bf16 v[36:39], v[126:129], v[186:189], v[36:39]
	v_mfma_f32_16x16x32_bf16 v[40:43], v[170:173], v[186:189], v[40:43]
	v_mfma_f32_16x16x32_bf16 v[178:181], v[126:129], v[202:205], v[44:47]
	v_mfma_f32_16x16x32_bf16 v[44:47], v[166:169], v[198:201], v[56:59]
	v_mfma_f32_16x16x32_bf16 v[182:185], v[170:173], v[202:205], v[44:47]
	s_setprio 0
	s_barrier
	s_mov_b32 m0, s49
	v_lshl_add_u64 v[198:199], s[68:69], 0, v[132:133]
	s_add_u32 s18, s68, 0x10000
	s_nop 1
	ds_read_b128 v[44:47], v141 offset:16384
	ds_read_b128 v[52:55], v141 offset:17408
	ds_read_b128 v[56:59], v141 offset:18432
	ds_read_b128 v[88:91], v141 offset:19456
	ds_read_b128 v[98:101], v141 offset:20480
	ds_read_b128 v[186:189], v141 offset:21504
	ds_read_b128 v[190:193], v141 offset:22528
	ds_read_b128 v[194:197], v141 offset:23552
	global_load_lds_dwordx4 v[198:199], off
	v_lshl_add_u64 v[198:199], s[68:69], 0, v[136:137]
	s_mov_b32 m0, s19
	s_addc_u32 s19, s69, 0
	global_load_lds_dwordx4 v[198:199], off
	v_lshl_add_u64 v[198:199], s[18:19], 0, v[132:133]
	s_mov_b32 m0, s20
	s_nop 0
	global_load_lds_dwordx4 v[198:199], off
	v_lshl_add_u64 v[198:199], s[18:19], 0, v[136:137]
	s_mov_b32 m0, s33
	s_nop 0
	global_load_lds_dwordx4 v[198:199], off
	v_lshl_add_u64 v[198:199], s[38:39], 0, v[130:131]
	s_mov_b32 m0, s67
	s_nop 0
	global_load_lds_dwordx4 v[198:199], off
	v_lshl_add_u64 v[198:199], s[38:39], 0, v[134:135]
	s_mov_b32 m0, s72
	s_nop 0
	global_load_lds_dwordx4 v[198:199], off
	s_waitcnt vmcnt(8)
	s_waitcnt lgkmcnt(0)
	s_barrier
	s_setprio 1
	s_waitcnt lgkmcnt(0)
	v_mfma_f32_16x16x32_bf16 v[0:3], v[106:109], v[190:193], v[0:3]
	v_mfma_f32_16x16x32_bf16 v[4:7], v[114:117], v[190:193], v[4:7]
	v_mfma_f32_16x16x32_bf16 v[142:145], v[106:109], v[44:47], v[142:145]
	v_mfma_f32_16x16x32_bf16 v[146:149], v[114:117], v[44:47], v[146:149]
	v_mfma_f32_16x16x32_bf16 v[150:153], v[106:109], v[56:59], v[150:153]
	v_mfma_f32_16x16x32_bf16 v[154:157], v[114:117], v[56:59], v[154:157]
	v_mfma_f32_16x16x32_bf16 v[158:161], v[106:109], v[98:101], v[158:161]
	v_mfma_f32_16x16x32_bf16 v[162:165], v[114:117], v[98:101], v[162:165]
	v_mfma_f32_16x16x32_bf16 v[0:3], v[110:113], v[194:197], v[0:3]
	v_mfma_f32_16x16x32_bf16 v[4:7], v[118:121], v[194:197], v[4:7]
	v_mfma_f32_16x16x32_bf16 v[142:145], v[110:113], v[52:55], v[142:145]
	v_mfma_f32_16x16x32_bf16 v[146:149], v[118:121], v[52:55], v[146:149]
	v_mfma_f32_16x16x32_bf16 v[150:153], v[110:113], v[88:91], v[150:153]
	v_mfma_f32_16x16x32_bf16 v[154:157], v[118:121], v[88:91], v[154:157]
	v_mfma_f32_16x16x32_bf16 v[158:161], v[110:113], v[186:189], v[158:161]
	v_mfma_f32_16x16x32_bf16 v[162:165], v[118:121], v[186:189], v[162:165]
	v_mfma_f32_16x16x32_bf16 v[28:31], v[166:169], v[56:59], v[28:31]
	v_mfma_f32_16x16x32_bf16 v[8:11], v[122:125], v[44:47], v[8:11]
	v_mfma_f32_16x16x32_bf16 v[12:15], v[166:169], v[44:47], v[12:15]
	v_mfma_f32_16x16x32_bf16 v[24:27], v[122:125], v[56:59], v[24:27]
	v_mfma_f32_16x16x32_bf16 v[198:201], v[170:173], v[88:91], v[28:31]
	v_mfma_f32_16x16x32_bf16 v[28:31], v[122:125], v[98:101], v[60:63]
	v_mfma_f32_16x16x32_bf16 v[16:19], v[122:125], v[190:193], v[16:19]
	v_mfma_f32_16x16x32_bf16 v[8:11], v[126:129], v[52:55], v[8:11]
	v_mfma_f32_16x16x32_bf16 v[12:15], v[170:173], v[52:55], v[12:15]
	v_mfma_f32_16x16x32_bf16 v[24:27], v[126:129], v[88:91], v[24:27]
	v_mfma_f32_16x16x32_bf16 v[202:205], v[126:129], v[186:189], v[28:31]
	v_mfma_f32_16x16x32_bf16 v[28:31], v[166:169], v[98:101], v[102:105]
	v_mfma_f32_16x16x32_bf16 v[16:19], v[126:129], v[194:197], v[16:19]
	v_mfma_f32_16x16x32_bf16 v[20:23], v[166:169], v[190:193], v[20:23]
	v_mfma_f32_16x16x32_bf16 v[186:189], v[170:173], v[186:189], v[28:31]
	v_mfma_f32_16x16x32_bf16 v[166:169], v[170:173], v[194:197], v[20:23]
	s_setprio 0
	s_barrier
	ds_read_b128 v[170:173], v140
	ds_read_b128 v[190:193], v140 offset:1024
	ds_read_b128 v[194:197], v140 offset:2048
	ds_read_b128 v[220:223], v140 offset:3072
	ds_read_b128 v[224:227], v236
	ds_read_b128 v[228:231], v236 offset:1024
	ds_read_b128 v[232:235], v236 offset:2048
	ds_read_b128 v[236:239], v236 offset:3072
	s_add_u32 s18, s38, 0x10000
	s_addc_u32 s19, s39, 0
	s_mov_b32 m0, s73
	v_lshl_add_u64 v[44:45], s[18:19], 0, v[130:131]
	ds_read_b128 v[20:23], v141 offset:32768
	ds_read_b128 v[28:31], v141 offset:33792
	ds_read_b128 v[52:55], v141 offset:34816
	ds_read_b128 v[102:105], v141 offset:35840
	ds_read_b128 v[110:113], v141 offset:36864
	ds_read_b128 v[118:121], v141 offset:37888
	ds_read_b128 v[240:243], v141 offset:38912
	ds_read_b128 v[244:247], v141 offset:39936
	global_load_lds_dwordx4 v[44:45], off
	v_lshl_add_u64 v[44:45], s[18:19], 0, v[134:135]
	s_mov_b32 m0, s74
	s_nop 0
	global_load_lds_dwordx4 v[44:45], off
	s_waitcnt vmcnt(8)
	s_waitcnt lgkmcnt(0)
	s_barrier
	s_setprio 1
	s_waitcnt lgkmcnt(0)
	v_mfma_f32_16x16x32_bf16 v[44:47], v[170:173], v[20:23], v[64:67]
	v_mfma_f32_16x16x32_bf16 v[126:129], v[190:193], v[28:31], v[44:47]
	v_mfma_f32_16x16x32_bf16 v[44:47], v[194:197], v[20:23], v[68:71]
	v_mfma_f32_16x16x32_bf16 v[122:125], v[220:223], v[28:31], v[44:47]
	v_mfma_f32_16x16x32_bf16 v[44:47], v[170:173], v[52:55], v[72:75]
	v_mfma_f32_16x16x32_bf16 v[114:117], v[190:193], v[102:105], v[44:47]
	v_mfma_f32_16x16x32_bf16 v[44:47], v[194:197], v[52:55], v[76:79]
	v_mfma_f32_16x16x32_bf16 v[106:109], v[220:223], v[102:105], v[44:47]
	v_mfma_f32_16x16x32_bf16 v[44:47], v[170:173], v[110:113], v[80:83]
	v_mfma_f32_16x16x32_bf16 v[98:101], v[190:193], v[118:121], v[44:47]
	v_mfma_f32_16x16x32_bf16 v[44:47], v[194:197], v[110:113], v[84:87]
	v_mfma_f32_16x16x32_bf16 v[88:91], v[220:223], v[118:121], v[44:47]
	v_mfma_f32_16x16x32_bf16 v[44:47], v[170:173], v[240:243], v[206:209]
	v_mfma_f32_16x16x32_bf16 v[80:83], v[190:193], v[244:247], v[44:47]
	v_mfma_f32_16x16x32_bf16 v[44:47], v[194:197], v[240:243], v[92:95]
	v_mfma_f32_16x16x32_bf16 v[72:75], v[220:223], v[244:247], v[44:47]
	v_mfma_f32_16x16x32_bf16 v[44:47], v[224:227], v[20:23], v[210:213]
	v_mfma_f32_16x16x32_bf16 v[20:23], v[232:235], v[20:23], v[32:35]
	v_mfma_f32_16x16x32_bf16 v[60:63], v[228:231], v[28:31], v[44:47]
	v_mfma_f32_16x16x32_bf16 v[44:47], v[236:239], v[28:31], v[20:23]
	v_mfma_f32_16x16x32_bf16 v[20:23], v[224:227], v[52:55], v[36:39]
	v_mfma_f32_16x16x32_bf16 v[56:59], v[228:231], v[102:105], v[20:23]
	v_mfma_f32_16x16x32_bf16 v[20:23], v[232:235], v[52:55], v[40:43]
	v_mfma_f32_16x16x32_bf16 v[36:39], v[236:239], v[102:105], v[20:23]
	v_mfma_f32_16x16x32_bf16 v[20:23], v[224:227], v[110:113], v[174:177]
	v_mfma_f32_16x16x32_bf16 v[52:55], v[228:231], v[118:121], v[20:23]
	v_mfma_f32_16x16x32_bf16 v[20:23], v[232:235], v[110:113], v[48:51]
	v_mfma_f32_16x16x32_bf16 v[28:31], v[236:239], v[118:121], v[20:23]
	v_mfma_f32_16x16x32_bf16 v[20:23], v[224:227], v[240:243], v[178:181]
	v_mfma_f32_16x16x32_bf16 v[48:51], v[228:231], v[244:247], v[20:23]
	v_mfma_f32_16x16x32_bf16 v[20:23], v[232:235], v[240:243], v[182:185]
	v_mfma_f32_16x16x32_bf16 v[20:23], v[236:239], v[244:247], v[20:23]
	s_setprio 0
	s_barrier
	s_mov_b32 m0, s61
	v_lshl_add_u64 v[40:41], s[42:43], 0, v[132:133]
	s_add_u32 s18, s42, 0x10000
	ds_read_b128 v[32:35], v141 offset:49152
	ds_read_b128 v[174:177], v141 offset:50176
	ds_read_b128 v[178:181], v141 offset:51200
	ds_read_b128 v[182:185], v141 offset:52224
	ds_read_b128 v[206:209], v141 offset:53248
	ds_read_b128 v[210:213], v141 offset:54272
	ds_read_b128 v[240:243], v141 offset:55296
	ds_read_b128 v[244:247], v141 offset:56320
	global_load_lds_dwordx4 v[40:41], off
	v_lshl_add_u64 v[40:41], s[42:43], 0, v[136:137]
	s_mov_b32 m0, s35
	s_addc_u32 s19, s43, 0
	global_load_lds_dwordx4 v[40:41], off
	v_lshl_add_u64 v[40:41], s[18:19], 0, v[132:133]
	s_mov_b32 m0, s44
	s_nop 0
	global_load_lds_dwordx4 v[40:41], off
	v_lshl_add_u64 v[40:41], s[18:19], 0, v[136:137]
	s_mov_b32 m0, s45
	s_nop 0
	global_load_lds_dwordx4 v[40:41], off
	v_lshl_add_u64 v[40:41], s[76:77], 0, v[130:131]
	s_mov_b32 m0, s85
	s_nop 0
	global_load_lds_dwordx4 v[40:41], off
	v_lshl_add_u64 v[40:41], s[76:77], 0, v[134:135]
	s_mov_b32 m0, s86
	s_nop 0
	global_load_lds_dwordx4 v[40:41], off
	s_waitcnt vmcnt(8)
	s_waitcnt lgkmcnt(0)
	s_barrier
	s_setprio 1
	s_waitcnt lgkmcnt(0)
	v_mfma_f32_16x16x32_bf16 v[40:43], v[170:173], v[32:35], v[142:145]
	v_mfma_f32_16x16x32_bf16 v[118:121], v[190:193], v[174:177], v[40:43]
	v_mfma_f32_16x16x32_bf16 v[40:43], v[194:197], v[32:35], v[146:149]
	v_mfma_f32_16x16x32_bf16 v[110:113], v[220:223], v[174:177], v[40:43]
	v_mfma_f32_16x16x32_bf16 v[40:43], v[170:173], v[178:181], v[150:153]
	v_mfma_f32_16x16x32_bf16 v[102:105], v[190:193], v[182:185], v[40:43]
	v_mfma_f32_16x16x32_bf16 v[40:43], v[194:197], v[178:181], v[154:157]
	v_mfma_f32_16x16x32_bf16 v[92:95], v[220:223], v[182:185], v[40:43]
	v_mfma_f32_16x16x32_bf16 v[40:43], v[170:173], v[206:209], v[158:161]
	v_mfma_f32_16x16x32_bf16 v[0:3], v[170:173], v[240:243], v[0:3]
	v_mfma_f32_16x16x32_bf16 v[84:87], v[190:193], v[210:213], v[40:43]
	v_mfma_f32_16x16x32_bf16 v[40:43], v[194:197], v[206:209], v[162:165]
	v_mfma_f32_16x16x32_bf16 v[68:71], v[190:193], v[244:247], v[0:3]
	v_mfma_f32_16x16x32_bf16 v[0:3], v[194:197], v[240:243], v[4:7]
	v_mfma_f32_16x16x32_bf16 v[76:79], v[220:223], v[210:213], v[40:43]
	v_mfma_f32_16x16x32_bf16 v[64:67], v[220:223], v[244:247], v[0:3]
	v_mfma_f32_16x16x32_bf16 v[0:3], v[224:227], v[32:35], v[8:11]
	v_mfma_f32_16x16x32_bf16 v[40:43], v[228:231], v[174:177], v[0:3]
	v_mfma_f32_16x16x32_bf16 v[0:3], v[232:235], v[32:35], v[12:15]
	v_mfma_f32_16x16x32_bf16 v[12:15], v[236:239], v[174:177], v[0:3]
	v_mfma_f32_16x16x32_bf16 v[0:3], v[224:227], v[178:181], v[24:27]
	v_mfma_f32_16x16x32_bf16 v[32:35], v[228:231], v[182:185], v[0:3]
	v_mfma_f32_16x16x32_bf16 v[0:3], v[232:235], v[178:181], v[198:201]
	v_mfma_f32_16x16x32_bf16 v[8:11], v[236:239], v[182:185], v[0:3]
	v_mfma_f32_16x16x32_bf16 v[0:3], v[224:227], v[206:209], v[202:205]
	v_mfma_f32_16x16x32_bf16 v[24:27], v[228:231], v[210:213], v[0:3]
	v_mfma_f32_16x16x32_bf16 v[0:3], v[232:235], v[206:209], v[186:189]
	v_mfma_f32_16x16x32_bf16 v[4:7], v[236:239], v[210:213], v[0:3]
	v_mfma_f32_16x16x32_bf16 v[0:3], v[224:227], v[240:243], v[16:19]
	v_mfma_f32_16x16x32_bf16 v[16:19], v[228:231], v[244:247], v[0:3]
	v_mfma_f32_16x16x32_bf16 v[0:3], v[232:235], v[240:243], v[166:169]
	v_mfma_f32_16x16x32_bf16 v[0:3], v[236:239], v[244:247], v[0:3]
	s_setprio 0
	s_barrier
	s_andn2_b64 vcc, exec, s[10:11]
	s_cbranch_vccnz .LBB0_411
	s_barrier

.LBB0_433:
	s_add_u32 s18, s10, 0x80
	s_addc_u32 s19, s11, 0
	s_add_u32 s10, s10, 0x100
	s_addc_u32 s11, s11, 0
	s_cmp_eq_u32 s92, 12
	s_cselect_b32 s42, s87, s10
	s_cselect_b32 s43, s9, s11
	s_cselect_b32 s45, s85, s94
	s_cselect_b32 s44, vcc_lo, vcc_hi
	s_add_u32 s38, s42, 0x80
	s_addc_u32 s39, s43, 0
	s_add_u32 s68, s44, 0x80
	s_addc_u32 s69, s45, 0
	s_add_i32 s35, 0, 0x10000
	s_add_i32 s49, 0, 0x14000
	v_add_u32_e32 v96, s35, v199
	v_add_u32_e32 v166, s49, v199
	ds_read_b128 v[138:141], v96
	ds_read_b128 v[142:145], v96 offset:1024
	ds_read_b128 v[146:149], v96 offset:2048
	ds_read_b128 v[150:153], v96 offset:3072
	s_waitcnt lgkmcnt(0)
	ds_read_b128 v[154:157], v166
	ds_read_b128 v[158:161], v166 offset:1024
	ds_read_b128 v[162:165], v166 offset:2048
	ds_read_b128 v[166:169], v166 offset:3072
	s_add_u32 s18, s18, 0x40000
	s_addc_u32 s19, s19, 0
	v_lshl_add_u64 v[186:187], s[18:19], 0, v[130:131]
	s_add_i32 m0, s73, 0xc000
	ds_read_b128 v[170:173], v200
	ds_read_b128 v[174:177], v200 offset:1024
	ds_read_b128 v[178:181], v200 offset:2048
	ds_read_b128 v[182:185], v200 offset:3072
	ds_read_b128 v[190:193], v200 offset:4096
	ds_read_b128 v[194:197], v200 offset:5120
	ds_read_b128 v[202:205], v200 offset:6144
	ds_read_b128 v[206:209], v200 offset:7168
	global_load_lds_dwordx4 v[186:187], off
	v_lshl_add_u64 v[186:187], s[18:19], 0, v[134:135]
	s_add_i32 m0, s73, 0xe000
	s_nop 0
	global_load_lds_dwordx4 v[186:187], off
	s_waitcnt vmcnt(8)
	s_waitcnt lgkmcnt(0)
	s_barrier
	s_setprio 1
	s_waitcnt lgkmcnt(0)
	v_mfma_f32_16x16x32_bf16 v[126:129], v[138:141], v[170:173], v[126:129]
	v_mfma_f32_16x16x32_bf16 v[122:125], v[146:149], v[170:173], v[122:125]
	v_mfma_f32_16x16x32_bf16 v[118:121], v[138:141], v[178:181], v[118:121]
	v_mfma_f32_16x16x32_bf16 v[110:113], v[146:149], v[178:181], v[110:113]
	v_mfma_f32_16x16x32_bf16 v[102:105], v[138:141], v[190:193], v[102:105]
	v_mfma_f32_16x16x32_bf16 v[92:95], v[146:149], v[190:193], v[92:95]
	v_mfma_f32_16x16x32_bf16 v[84:87], v[138:141], v[202:205], v[84:87]
	v_mfma_f32_16x16x32_bf16 v[76:79], v[146:149], v[202:205], v[76:79]
	v_mfma_f32_16x16x32_bf16 v[126:129], v[142:145], v[174:177], v[126:129]
	v_mfma_f32_16x16x32_bf16 v[122:125], v[150:153], v[174:177], v[122:125]
	v_mfma_f32_16x16x32_bf16 v[118:121], v[142:145], v[182:185], v[118:121]
	v_mfma_f32_16x16x32_bf16 v[110:113], v[150:153], v[182:185], v[110:113]
	v_mfma_f32_16x16x32_bf16 v[102:105], v[142:145], v[194:197], v[102:105]
	v_mfma_f32_16x16x32_bf16 v[92:95], v[150:153], v[194:197], v[92:95]
	v_mfma_f32_16x16x32_bf16 v[84:87], v[142:145], v[206:209], v[84:87]
	v_mfma_f32_16x16x32_bf16 v[76:79], v[150:153], v[206:209], v[76:79]
	v_mfma_f32_16x16x32_bf16 v[114:117], v[154:157], v[170:173], v[114:117]
	v_mfma_f32_16x16x32_bf16 v[106:109], v[162:165], v[170:173], v[106:109]
	v_mfma_f32_16x16x32_bf16 v[98:101], v[154:157], v[178:181], v[98:101]
	v_mfma_f32_16x16x32_bf16 v[88:91], v[162:165], v[178:181], v[88:91]
	v_mfma_f32_16x16x32_bf16 v[80:83], v[154:157], v[190:193], v[80:83]
	v_mfma_f32_16x16x32_bf16 v[72:75], v[162:165], v[190:193], v[72:75]
	v_mfma_f32_16x16x32_bf16 v[68:71], v[154:157], v[202:205], v[68:71]
	v_mfma_f32_16x16x32_bf16 v[64:67], v[162:165], v[202:205], v[64:67]
	v_mfma_f32_16x16x32_bf16 v[114:117], v[158:161], v[174:177], v[114:117]
	v_mfma_f32_16x16x32_bf16 v[106:109], v[166:169], v[174:177], v[106:109]
	v_mfma_f32_16x16x32_bf16 v[98:101], v[158:161], v[182:185], v[98:101]
	v_mfma_f32_16x16x32_bf16 v[88:91], v[166:169], v[182:185], v[88:91]
	v_mfma_f32_16x16x32_bf16 v[80:83], v[158:161], v[194:197], v[80:83]
	v_mfma_f32_16x16x32_bf16 v[72:75], v[166:169], v[194:197], v[72:75]
	v_mfma_f32_16x16x32_bf16 v[68:71], v[158:161], v[206:209], v[68:71]
	v_mfma_f32_16x16x32_bf16 v[64:67], v[166:169], v[206:209], v[64:67]
	s_setprio 0
	s_barrier
	s_add_i32 s18, s35, s72
	v_lshl_add_u64 v[186:187], s[44:45], 0, v[132:133]
	s_mov_b32 m0, s18
	ds_read_b128 v[170:173], v200 offset:16384
	ds_read_b128 v[174:177], v200 offset:17408
	ds_read_b128 v[178:181], v200 offset:18432
	ds_read_b128 v[182:185], v200 offset:19456
	ds_read_b128 v[190:193], v200 offset:20480
	ds_read_b128 v[194:197], v200 offset:21504
	ds_read_b128 v[202:205], v200 offset:22528
	ds_read_b128 v[206:209], v200 offset:23552
	global_load_lds_dwordx4 v[186:187], off
	s_add_i32 m0, s18, 0x2000
	s_add_u32 s18, s44, 0x40000
	v_lshl_add_u64 v[186:187], s[44:45], 0, v[136:137]
	s_addc_u32 s19, s45, 0
	s_add_i32 s35, s49, s72
	global_load_lds_dwordx4 v[186:187], off
	v_lshl_add_u64 v[186:187], s[18:19], 0, v[132:133]
	s_mov_b32 m0, s35
	s_nop 0
	global_load_lds_dwordx4 v[186:187], off
	v_lshl_add_u64 v[186:187], s[18:19], 0, v[136:137]
	s_add_i32 m0, s35, 0x2000
	s_nop 0
	global_load_lds_dwordx4 v[186:187], off
	v_lshl_add_u64 v[186:187], s[42:43], 0, v[130:131]
	s_mov_b32 m0, s73
	s_nop 0
	global_load_lds_dwordx4 v[186:187], off
	v_lshl_add_u64 v[186:187], s[42:43], 0, v[134:135]
	s_mov_b32 m0, s74
	s_nop 0
	global_load_lds_dwordx4 v[186:187], off
	s_waitcnt vmcnt(8)
	s_waitcnt lgkmcnt(0)
	s_barrier
	s_setprio 1
	s_waitcnt lgkmcnt(0)
	v_mfma_f32_16x16x32_bf16 v[60:63], v[138:141], v[170:173], v[60:63]
	v_mfma_f32_16x16x32_bf16 v[56:59], v[146:149], v[170:173], v[56:59]
	v_mfma_f32_16x16x32_bf16 v[52:55], v[138:141], v[178:181], v[52:55]
	v_mfma_f32_16x16x32_bf16 v[44:47], v[146:149], v[178:181], v[44:47]
	v_mfma_f32_16x16x32_bf16 v[36:39], v[138:141], v[190:193], v[36:39]
	v_mfma_f32_16x16x32_bf16 v[28:31], v[146:149], v[190:193], v[28:31]
	v_mfma_f32_16x16x32_bf16 v[20:23], v[138:141], v[202:205], v[20:23]
	v_mfma_f32_16x16x32_bf16 v[12:15], v[146:149], v[202:205], v[12:15]
	v_mfma_f32_16x16x32_bf16 v[60:63], v[142:145], v[174:177], v[60:63]
	v_mfma_f32_16x16x32_bf16 v[56:59], v[150:153], v[174:177], v[56:59]
	v_mfma_f32_16x16x32_bf16 v[52:55], v[142:145], v[182:185], v[52:55]
	v_mfma_f32_16x16x32_bf16 v[44:47], v[150:153], v[182:185], v[44:47]
	v_mfma_f32_16x16x32_bf16 v[36:39], v[142:145], v[194:197], v[36:39]
	v_mfma_f32_16x16x32_bf16 v[28:31], v[150:153], v[194:197], v[28:31]
	v_mfma_f32_16x16x32_bf16 v[20:23], v[142:145], v[206:209], v[20:23]
	v_mfma_f32_16x16x32_bf16 v[12:15], v[150:153], v[206:209], v[12:15]
	v_mfma_f32_16x16x32_bf16 v[48:51], v[154:157], v[170:173], v[48:51]
	v_mfma_f32_16x16x32_bf16 v[40:43], v[162:165], v[170:173], v[40:43]
	v_mfma_f32_16x16x32_bf16 v[32:35], v[154:157], v[178:181], v[32:35]
	v_mfma_f32_16x16x32_bf16 v[24:27], v[162:165], v[178:181], v[24:27]
	v_mfma_f32_16x16x32_bf16 v[16:19], v[154:157], v[190:193], v[16:19]
	v_mfma_f32_16x16x32_bf16 v[8:11], v[162:165], v[190:193], v[8:11]
	v_mfma_f32_16x16x32_bf16 v[4:7], v[154:157], v[202:205], v[4:7]
	v_mfma_f32_16x16x32_bf16 v[0:3], v[162:165], v[202:205], v[0:3]
	v_mfma_f32_16x16x32_bf16 v[48:51], v[158:161], v[174:177], v[48:51]
	v_mfma_f32_16x16x32_bf16 v[40:43], v[166:169], v[174:177], v[40:43]
	v_mfma_f32_16x16x32_bf16 v[32:35], v[158:161], v[182:185], v[32:35]
	v_mfma_f32_16x16x32_bf16 v[24:27], v[166:169], v[182:185], v[24:27]
	v_mfma_f32_16x16x32_bf16 v[16:19], v[158:161], v[194:197], v[16:19]
	v_mfma_f32_16x16x32_bf16 v[8:11], v[166:169], v[194:197], v[8:11]
	v_mfma_f32_16x16x32_bf16 v[4:7], v[158:161], v[206:209], v[4:7]
	v_mfma_f32_16x16x32_bf16 v[0:3], v[166:169], v[206:209], v[0:3]
	s_setprio 0
	s_barrier
	s_add_i32 s35, 0, 0x18000
	v_add_u32_e32 v96, s35, v199
	s_add_i32 s44, 0, 0x1c000
	ds_read_b128 v[138:141], v96
	ds_read_b128 v[142:145], v96 offset:1024
	ds_read_b128 v[146:149], v96 offset:2048
	ds_read_b128 v[150:153], v96 offset:3072
	v_add_u32_e32 v96, s44, v199
	ds_read_b128 v[154:157], v96
	ds_read_b128 v[158:161], v96 offset:1024
	ds_read_b128 v[162:165], v96 offset:2048
	ds_read_b128 v[166:169], v96 offset:3072
	s_add_u32 s18, s42, 0x40000
	s_addc_u32 s19, s43, 0
	s_mov_b32 m0, s75
	v_lshl_add_u64 v[186:187], s[18:19], 0, v[130:131]
	ds_read_b128 v[170:173], v200 offset:32768
	ds_read_b128 v[174:177], v200 offset:33792
	ds_read_b128 v[178:181], v200 offset:34816
	ds_read_b128 v[182:185], v200 offset:35840
	ds_read_b128 v[190:193], v200 offset:36864
	ds_read_b128 v[194:197], v200 offset:37888
	ds_read_b128 v[202:205], v200 offset:38912
	ds_read_b128 v[206:209], v200 offset:39936
	global_load_lds_dwordx4 v[186:187], off
	v_lshl_add_u64 v[186:187], s[18:19], 0, v[134:135]
	s_mov_b32 m0, s83
	s_nop 0
	global_load_lds_dwordx4 v[186:187], off
	s_waitcnt vmcnt(8)
	s_waitcnt lgkmcnt(0)
	s_barrier
	s_setprio 1
	s_waitcnt lgkmcnt(0)
	v_mfma_f32_16x16x32_bf16 v[126:129], v[138:141], v[170:173], v[126:129]
	v_mfma_f32_16x16x32_bf16 v[122:125], v[146:149], v[170:173], v[122:125]
	v_mfma_f32_16x16x32_bf16 v[118:121], v[138:141], v[178:181], v[118:121]
	v_mfma_f32_16x16x32_bf16 v[110:113], v[146:149], v[178:181], v[110:113]
	v_mfma_f32_16x16x32_bf16 v[102:105], v[138:141], v[190:193], v[102:105]
	v_mfma_f32_16x16x32_bf16 v[92:95], v[146:149], v[190:193], v[92:95]
	v_mfma_f32_16x16x32_bf16 v[84:87], v[138:141], v[202:205], v[84:87]
	v_mfma_f32_16x16x32_bf16 v[76:79], v[146:149], v[202:205], v[76:79]
	v_mfma_f32_16x16x32_bf16 v[126:129], v[142:145], v[174:177], v[126:129]
	v_mfma_f32_16x16x32_bf16 v[122:125], v[150:153], v[174:177], v[122:125]
	v_mfma_f32_16x16x32_bf16 v[118:121], v[142:145], v[182:185], v[118:121]
	v_mfma_f32_16x16x32_bf16 v[110:113], v[150:153], v[182:185], v[110:113]
	v_mfma_f32_16x16x32_bf16 v[102:105], v[142:145], v[194:197], v[102:105]
	v_mfma_f32_16x16x32_bf16 v[92:95], v[150:153], v[194:197], v[92:95]
	v_mfma_f32_16x16x32_bf16 v[84:87], v[142:145], v[206:209], v[84:87]
	v_mfma_f32_16x16x32_bf16 v[76:79], v[150:153], v[206:209], v[76:79]
	v_mfma_f32_16x16x32_bf16 v[114:117], v[154:157], v[170:173], v[114:117]
	v_mfma_f32_16x16x32_bf16 v[106:109], v[162:165], v[170:173], v[106:109]
	v_mfma_f32_16x16x32_bf16 v[98:101], v[154:157], v[178:181], v[98:101]
	v_mfma_f32_16x16x32_bf16 v[88:91], v[162:165], v[178:181], v[88:91]
	v_mfma_f32_16x16x32_bf16 v[80:83], v[154:157], v[190:193], v[80:83]
	v_mfma_f32_16x16x32_bf16 v[72:75], v[162:165], v[190:193], v[72:75]
	v_mfma_f32_16x16x32_bf16 v[68:71], v[154:157], v[202:205], v[68:71]
	v_mfma_f32_16x16x32_bf16 v[64:67], v[162:165], v[202:205], v[64:67]
	v_mfma_f32_16x16x32_bf16 v[114:117], v[158:161], v[174:177], v[114:117]
	v_mfma_f32_16x16x32_bf16 v[106:109], v[166:169], v[174:177], v[106:109]
	v_mfma_f32_16x16x32_bf16 v[98:101], v[158:161], v[182:185], v[98:101]
	v_mfma_f32_16x16x32_bf16 v[88:91], v[166:169], v[182:185], v[88:91]
	v_mfma_f32_16x16x32_bf16 v[80:83], v[158:161], v[194:197], v[80:83]
	v_mfma_f32_16x16x32_bf16 v[72:75], v[166:169], v[194:197], v[72:75]
	v_mfma_f32_16x16x32_bf16 v[68:71], v[158:161], v[206:209], v[68:71]
	v_mfma_f32_16x16x32_bf16 v[64:67], v[166:169], v[206:209], v[64:67]
	s_setprio 0
	s_barrier
	s_add_i32 s18, s35, s72
	v_lshl_add_u64 v[186:187], s[68:69], 0, v[132:133]
	s_mov_b32 m0, s18
	ds_read_b128 v[170:173], v200 offset:49152
	ds_read_b128 v[174:177], v200 offset:50176
	ds_read_b128 v[178:181], v200 offset:51200
	ds_read_b128 v[182:185], v200 offset:52224
	ds_read_b128 v[190:193], v200 offset:53248
	ds_read_b128 v[194:197], v200 offset:54272
	ds_read_b128 v[202:205], v200 offset:55296
	ds_read_b128 v[206:209], v200 offset:56320
	global_load_lds_dwordx4 v[186:187], off
	s_add_i32 m0, s18, 0x2000
	s_add_u32 s18, s68, 0x40000
	v_lshl_add_u64 v[186:187], s[68:69], 0, v[136:137]
	s_addc_u32 s19, s69, 0
	s_add_i32 s35, s44, s72
	global_load_lds_dwordx4 v[186:187], off
	v_lshl_add_u64 v[186:187], s[18:19], 0, v[132:133]
	s_mov_b32 m0, s35
	s_nop 0
	global_load_lds_dwordx4 v[186:187], off
	v_lshl_add_u64 v[186:187], s[18:19], 0, v[136:137]
	s_add_i32 m0, s35, 0x2000
	s_nop 0
	global_load_lds_dwordx4 v[186:187], off
	v_lshl_add_u64 v[186:187], s[38:39], 0, v[130:131]
	s_mov_b32 m0, s29
	s_nop 0
	global_load_lds_dwordx4 v[186:187], off
	v_lshl_add_u64 v[186:187], s[38:39], 0, v[134:135]
	s_mov_b32 m0, s16
	s_nop 0
	global_load_lds_dwordx4 v[186:187], off
	s_waitcnt vmcnt(8)
	s_waitcnt lgkmcnt(0)
	s_barrier
	s_setprio 1
	s_waitcnt lgkmcnt(0)
	v_mfma_f32_16x16x32_bf16 v[60:63], v[138:141], v[170:173], v[60:63]
	v_mfma_f32_16x16x32_bf16 v[56:59], v[146:149], v[170:173], v[56:59]
	v_mfma_f32_16x16x32_bf16 v[52:55], v[138:141], v[178:181], v[52:55]
	v_mfma_f32_16x16x32_bf16 v[44:47], v[146:149], v[178:181], v[44:47]
	v_mfma_f32_16x16x32_bf16 v[36:39], v[138:141], v[190:193], v[36:39]
	v_mfma_f32_16x16x32_bf16 v[28:31], v[146:149], v[190:193], v[28:31]
	v_mfma_f32_16x16x32_bf16 v[20:23], v[138:141], v[202:205], v[20:23]
	v_mfma_f32_16x16x32_bf16 v[12:15], v[146:149], v[202:205], v[12:15]
	v_mfma_f32_16x16x32_bf16 v[60:63], v[142:145], v[174:177], v[60:63]
	v_mfma_f32_16x16x32_bf16 v[56:59], v[150:153], v[174:177], v[56:59]
	v_mfma_f32_16x16x32_bf16 v[52:55], v[142:145], v[182:185], v[52:55]
	v_mfma_f32_16x16x32_bf16 v[44:47], v[150:153], v[182:185], v[44:47]
	v_mfma_f32_16x16x32_bf16 v[36:39], v[142:145], v[194:197], v[36:39]
	v_mfma_f32_16x16x32_bf16 v[28:31], v[150:153], v[194:197], v[28:31]
	v_mfma_f32_16x16x32_bf16 v[20:23], v[142:145], v[206:209], v[20:23]
	v_mfma_f32_16x16x32_bf16 v[12:15], v[150:153], v[206:209], v[12:15]
	v_mfma_f32_16x16x32_bf16 v[48:51], v[154:157], v[170:173], v[48:51]
	v_mfma_f32_16x16x32_bf16 v[40:43], v[162:165], v[170:173], v[40:43]
	v_mfma_f32_16x16x32_bf16 v[32:35], v[154:157], v[178:181], v[32:35]
	v_mfma_f32_16x16x32_bf16 v[24:27], v[162:165], v[178:181], v[24:27]
	v_mfma_f32_16x16x32_bf16 v[16:19], v[154:157], v[190:193], v[16:19]
	v_mfma_f32_16x16x32_bf16 v[8:11], v[162:165], v[190:193], v[8:11]
	v_mfma_f32_16x16x32_bf16 v[4:7], v[154:157], v[202:205], v[4:7]
	v_mfma_f32_16x16x32_bf16 v[0:3], v[162:165], v[202:205], v[0:3]
	v_mfma_f32_16x16x32_bf16 v[48:51], v[158:161], v[174:177], v[48:51]
	v_mfma_f32_16x16x32_bf16 v[40:43], v[166:169], v[174:177], v[40:43]
	v_mfma_f32_16x16x32_bf16 v[32:35], v[158:161], v[182:185], v[32:35]
	v_mfma_f32_16x16x32_bf16 v[24:27], v[166:169], v[182:185], v[24:27]
	v_mfma_f32_16x16x32_bf16 v[16:19], v[158:161], v[194:197], v[16:19]
	v_mfma_f32_16x16x32_bf16 v[8:11], v[166:169], v[194:197], v[8:11]
	v_mfma_f32_16x16x32_bf16 v[4:7], v[158:161], v[206:209], v[4:7]
	v_mfma_f32_16x16x32_bf16 v[0:3], v[166:169], v[206:209], v[0:3]
	s_setprio 0
	s_barrier
	s_add_i32 s92, s92, 2
	s_add_u32 vcc_hi, vcc_hi, 0x100
	s_addc_u32 s94, s94, 0
	s_cmp_gt_u32 s92, 13
	s_cbranch_scc0 .LBB0_433
	s_and_b64 vcc, exec, s[76:77]
	s_cbranch_vccz .LBB0_436
	s_barrier

.LBB0_703:
	s_cmp_eq_u32 s85, 40
	s_cselect_b32 s42, s8, s81
	s_cselect_b32 s43, s9, s82
	s_cselect_b32 s45, s59, s84
	s_cselect_b32 s44, s58, s83
	s_add_u32 s38, s42, 0x80
	s_addc_u32 s39, s43, 0
	s_add_u32 s62, s44, 0x80
	s_addc_u32 s63, s45, 0
	s_add_i32 s35, 0, 0x10000
	s_mov_b64 s[18:19], s[60:61]
	v_add_u32_e32 v140, s35, v142
	s_add_i32 s49, 0, 0x14000
	ds_read_b128 v[136:139], v140
	ds_read_b128 v[144:147], v140 offset:1024
	ds_read_b128 v[148:151], v140 offset:2048
	ds_read_b128 v[152:155], v140 offset:3072
	v_add_u32_e32 v140, s49, v142
	ds_read_b128 v[156:159], v140
	ds_read_b128 v[160:163], v140 offset:1024
	ds_read_b128 v[164:167], v140 offset:2048
	ds_read_b128 v[168:171], v140 offset:3072
	s_add_u32 s18, s18, 0xb0000
	s_addc_u32 s19, s19, 0
	v_lshl_add_u64 v[140:141], s[18:19], 0, v[130:131]
	s_add_i32 m0, s66, 0xc000
	ds_read_b128 v[172:175], v143
	ds_read_b128 v[176:179], v143 offset:1024
	ds_read_b128 v[180:183], v143 offset:2048
	ds_read_b128 v[190:193], v143 offset:3072
	ds_read_b128 v[194:197], v143 offset:4096
	ds_read_b128 v[198:201], v143 offset:5120
	ds_read_b128 v[202:205], v143 offset:6144
	ds_read_b128 v[206:209], v143 offset:7168
	global_load_lds_dwordx4 v[140:141], off
	v_lshl_add_u64 v[140:141], s[18:19], 0, v[132:133]
	s_add_i32 m0, s66, 0xe000
	s_nop 0
	global_load_lds_dwordx4 v[140:141], off
	s_waitcnt vmcnt(8)
	s_waitcnt lgkmcnt(0)
	s_barrier
	s_setprio 1
	s_waitcnt lgkmcnt(0)
	v_mfma_f32_16x16x32_bf16 v[126:129], v[136:139], v[172:175], v[126:129]
	v_mfma_f32_16x16x32_bf16 v[122:125], v[148:151], v[172:175], v[122:125]
	v_mfma_f32_16x16x32_bf16 v[110:113], v[136:139], v[180:183], v[110:113]
	v_mfma_f32_16x16x32_bf16 v[106:109], v[148:151], v[180:183], v[106:109]
	v_mfma_f32_16x16x32_bf16 v[92:95], v[136:139], v[194:197], v[92:95]
	v_mfma_f32_16x16x32_bf16 v[88:91], v[148:151], v[194:197], v[88:91]
	v_mfma_f32_16x16x32_bf16 v[76:79], v[136:139], v[202:205], v[76:79]
	v_mfma_f32_16x16x32_bf16 v[72:75], v[148:151], v[202:205], v[72:75]
	v_mfma_f32_16x16x32_bf16 v[126:129], v[144:147], v[176:179], v[126:129]
	v_mfma_f32_16x16x32_bf16 v[122:125], v[152:155], v[176:179], v[122:125]
	v_mfma_f32_16x16x32_bf16 v[110:113], v[144:147], v[190:193], v[110:113]
	v_mfma_f32_16x16x32_bf16 v[106:109], v[152:155], v[190:193], v[106:109]
	v_mfma_f32_16x16x32_bf16 v[92:95], v[144:147], v[198:201], v[92:95]
	v_mfma_f32_16x16x32_bf16 v[88:91], v[152:155], v[198:201], v[88:91]
	v_mfma_f32_16x16x32_bf16 v[76:79], v[144:147], v[206:209], v[76:79]
	v_mfma_f32_16x16x32_bf16 v[72:75], v[152:155], v[206:209], v[72:75]
	v_mfma_f32_16x16x32_bf16 v[118:121], v[156:159], v[172:175], v[118:121]
	v_mfma_f32_16x16x32_bf16 v[114:117], v[164:167], v[172:175], v[114:117]
	v_mfma_f32_16x16x32_bf16 v[102:105], v[156:159], v[180:183], v[102:105]
	v_mfma_f32_16x16x32_bf16 v[98:101], v[164:167], v[180:183], v[98:101]
	v_mfma_f32_16x16x32_bf16 v[84:87], v[156:159], v[194:197], v[84:87]
	v_mfma_f32_16x16x32_bf16 v[80:83], v[164:167], v[194:197], v[80:83]
	v_mfma_f32_16x16x32_bf16 v[68:71], v[156:159], v[202:205], v[68:71]
	v_mfma_f32_16x16x32_bf16 v[64:67], v[164:167], v[202:205], v[64:67]
	v_mfma_f32_16x16x32_bf16 v[118:121], v[160:163], v[176:179], v[118:121]
	v_mfma_f32_16x16x32_bf16 v[114:117], v[168:171], v[176:179], v[114:117]
	v_mfma_f32_16x16x32_bf16 v[102:105], v[160:163], v[190:193], v[102:105]
	v_mfma_f32_16x16x32_bf16 v[98:101], v[168:171], v[190:193], v[98:101]
	v_mfma_f32_16x16x32_bf16 v[84:87], v[160:163], v[198:201], v[84:87]
	v_mfma_f32_16x16x32_bf16 v[80:83], v[168:171], v[198:201], v[80:83]
	v_mfma_f32_16x16x32_bf16 v[68:71], v[160:163], v[206:209], v[68:71]
	v_mfma_f32_16x16x32_bf16 v[64:67], v[168:171], v[206:209], v[64:67]
	s_setprio 0
	s_barrier
	s_add_i32 s18, s35, s14
	v_lshl_add_u64 v[140:141], s[44:45], 0, v[96:97]
	s_mov_b32 m0, s18
	ds_read_b128 v[172:175], v143 offset:16384
	ds_read_b128 v[176:179], v143 offset:17408
	ds_read_b128 v[180:183], v143 offset:18432
	ds_read_b128 v[190:193], v143 offset:19456
	ds_read_b128 v[194:197], v143 offset:20480
	ds_read_b128 v[198:201], v143 offset:21504
	ds_read_b128 v[202:205], v143 offset:22528
	ds_read_b128 v[206:209], v143 offset:23552
	global_load_lds_dwordx4 v[140:141], off
	s_add_i32 m0, s18, 0x2000
	s_add_u32 s18, s44, 0xb0000
	v_lshl_add_u64 v[140:141], s[44:45], 0, v[134:135]
	s_addc_u32 s19, s45, 0
	s_add_i32 s35, s49, s14
	global_load_lds_dwordx4 v[140:141], off
	v_lshl_add_u64 v[140:141], s[18:19], 0, v[96:97]
	s_mov_b32 m0, s35
	s_nop 0
	global_load_lds_dwordx4 v[140:141], off
	v_lshl_add_u64 v[140:141], s[18:19], 0, v[134:135]
	s_add_i32 m0, s35, 0x2000
	s_nop 0
	global_load_lds_dwordx4 v[140:141], off
	v_lshl_add_u64 v[140:141], s[42:43], 0, v[130:131]
	s_mov_b32 m0, s66
	s_nop 0
	global_load_lds_dwordx4 v[140:141], off
	v_lshl_add_u64 v[140:141], s[42:43], 0, v[132:133]
	s_mov_b32 m0, s67
	s_nop 0
	global_load_lds_dwordx4 v[140:141], off
	s_waitcnt vmcnt(8)
	s_waitcnt lgkmcnt(0)
	s_barrier
	s_setprio 1
	s_waitcnt lgkmcnt(0)
	v_mfma_f32_16x16x32_bf16 v[60:63], v[136:139], v[172:175], v[60:63]
	v_mfma_f32_16x16x32_bf16 v[56:59], v[148:151], v[172:175], v[56:59]
	v_mfma_f32_16x16x32_bf16 v[44:47], v[136:139], v[180:183], v[44:47]
	v_mfma_f32_16x16x32_bf16 v[40:43], v[148:151], v[180:183], v[40:43]
	v_mfma_f32_16x16x32_bf16 v[28:31], v[136:139], v[194:197], v[28:31]
	v_mfma_f32_16x16x32_bf16 v[24:27], v[148:151], v[194:197], v[24:27]
	v_mfma_f32_16x16x32_bf16 v[12:15], v[136:139], v[202:205], v[12:15]
	v_mfma_f32_16x16x32_bf16 v[8:11], v[148:151], v[202:205], v[8:11]
	v_mfma_f32_16x16x32_bf16 v[60:63], v[144:147], v[176:179], v[60:63]
	v_mfma_f32_16x16x32_bf16 v[56:59], v[152:155], v[176:179], v[56:59]
	v_mfma_f32_16x16x32_bf16 v[44:47], v[144:147], v[190:193], v[44:47]
	v_mfma_f32_16x16x32_bf16 v[40:43], v[152:155], v[190:193], v[40:43]
	v_mfma_f32_16x16x32_bf16 v[28:31], v[144:147], v[198:201], v[28:31]
	v_mfma_f32_16x16x32_bf16 v[24:27], v[152:155], v[198:201], v[24:27]
	v_mfma_f32_16x16x32_bf16 v[12:15], v[144:147], v[206:209], v[12:15]
	v_mfma_f32_16x16x32_bf16 v[8:11], v[152:155], v[206:209], v[8:11]
	v_mfma_f32_16x16x32_bf16 v[52:55], v[156:159], v[172:175], v[52:55]
	v_mfma_f32_16x16x32_bf16 v[48:51], v[164:167], v[172:175], v[48:51]
	v_mfma_f32_16x16x32_bf16 v[36:39], v[156:159], v[180:183], v[36:39]
	v_mfma_f32_16x16x32_bf16 v[32:35], v[164:167], v[180:183], v[32:35]
	v_mfma_f32_16x16x32_bf16 v[20:23], v[156:159], v[194:197], v[20:23]
	v_mfma_f32_16x16x32_bf16 v[16:19], v[164:167], v[194:197], v[16:19]
	v_mfma_f32_16x16x32_bf16 v[4:7], v[156:159], v[202:205], v[4:7]
	v_mfma_f32_16x16x32_bf16 v[0:3], v[164:167], v[202:205], v[0:3]
	v_mfma_f32_16x16x32_bf16 v[52:55], v[160:163], v[176:179], v[52:55]
	v_mfma_f32_16x16x32_bf16 v[48:51], v[168:171], v[176:179], v[48:51]
	v_mfma_f32_16x16x32_bf16 v[36:39], v[160:163], v[190:193], v[36:39]
	v_mfma_f32_16x16x32_bf16 v[32:35], v[168:171], v[190:193], v[32:35]
	v_mfma_f32_16x16x32_bf16 v[20:23], v[160:163], v[198:201], v[20:23]
	v_mfma_f32_16x16x32_bf16 v[16:19], v[168:171], v[198:201], v[16:19]
	v_mfma_f32_16x16x32_bf16 v[4:7], v[160:163], v[206:209], v[4:7]
	v_mfma_f32_16x16x32_bf16 v[0:3], v[168:171], v[206:209], v[0:3]
	s_setprio 0
	s_barrier
	s_add_i32 s35, 0, 0x18000
	v_add_u32_e32 v140, s35, v142
	s_add_i32 s44, 0, 0x1c000
	ds_read_b128 v[136:139], v140
	ds_read_b128 v[144:147], v140 offset:1024
	ds_read_b128 v[148:151], v140 offset:2048
	ds_read_b128 v[152:155], v140 offset:3072
	v_add_u32_e32 v140, s44, v142
	ds_read_b128 v[156:159], v140
	ds_read_b128 v[160:163], v140 offset:1024
	ds_read_b128 v[164:167], v140 offset:2048
	ds_read_b128 v[168:171], v140 offset:3072
	s_add_u32 s18, s42, 0xb0000
	s_addc_u32 s19, s43, 0
	s_mov_b32 m0, s68
	v_lshl_add_u64 v[140:141], s[18:19], 0, v[130:131]
	ds_read_b128 v[172:175], v143 offset:32768
	ds_read_b128 v[176:179], v143 offset:33792
	ds_read_b128 v[180:183], v143 offset:34816
	ds_read_b128 v[190:193], v143 offset:35840
	ds_read_b128 v[194:197], v143 offset:36864
	ds_read_b128 v[198:201], v143 offset:37888
	ds_read_b128 v[202:205], v143 offset:38912
	ds_read_b128 v[206:209], v143 offset:39936
	global_load_lds_dwordx4 v[140:141], off
	v_lshl_add_u64 v[140:141], s[18:19], 0, v[132:133]
	s_mov_b32 m0, s69
	s_nop 0
	global_load_lds_dwordx4 v[140:141], off
	s_waitcnt vmcnt(8)
	s_waitcnt lgkmcnt(0)
	s_barrier
	s_setprio 1
	s_waitcnt lgkmcnt(0)
	v_mfma_f32_16x16x32_bf16 v[126:129], v[136:139], v[172:175], v[126:129]
	v_mfma_f32_16x16x32_bf16 v[122:125], v[148:151], v[172:175], v[122:125]
	v_mfma_f32_16x16x32_bf16 v[110:113], v[136:139], v[180:183], v[110:113]
	v_mfma_f32_16x16x32_bf16 v[106:109], v[148:151], v[180:183], v[106:109]
	v_mfma_f32_16x16x32_bf16 v[92:95], v[136:139], v[194:197], v[92:95]
	v_mfma_f32_16x16x32_bf16 v[88:91], v[148:151], v[194:197], v[88:91]
	v_mfma_f32_16x16x32_bf16 v[76:79], v[136:139], v[202:205], v[76:79]
	v_mfma_f32_16x16x32_bf16 v[72:75], v[148:151], v[202:205], v[72:75]
	v_mfma_f32_16x16x32_bf16 v[126:129], v[144:147], v[176:179], v[126:129]
	v_mfma_f32_16x16x32_bf16 v[122:125], v[152:155], v[176:179], v[122:125]
	v_mfma_f32_16x16x32_bf16 v[110:113], v[144:147], v[190:193], v[110:113]
	v_mfma_f32_16x16x32_bf16 v[106:109], v[152:155], v[190:193], v[106:109]
	v_mfma_f32_16x16x32_bf16 v[92:95], v[144:147], v[198:201], v[92:95]
	v_mfma_f32_16x16x32_bf16 v[88:91], v[152:155], v[198:201], v[88:91]
	v_mfma_f32_16x16x32_bf16 v[76:79], v[144:147], v[206:209], v[76:79]
	v_mfma_f32_16x16x32_bf16 v[72:75], v[152:155], v[206:209], v[72:75]
	v_mfma_f32_16x16x32_bf16 v[118:121], v[156:159], v[172:175], v[118:121]
	v_mfma_f32_16x16x32_bf16 v[114:117], v[164:167], v[172:175], v[114:117]
	v_mfma_f32_16x16x32_bf16 v[102:105], v[156:159], v[180:183], v[102:105]
	v_mfma_f32_16x16x32_bf16 v[98:101], v[164:167], v[180:183], v[98:101]
	v_mfma_f32_16x16x32_bf16 v[84:87], v[156:159], v[194:197], v[84:87]
	v_mfma_f32_16x16x32_bf16 v[80:83], v[164:167], v[194:197], v[80:83]
	v_mfma_f32_16x16x32_bf16 v[68:71], v[156:159], v[202:205], v[68:71]
	v_mfma_f32_16x16x32_bf16 v[64:67], v[164:167], v[202:205], v[64:67]
	v_mfma_f32_16x16x32_bf16 v[118:121], v[160:163], v[176:179], v[118:121]
	v_mfma_f32_16x16x32_bf16 v[114:117], v[168:171], v[176:179], v[114:117]
	v_mfma_f32_16x16x32_bf16 v[102:105], v[160:163], v[190:193], v[102:105]
	v_mfma_f32_16x16x32_bf16 v[98:101], v[168:171], v[190:193], v[98:101]
	v_mfma_f32_16x16x32_bf16 v[84:87], v[160:163], v[198:201], v[84:87]
	v_mfma_f32_16x16x32_bf16 v[80:83], v[168:171], v[198:201], v[80:83]
	v_mfma_f32_16x16x32_bf16 v[68:71], v[160:163], v[206:209], v[68:71]
	v_mfma_f32_16x16x32_bf16 v[64:67], v[168:171], v[206:209], v[64:67]
	s_setprio 0
	s_barrier
	s_add_i32 s18, s35, s14
	v_lshl_add_u64 v[140:141], s[62:63], 0, v[96:97]
	s_mov_b32 m0, s18
	ds_read_b128 v[172:175], v143 offset:49152
	ds_read_b128 v[176:179], v143 offset:50176
	ds_read_b128 v[180:183], v143 offset:51200
	ds_read_b128 v[190:193], v143 offset:52224
	ds_read_b128 v[194:197], v143 offset:53248
	ds_read_b128 v[198:201], v143 offset:54272
	ds_read_b128 v[202:205], v143 offset:55296
	ds_read_b128 v[206:209], v143 offset:56320
	global_load_lds_dwordx4 v[140:141], off
	s_add_i32 m0, s18, 0x2000
	s_add_u32 s18, s62, 0xb0000
	v_lshl_add_u64 v[140:141], s[62:63], 0, v[134:135]
	s_addc_u32 s19, s63, 0
	s_add_i32 s35, s44, s14
	global_load_lds_dwordx4 v[140:141], off
	v_lshl_add_u64 v[140:141], s[18:19], 0, v[96:97]
	s_mov_b32 m0, s35
	s_nop 0
	global_load_lds_dwordx4 v[140:141], off
	v_lshl_add_u64 v[140:141], s[18:19], 0, v[134:135]
	s_add_i32 m0, s35, 0x2000
	s_nop 0
	global_load_lds_dwordx4 v[140:141], off
	v_lshl_add_u64 v[140:141], s[38:39], 0, v[130:131]
	s_mov_b32 m0, s74
	s_nop 0
	global_load_lds_dwordx4 v[140:141], off
	v_lshl_add_u64 v[140:141], s[38:39], 0, v[132:133]
	s_mov_b32 m0, s75
	s_nop 0
	global_load_lds_dwordx4 v[140:141], off
	s_waitcnt vmcnt(8)
	s_waitcnt lgkmcnt(0)
	s_barrier
	s_setprio 1
	s_waitcnt lgkmcnt(0)
	v_mfma_f32_16x16x32_bf16 v[60:63], v[136:139], v[172:175], v[60:63]
	v_mfma_f32_16x16x32_bf16 v[56:59], v[148:151], v[172:175], v[56:59]
	v_mfma_f32_16x16x32_bf16 v[44:47], v[136:139], v[180:183], v[44:47]
	v_mfma_f32_16x16x32_bf16 v[40:43], v[148:151], v[180:183], v[40:43]
	v_mfma_f32_16x16x32_bf16 v[28:31], v[136:139], v[194:197], v[28:31]
	v_mfma_f32_16x16x32_bf16 v[24:27], v[148:151], v[194:197], v[24:27]
	v_mfma_f32_16x16x32_bf16 v[12:15], v[136:139], v[202:205], v[12:15]
	v_mfma_f32_16x16x32_bf16 v[8:11], v[148:151], v[202:205], v[8:11]
	v_mfma_f32_16x16x32_bf16 v[60:63], v[144:147], v[176:179], v[60:63]
	v_mfma_f32_16x16x32_bf16 v[56:59], v[152:155], v[176:179], v[56:59]
	v_mfma_f32_16x16x32_bf16 v[44:47], v[144:147], v[190:193], v[44:47]
	v_mfma_f32_16x16x32_bf16 v[40:43], v[152:155], v[190:193], v[40:43]
	v_mfma_f32_16x16x32_bf16 v[28:31], v[144:147], v[198:201], v[28:31]
	v_mfma_f32_16x16x32_bf16 v[24:27], v[152:155], v[198:201], v[24:27]
	v_mfma_f32_16x16x32_bf16 v[12:15], v[144:147], v[206:209], v[12:15]
	v_mfma_f32_16x16x32_bf16 v[8:11], v[152:155], v[206:209], v[8:11]
	v_mfma_f32_16x16x32_bf16 v[52:55], v[156:159], v[172:175], v[52:55]
	v_mfma_f32_16x16x32_bf16 v[48:51], v[164:167], v[172:175], v[48:51]
	v_mfma_f32_16x16x32_bf16 v[36:39], v[156:159], v[180:183], v[36:39]
	v_mfma_f32_16x16x32_bf16 v[32:35], v[164:167], v[180:183], v[32:35]
	v_mfma_f32_16x16x32_bf16 v[20:23], v[156:159], v[194:197], v[20:23]
	v_mfma_f32_16x16x32_bf16 v[16:19], v[164:167], v[194:197], v[16:19]
	v_mfma_f32_16x16x32_bf16 v[4:7], v[156:159], v[202:205], v[4:7]
	v_mfma_f32_16x16x32_bf16 v[0:3], v[164:167], v[202:205], v[0:3]
	v_mfma_f32_16x16x32_bf16 v[52:55], v[160:163], v[176:179], v[52:55]
	v_mfma_f32_16x16x32_bf16 v[48:51], v[168:171], v[176:179], v[48:51]
	v_mfma_f32_16x16x32_bf16 v[36:39], v[160:163], v[190:193], v[36:39]
	v_mfma_f32_16x16x32_bf16 v[32:35], v[168:171], v[190:193], v[32:35]
	v_mfma_f32_16x16x32_bf16 v[20:23], v[160:163], v[198:201], v[20:23]
	v_mfma_f32_16x16x32_bf16 v[16:19], v[168:171], v[198:201], v[16:19]
	v_mfma_f32_16x16x32_bf16 v[4:7], v[160:163], v[206:209], v[4:7]
	v_mfma_f32_16x16x32_bf16 v[0:3], v[168:171], v[206:209], v[0:3]
	s_setprio 0
	s_barrier
	s_add_i32 s85, s85, 2
	s_add_u32 s81, s81, 0x100
	s_addc_u32 s82, s82, 0
	s_add_u32 s83, s83, 0x100
	s_addc_u32 s84, s84, 0
	s_add_u32 s60, s60, 0x100
	s_addc_u32 s61, s61, 0
	s_cmp_gt_u32 s85, 41
	s_cbranch_scc0 .LBB0_703
	s_and_b64 vcc, exec, s[30:31]
	s_cbranch_vccz .LBB0_706
	s_barrier

.LBB0_740:
	s_add_u32 s18, s66, 0x80
	s_addc_u32 s19, s67, 0
	s_add_u32 s66, s66, 0x100
	s_addc_u32 s67, s67, 0
	s_cmp_eq_u32 s85, 12
	s_cselect_b32 s42, s81, s66
	s_cselect_b32 s43, s59, s67
	s_cselect_b32 s45, s31, s84
	s_cselect_b32 s44, s82, s83
	s_add_u32 s38, s42, 0x80
	s_addc_u32 s39, s43, 0
	s_add_u32 s68, s44, 0x80
	s_addc_u32 s69, s45, 0
	s_add_i32 s35, 0, 0x10000
	s_add_i32 s49, 0, 0x14000
	v_add_u32_e32 v96, s35, v151
	v_add_u32_e32 v150, s49, v151
	ds_read_b128 v[138:141], v96
	ds_read_b128 v[142:145], v96 offset:1024
	ds_read_b128 v[146:149], v96 offset:2048
	ds_read_b128 v[156:159], v96 offset:3072
	ds_read_b128 v[160:163], v150
	ds_read_b128 v[164:167], v150 offset:1024
	ds_read_b128 v[168:171], v150 offset:2048
	ds_read_b128 v[172:175], v150 offset:3072
	s_add_u32 s18, s18, 0x40000
	s_addc_u32 s19, s19, 0
	v_lshl_add_u64 v[152:153], s[18:19], 0, v[136:137]
	s_add_i32 m0, s65, 0xc000
	ds_read_b128 v[176:179], v155
	ds_read_b128 v[180:183], v155 offset:1024
	ds_read_b128 v[190:193], v155 offset:2048
	ds_read_b128 v[194:197], v155 offset:3072
	ds_read_b128 v[198:201], v155 offset:4096
	ds_read_b128 v[202:205], v155 offset:5120
	ds_read_b128 v[206:209], v155 offset:6144
	ds_read_b128 v[210:213], v155 offset:7168
	global_load_lds_dwordx4 v[152:153], off
	v_lshl_add_u64 v[152:153], s[18:19], 0, v[132:133]
	s_add_i32 m0, s65, 0xe000
	s_nop 0
	global_load_lds_dwordx4 v[152:153], off
	s_waitcnt vmcnt(8)
	s_waitcnt lgkmcnt(0)
	s_barrier
	s_setprio 1
	s_waitcnt lgkmcnt(0)
	v_mfma_f32_16x16x32_bf16 v[126:129], v[138:141], v[176:179], v[126:129]
	v_mfma_f32_16x16x32_bf16 v[118:121], v[146:149], v[176:179], v[118:121]
	v_mfma_f32_16x16x32_bf16 v[110:113], v[138:141], v[190:193], v[110:113]
	v_mfma_f32_16x16x32_bf16 v[102:105], v[146:149], v[190:193], v[102:105]
	v_mfma_f32_16x16x32_bf16 v[92:95], v[138:141], v[198:201], v[92:95]
	v_mfma_f32_16x16x32_bf16 v[84:87], v[146:149], v[198:201], v[84:87]
	v_mfma_f32_16x16x32_bf16 v[76:79], v[138:141], v[206:209], v[76:79]
	v_mfma_f32_16x16x32_bf16 v[68:71], v[146:149], v[206:209], v[68:71]
	v_mfma_f32_16x16x32_bf16 v[126:129], v[142:145], v[180:183], v[126:129]
	v_mfma_f32_16x16x32_bf16 v[118:121], v[156:159], v[180:183], v[118:121]
	v_mfma_f32_16x16x32_bf16 v[110:113], v[142:145], v[194:197], v[110:113]
	v_mfma_f32_16x16x32_bf16 v[102:105], v[156:159], v[194:197], v[102:105]
	v_mfma_f32_16x16x32_bf16 v[92:95], v[142:145], v[202:205], v[92:95]
	v_mfma_f32_16x16x32_bf16 v[84:87], v[156:159], v[202:205], v[84:87]
	v_mfma_f32_16x16x32_bf16 v[76:79], v[142:145], v[210:213], v[76:79]
	v_mfma_f32_16x16x32_bf16 v[68:71], v[156:159], v[210:213], v[68:71]
	v_mfma_f32_16x16x32_bf16 v[122:125], v[160:163], v[176:179], v[122:125]
	v_mfma_f32_16x16x32_bf16 v[114:117], v[168:171], v[176:179], v[114:117]
	v_mfma_f32_16x16x32_bf16 v[106:109], v[160:163], v[190:193], v[106:109]
	v_mfma_f32_16x16x32_bf16 v[98:101], v[168:171], v[190:193], v[98:101]
	v_mfma_f32_16x16x32_bf16 v[88:91], v[160:163], v[198:201], v[88:91]
	v_mfma_f32_16x16x32_bf16 v[80:83], v[168:171], v[198:201], v[80:83]
	v_mfma_f32_16x16x32_bf16 v[72:75], v[160:163], v[206:209], v[72:75]
	v_mfma_f32_16x16x32_bf16 v[64:67], v[168:171], v[206:209], v[64:67]
	v_mfma_f32_16x16x32_bf16 v[122:125], v[164:167], v[180:183], v[122:125]
	v_mfma_f32_16x16x32_bf16 v[114:117], v[172:175], v[180:183], v[114:117]
	v_mfma_f32_16x16x32_bf16 v[106:109], v[164:167], v[194:197], v[106:109]
	v_mfma_f32_16x16x32_bf16 v[98:101], v[172:175], v[194:197], v[98:101]
	v_mfma_f32_16x16x32_bf16 v[88:91], v[164:167], v[202:205], v[88:91]
	v_mfma_f32_16x16x32_bf16 v[80:83], v[172:175], v[202:205], v[80:83]
	v_mfma_f32_16x16x32_bf16 v[72:75], v[164:167], v[210:213], v[72:75]
	v_mfma_f32_16x16x32_bf16 v[64:67], v[172:175], v[210:213], v[64:67]
	s_setprio 0
	s_barrier
	s_add_i32 s18, s35, s47
	v_lshl_add_u64 v[152:153], s[44:45], 0, v[134:135]
	s_mov_b32 m0, s18
	ds_read_b128 v[176:179], v155 offset:16384
	ds_read_b128 v[180:183], v155 offset:17408
	ds_read_b128 v[190:193], v155 offset:18432
	ds_read_b128 v[194:197], v155 offset:19456
	ds_read_b128 v[198:201], v155 offset:20480
	ds_read_b128 v[202:205], v155 offset:21504
	ds_read_b128 v[206:209], v155 offset:22528
	ds_read_b128 v[210:213], v155 offset:23552
	global_load_lds_dwordx4 v[152:153], off
	s_add_i32 m0, s18, 0x2000
	s_add_u32 s18, s44, 0x40000
	v_lshl_add_u64 v[152:153], s[44:45], 0, v[130:131]
	s_addc_u32 s19, s45, 0
	s_add_i32 s35, s49, s47
	global_load_lds_dwordx4 v[152:153], off
	v_lshl_add_u64 v[152:153], s[18:19], 0, v[134:135]
	s_mov_b32 m0, s35
	s_nop 0
	global_load_lds_dwordx4 v[152:153], off
	v_lshl_add_u64 v[152:153], s[18:19], 0, v[130:131]
	s_add_i32 m0, s35, 0x2000
	s_nop 0
	global_load_lds_dwordx4 v[152:153], off
	v_lshl_add_u64 v[152:153], s[42:43], 0, v[136:137]
	s_mov_b32 m0, s65
	s_nop 0
	global_load_lds_dwordx4 v[152:153], off
	v_lshl_add_u64 v[152:153], s[42:43], 0, v[132:133]
	s_mov_b32 m0, s72
	s_nop 0
	global_load_lds_dwordx4 v[152:153], off
	s_waitcnt vmcnt(8)
	s_waitcnt lgkmcnt(0)
	s_barrier
	s_setprio 1
	s_waitcnt lgkmcnt(0)
	v_mfma_f32_16x16x32_bf16 v[60:63], v[138:141], v[176:179], v[60:63]
	v_mfma_f32_16x16x32_bf16 v[52:55], v[146:149], v[176:179], v[52:55]
	v_mfma_f32_16x16x32_bf16 v[44:47], v[138:141], v[190:193], v[44:47]
	v_mfma_f32_16x16x32_bf16 v[36:39], v[146:149], v[190:193], v[36:39]
	v_mfma_f32_16x16x32_bf16 v[28:31], v[138:141], v[198:201], v[28:31]
	v_mfma_f32_16x16x32_bf16 v[20:23], v[146:149], v[198:201], v[20:23]
	v_mfma_f32_16x16x32_bf16 v[12:15], v[138:141], v[206:209], v[12:15]
	v_mfma_f32_16x16x32_bf16 v[4:7], v[146:149], v[206:209], v[4:7]
	v_mfma_f32_16x16x32_bf16 v[60:63], v[142:145], v[180:183], v[60:63]
	v_mfma_f32_16x16x32_bf16 v[52:55], v[156:159], v[180:183], v[52:55]
	v_mfma_f32_16x16x32_bf16 v[44:47], v[142:145], v[194:197], v[44:47]
	v_mfma_f32_16x16x32_bf16 v[36:39], v[156:159], v[194:197], v[36:39]
	v_mfma_f32_16x16x32_bf16 v[28:31], v[142:145], v[202:205], v[28:31]
	v_mfma_f32_16x16x32_bf16 v[20:23], v[156:159], v[202:205], v[20:23]
	v_mfma_f32_16x16x32_bf16 v[12:15], v[142:145], v[210:213], v[12:15]
	v_mfma_f32_16x16x32_bf16 v[4:7], v[156:159], v[210:213], v[4:7]
	v_mfma_f32_16x16x32_bf16 v[56:59], v[160:163], v[176:179], v[56:59]
	v_mfma_f32_16x16x32_bf16 v[48:51], v[168:171], v[176:179], v[48:51]
	v_mfma_f32_16x16x32_bf16 v[40:43], v[160:163], v[190:193], v[40:43]
	v_mfma_f32_16x16x32_bf16 v[32:35], v[168:171], v[190:193], v[32:35]
	v_mfma_f32_16x16x32_bf16 v[24:27], v[160:163], v[198:201], v[24:27]
	v_mfma_f32_16x16x32_bf16 v[16:19], v[168:171], v[198:201], v[16:19]
	v_mfma_f32_16x16x32_bf16 v[8:11], v[160:163], v[206:209], v[8:11]
	v_mfma_f32_16x16x32_bf16 v[0:3], v[168:171], v[206:209], v[0:3]
	v_mfma_f32_16x16x32_bf16 v[56:59], v[164:167], v[180:183], v[56:59]
	v_mfma_f32_16x16x32_bf16 v[48:51], v[172:175], v[180:183], v[48:51]
	v_mfma_f32_16x16x32_bf16 v[40:43], v[164:167], v[194:197], v[40:43]
	v_mfma_f32_16x16x32_bf16 v[32:35], v[172:175], v[194:197], v[32:35]
	v_mfma_f32_16x16x32_bf16 v[24:27], v[164:167], v[202:205], v[24:27]
	v_mfma_f32_16x16x32_bf16 v[16:19], v[172:175], v[202:205], v[16:19]
	v_mfma_f32_16x16x32_bf16 v[8:11], v[164:167], v[210:213], v[8:11]
	v_mfma_f32_16x16x32_bf16 v[0:3], v[172:175], v[210:213], v[0:3]
	s_setprio 0
	s_barrier
	s_add_i32 s35, 0, 0x18000
	v_add_u32_e32 v96, s35, v151
	s_add_i32 s44, 0, 0x1c000
	ds_read_b128 v[138:141], v96
	ds_read_b128 v[142:145], v96 offset:1024
	ds_read_b128 v[146:149], v96 offset:2048
	ds_read_b128 v[156:159], v96 offset:3072
	v_add_u32_e32 v96, s44, v151
	ds_read_b128 v[160:163], v96
	ds_read_b128 v[164:167], v96 offset:1024
	ds_read_b128 v[168:171], v96 offset:2048
	ds_read_b128 v[172:175], v96 offset:3072
	s_add_u32 s18, s42, 0x40000
	s_addc_u32 s19, s43, 0
	s_mov_b32 m0, s73
	v_lshl_add_u64 v[152:153], s[18:19], 0, v[136:137]
	ds_read_b128 v[176:179], v155 offset:32768
	ds_read_b128 v[180:183], v155 offset:33792
	ds_read_b128 v[190:193], v155 offset:34816
	ds_read_b128 v[194:197], v155 offset:35840
	ds_read_b128 v[198:201], v155 offset:36864
	ds_read_b128 v[202:205], v155 offset:37888
	ds_read_b128 v[206:209], v155 offset:38912
	ds_read_b128 v[210:213], v155 offset:39936
	global_load_lds_dwordx4 v[152:153], off
	v_lshl_add_u64 v[152:153], s[18:19], 0, v[132:133]
	s_mov_b32 m0, s74
	s_nop 0
	global_load_lds_dwordx4 v[152:153], off
	s_waitcnt vmcnt(8)
	s_waitcnt lgkmcnt(0)
	s_barrier
	s_setprio 1
	s_waitcnt lgkmcnt(0)
	v_mfma_f32_16x16x32_bf16 v[126:129], v[138:141], v[176:179], v[126:129]
	v_mfma_f32_16x16x32_bf16 v[118:121], v[146:149], v[176:179], v[118:121]
	v_mfma_f32_16x16x32_bf16 v[110:113], v[138:141], v[190:193], v[110:113]
	v_mfma_f32_16x16x32_bf16 v[102:105], v[146:149], v[190:193], v[102:105]
	v_mfma_f32_16x16x32_bf16 v[92:95], v[138:141], v[198:201], v[92:95]
	v_mfma_f32_16x16x32_bf16 v[84:87], v[146:149], v[198:201], v[84:87]
	v_mfma_f32_16x16x32_bf16 v[76:79], v[138:141], v[206:209], v[76:79]
	v_mfma_f32_16x16x32_bf16 v[68:71], v[146:149], v[206:209], v[68:71]
	v_mfma_f32_16x16x32_bf16 v[126:129], v[142:145], v[180:183], v[126:129]
	v_mfma_f32_16x16x32_bf16 v[118:121], v[156:159], v[180:183], v[118:121]
	v_mfma_f32_16x16x32_bf16 v[110:113], v[142:145], v[194:197], v[110:113]
	v_mfma_f32_16x16x32_bf16 v[102:105], v[156:159], v[194:197], v[102:105]
	v_mfma_f32_16x16x32_bf16 v[92:95], v[142:145], v[202:205], v[92:95]
	v_mfma_f32_16x16x32_bf16 v[84:87], v[156:159], v[202:205], v[84:87]
	v_mfma_f32_16x16x32_bf16 v[76:79], v[142:145], v[210:213], v[76:79]
	v_mfma_f32_16x16x32_bf16 v[68:71], v[156:159], v[210:213], v[68:71]
	v_mfma_f32_16x16x32_bf16 v[122:125], v[160:163], v[176:179], v[122:125]
	v_mfma_f32_16x16x32_bf16 v[114:117], v[168:171], v[176:179], v[114:117]
	v_mfma_f32_16x16x32_bf16 v[106:109], v[160:163], v[190:193], v[106:109]
	v_mfma_f32_16x16x32_bf16 v[98:101], v[168:171], v[190:193], v[98:101]
	v_mfma_f32_16x16x32_bf16 v[88:91], v[160:163], v[198:201], v[88:91]
	v_mfma_f32_16x16x32_bf16 v[80:83], v[168:171], v[198:201], v[80:83]
	v_mfma_f32_16x16x32_bf16 v[72:75], v[160:163], v[206:209], v[72:75]
	v_mfma_f32_16x16x32_bf16 v[64:67], v[168:171], v[206:209], v[64:67]
	v_mfma_f32_16x16x32_bf16 v[122:125], v[164:167], v[180:183], v[122:125]
	v_mfma_f32_16x16x32_bf16 v[114:117], v[172:175], v[180:183], v[114:117]
	v_mfma_f32_16x16x32_bf16 v[106:109], v[164:167], v[194:197], v[106:109]
	v_mfma_f32_16x16x32_bf16 v[98:101], v[172:175], v[194:197], v[98:101]
	v_mfma_f32_16x16x32_bf16 v[88:91], v[164:167], v[202:205], v[88:91]
	v_mfma_f32_16x16x32_bf16 v[80:83], v[172:175], v[202:205], v[80:83]
	v_mfma_f32_16x16x32_bf16 v[72:75], v[164:167], v[210:213], v[72:75]
	v_mfma_f32_16x16x32_bf16 v[64:67], v[172:175], v[210:213], v[64:67]
	s_setprio 0
	s_barrier
	s_add_i32 s18, s35, s47
	v_lshl_add_u64 v[152:153], s[68:69], 0, v[134:135]
	s_mov_b32 m0, s18
	ds_read_b128 v[176:179], v155 offset:49152
	ds_read_b128 v[180:183], v155 offset:50176
	ds_read_b128 v[190:193], v155 offset:51200
	ds_read_b128 v[194:197], v155 offset:52224
	ds_read_b128 v[198:201], v155 offset:53248
	ds_read_b128 v[202:205], v155 offset:54272
	ds_read_b128 v[206:209], v155 offset:55296
	ds_read_b128 v[210:213], v155 offset:56320
	global_load_lds_dwordx4 v[152:153], off
	s_add_i32 m0, s18, 0x2000
	s_add_u32 s18, s68, 0x40000
	v_lshl_add_u64 v[152:153], s[68:69], 0, v[130:131]
	s_addc_u32 s19, s69, 0
	s_add_i32 s35, s44, s47
	global_load_lds_dwordx4 v[152:153], off
	v_lshl_add_u64 v[152:153], s[18:19], 0, v[134:135]
	s_mov_b32 m0, s35
	s_nop 0
	global_load_lds_dwordx4 v[152:153], off
	v_lshl_add_u64 v[152:153], s[18:19], 0, v[130:131]
	s_add_i32 m0, s35, 0x2000
	s_nop 0
	global_load_lds_dwordx4 v[152:153], off
	v_lshl_add_u64 v[152:153], s[38:39], 0, v[136:137]
	s_mov_b32 m0, s77
	s_nop 0
	global_load_lds_dwordx4 v[152:153], off
	v_lshl_add_u64 v[152:153], s[38:39], 0, v[132:133]
	s_mov_b32 m0, s78
	s_nop 0
	global_load_lds_dwordx4 v[152:153], off
	s_waitcnt vmcnt(8)
	s_cmp_lg_u32 s85, 12
	s_cbranch_scc1 .Lswi_ssq_skip
	global_load_dwordx4 v[220:223], v[252:253], off
	global_load_dwordx4 v[224:227], v[252:253], off offset:1024
	global_load_dwordx4 v[228:231], v[252:253], off offset:2048
	global_load_dwordx4 v[232:235], v[252:253], off offset:3072
	global_load_dwordx4 v[236:239], v[184:185], off
	global_load_dwordx4 v[240:243], v[184:185], off offset:1024
	global_load_dwordx4 v[244:247], v[184:185], off offset:2048
	global_load_dwordx4 v[248:251], v[184:185], off offset:3072
.Lswi_ssq_skip:
	s_waitcnt lgkmcnt(0)
	s_barrier
	s_setprio 1
	s_waitcnt lgkmcnt(0)
	v_mfma_f32_16x16x32_bf16 v[60:63], v[138:141], v[176:179], v[60:63]
	v_mfma_f32_16x16x32_bf16 v[52:55], v[146:149], v[176:179], v[52:55]
	v_mfma_f32_16x16x32_bf16 v[44:47], v[138:141], v[190:193], v[44:47]
	v_mfma_f32_16x16x32_bf16 v[36:39], v[146:149], v[190:193], v[36:39]
	v_mfma_f32_16x16x32_bf16 v[28:31], v[138:141], v[198:201], v[28:31]
	v_mfma_f32_16x16x32_bf16 v[20:23], v[146:149], v[198:201], v[20:23]
	v_mfma_f32_16x16x32_bf16 v[12:15], v[138:141], v[206:209], v[12:15]
	v_mfma_f32_16x16x32_bf16 v[4:7], v[146:149], v[206:209], v[4:7]
	v_mfma_f32_16x16x32_bf16 v[60:63], v[142:145], v[180:183], v[60:63]
	v_mfma_f32_16x16x32_bf16 v[52:55], v[156:159], v[180:183], v[52:55]
	v_mfma_f32_16x16x32_bf16 v[44:47], v[142:145], v[194:197], v[44:47]
	v_mfma_f32_16x16x32_bf16 v[36:39], v[156:159], v[194:197], v[36:39]
	v_mfma_f32_16x16x32_bf16 v[28:31], v[142:145], v[202:205], v[28:31]
	v_mfma_f32_16x16x32_bf16 v[20:23], v[156:159], v[202:205], v[20:23]
	v_mfma_f32_16x16x32_bf16 v[12:15], v[142:145], v[210:213], v[12:15]
	v_mfma_f32_16x16x32_bf16 v[4:7], v[156:159], v[210:213], v[4:7]
	v_mfma_f32_16x16x32_bf16 v[56:59], v[160:163], v[176:179], v[56:59]
	v_mfma_f32_16x16x32_bf16 v[48:51], v[168:171], v[176:179], v[48:51]
	v_mfma_f32_16x16x32_bf16 v[40:43], v[160:163], v[190:193], v[40:43]
	v_mfma_f32_16x16x32_bf16 v[32:35], v[168:171], v[190:193], v[32:35]
	v_mfma_f32_16x16x32_bf16 v[24:27], v[160:163], v[198:201], v[24:27]
	v_mfma_f32_16x16x32_bf16 v[16:19], v[168:171], v[198:201], v[16:19]
	v_mfma_f32_16x16x32_bf16 v[8:11], v[160:163], v[206:209], v[8:11]
	v_mfma_f32_16x16x32_bf16 v[0:3], v[168:171], v[206:209], v[0:3]
	v_mfma_f32_16x16x32_bf16 v[56:59], v[164:167], v[180:183], v[56:59]
	v_mfma_f32_16x16x32_bf16 v[48:51], v[172:175], v[180:183], v[48:51]
	v_mfma_f32_16x16x32_bf16 v[40:43], v[164:167], v[194:197], v[40:43]
	v_mfma_f32_16x16x32_bf16 v[32:35], v[172:175], v[194:197], v[32:35]
	v_mfma_f32_16x16x32_bf16 v[24:27], v[164:167], v[202:205], v[24:27]
	v_mfma_f32_16x16x32_bf16 v[16:19], v[172:175], v[202:205], v[16:19]
	v_mfma_f32_16x16x32_bf16 v[8:11], v[164:167], v[210:213], v[8:11]
	v_mfma_f32_16x16x32_bf16 v[0:3], v[172:175], v[210:213], v[0:3]
	s_setprio 0
	s_barrier
	s_add_i32 s85, s85, 2
	s_add_u32 s83, s83, 0x100
	s_addc_u32 s84, s84, 0
	s_cmp_gt_u32 s85, 13
	s_cbranch_scc0 .LBB0_740
	s_and_b64 vcc, exec, s[28:29]
	s_cbranch_vccz .LBB0_743
	s_barrier
